# MFMA order: Gray walk with m fastest (src0 shared 6x, src1 1x per block), second block mirrored
# baseline (speedup 1.0000x reference)
; #define PG8_STAGE(bufoff, gbase, voff) do { _Pragma("unroll") for (int _i = 0; _i < 2; ++_i) \
;         __builtin_amdgcn_global_load_lds((const unsigned*)((const char*)(gbase) + (voff)[_i]), (PG8_LAS unsigned*)(lds + (bufoff) + ldsw + _i * 8192), 16, 0, 0); } while (0)
; #define PG8_LDA(dst, b, h) do { _Pragma("unroll") for (int m = 0; m < 4; ++m) _Pragma("unroll") for (int k = 0; k < 2; ++k) dst[m][k] = *(const PG8_LAS bf16x8*)(lds + PG8_SA(b, h) + aoff + m * 2048 + k * 1024); } while (0)
; #define PG8_LDB(dst, b, h) do { _Pragma("unroll") for (int n = 0; n < 2; ++n) _Pragma("unroll") for (int k = 0; k < 2; ++k) dst[n][k] = *(const PG8_LAS bf16x8*)(lds + PG8_SB(b, h) + boff + n * 2048 + k * 1024); } while (0)
; #define PG8_MMA(ai, bj, At, Bt) do { __builtin_amdgcn_s_setprio(1); _Pragma("unroll") for (int m = 0; m < 4; ++m) _Pragma("unroll") for (int n = 0; n < 2; ++n) _Pragma("unroll") for (int k = 0; k < 2; ++k) \
;         acc[ai][bj][m][n] = mma16(Bt[n][k], At[m][k], acc[ai][bj][m][n]); __builtin_amdgcn_s_setprio(0); } while (0)
; #define PG8_WAIT_V(n) asm volatile("s_waitcnt vmcnt(" #n ")" ::: "memory")
; #define PG8_WAIT_L(n) asm volatile("s_waitcnt lgkmcnt(" #n ")" ::: "memory")
; template <class Epi, class Sched, bool ALIGN_EPI = false, bool SP2 = false>
; __device__ __forceinline__ void gemm_phase(PG8_LAS unsigned char* lds, const Gemm g, const Sched& S, const Epi& E) {
;     ...
;         for (int t = 0; t < nt; t += 2) {
;             const bool last = (t == nt - 2);
;             const char* a1 = cA + (size_t)(t + 1) * kstep;
;             const char* a2 = last ? nA : cA + (size_t)(t + 2) * kstep; const char* b2 = last ? nB : cB + (size_t)(t + 2) * kstep;
;             const char* a3 = a2 + kstep; const char* b3 = b2 + kstep;
;             if (last && has_next) S.a_ready(nxt);
;             if constexpr (SP2) {
;             PG8_LDB(B0, 0, 0); PG8_LDB(B1, 0, 1); PG8_SCHED; PG8_LDA(At, 0, 0); PG8_STAGE(PG8_SA(1, 1), a1 + hstepA, voffA);
;             PG8_WAIT_V(8); PG8_WAIT_L(0); PG8_BAR; PG8_MMA(0, 0, At, B0); PG8_MMA(0, 1, At, B1); PG8_BAR; PG8_SCHED;
;             PG8_LDA(At, 0, 1); PG8_STAGE(PG8_SB(0, 0), b2, voffB); PG8_STAGE(PG8_SB(0, 1), b2 + hstepB, voffB); PG8_STAGE(PG8_SA(0, 0), a2, voffA);
;             PG8_WAIT_V(8); PG8_WAIT_L(0); PG8_BAR; PG8_MMA(1, 0, At, B0); PG8_MMA(1, 1, At, B1); PG8_BAR; PG8_SCHED;
.LBB0_231:
	ds_read_b128 v[146:149], v158
	ds_read_b128 v[162:165], v158 offset:1024
	ds_read_b128 v[182:185], v158 offset:2048
	ds_read_b128 v[186:189], v158 offset:3072
	ds_read_b128 v[190:193], v159
	ds_read_b128 v[194:197], v159 offset:1024
	ds_read_b128 v[198:201], v159 offset:2048
	ds_read_b128 v[202:205], v159 offset:3072
	s_add_u32 s45, s0, 0xfff00080
	s_addc_u32 s46, s1, -1
	s_cmp_eq_u32 s37, 60
	s_cselect_b32 s67, s55, s46
	s_cselect_b32 s66, s54, s45
	s_cselect_b32 s65, s29, s36
	s_cselect_b32 s64, s33, s35
	v_lshl_add_u64 v[166:167], s[0:1], 0, v[138:139]
	s_add_i32 m0, s13, 0xc000
	ds_read_b128 v[206:209], v160
	ds_read_b128 v[212:215], v160 offset:1024
	ds_read_b128 v[216:219], v160 offset:2048
	ds_read_b128 v[220:223], v160 offset:3072
	ds_read_b128 v[224:227], v160 offset:4096
	ds_read_b128 v[228:231], v160 offset:5120
	ds_read_b128 v[232:235], v160 offset:6144
	ds_read_b128 v[236:239], v160 offset:7168
	global_load_lds_dwordx4 v[166:167], off
	v_lshl_add_u64 v[166:167], s[0:1], 0, v[140:141]
	s_add_i32 m0, s13, 0xe000
	s_nop 0
	global_load_lds_dwordx4 v[166:167], off
	s_waitcnt vmcnt(8)
	s_waitcnt lgkmcnt(0)
	s_barrier
	s_setprio 1
	s_waitcnt lgkmcnt(0)
	v_mfma_f32_16x16x32_bf16 v[126:129], v[146:149], v[206:209], v[126:129]
	v_mfma_f32_16x16x32_bf16 v[126:129], v[162:165], v[212:215], v[126:129]
	v_mfma_f32_16x16x32_bf16 v[118:121], v[162:165], v[220:223], v[118:121]
	v_mfma_f32_16x16x32_bf16 v[118:121], v[146:149], v[216:219], v[118:121]
	v_mfma_f32_16x16x32_bf16 v[102:105], v[146:149], v[224:227], v[102:105]
	v_mfma_f32_16x16x32_bf16 v[102:105], v[162:165], v[228:231], v[102:105]
	v_mfma_f32_16x16x32_bf16 v[86:89], v[162:165], v[236:239], v[86:89]
	v_mfma_f32_16x16x32_bf16 v[86:89], v[146:149], v[232:235], v[86:89]
	v_mfma_f32_16x16x32_bf16 v[78:81], v[182:185], v[232:235], v[78:81]
	v_mfma_f32_16x16x32_bf16 v[78:81], v[186:189], v[236:239], v[78:81]
	v_mfma_f32_16x16x32_bf16 v[94:97], v[186:189], v[228:231], v[94:97]
	v_mfma_f32_16x16x32_bf16 v[94:97], v[182:185], v[224:227], v[94:97]
	v_mfma_f32_16x16x32_bf16 v[110:113], v[182:185], v[216:219], v[110:113]
	v_mfma_f32_16x16x32_bf16 v[110:113], v[186:189], v[220:223], v[110:113]
	v_mfma_f32_16x16x32_bf16 v[122:125], v[186:189], v[212:215], v[122:125]
	v_mfma_f32_16x16x32_bf16 v[122:125], v[182:185], v[206:209], v[122:125]
	s_setprio 0
	s_setprio 1
	v_mfma_f32_16x16x32_bf16 v[106:109], v[198:201], v[206:209], v[106:109]
	v_mfma_f32_16x16x32_bf16 v[106:109], v[202:205], v[212:215], v[106:109]
	v_mfma_f32_16x16x32_bf16 v[90:93], v[202:205], v[220:223], v[90:93]
	v_mfma_f32_16x16x32_bf16 v[90:93], v[198:201], v[216:219], v[90:93]
	v_mfma_f32_16x16x32_bf16 v[74:77], v[198:201], v[224:227], v[74:77]
	v_mfma_f32_16x16x32_bf16 v[74:77], v[202:205], v[228:231], v[74:77]
	v_mfma_f32_16x16x32_bf16 v[66:69], v[202:205], v[236:239], v[66:69]
	v_mfma_f32_16x16x32_bf16 v[66:69], v[198:201], v[232:235], v[66:69]
	v_mfma_f32_16x16x32_bf16 v[70:73], v[190:193], v[232:235], v[70:73]
	v_mfma_f32_16x16x32_bf16 v[70:73], v[194:197], v[236:239], v[70:73]
	v_mfma_f32_16x16x32_bf16 v[82:85], v[194:197], v[228:231], v[82:85]
	v_mfma_f32_16x16x32_bf16 v[82:85], v[190:193], v[224:227], v[82:85]
	v_mfma_f32_16x16x32_bf16 v[98:101], v[190:193], v[216:219], v[98:101]
	v_mfma_f32_16x16x32_bf16 v[98:101], v[194:197], v[220:223], v[98:101]
	v_mfma_f32_16x16x32_bf16 v[114:117], v[194:197], v[212:215], v[114:117]
	v_mfma_f32_16x16x32_bf16 v[114:117], v[190:193], v[206:209], v[114:117]
	s_setprio 0
	s_barrier
	s_add_i32 s45, s26, s12
	v_lshl_add_u64 v[166:167], s[64:65], 0, v[132:133]
	s_mov_b32 m0, s45
	ds_read_b128 v[206:209], v160 offset:16384
	ds_read_b128 v[212:215], v160 offset:17408
	ds_read_b128 v[216:219], v160 offset:18432
	ds_read_b128 v[220:223], v160 offset:19456
	ds_read_b128 v[224:227], v160 offset:20480
	ds_read_b128 v[228:231], v160 offset:21504
	ds_read_b128 v[232:235], v160 offset:22528
	ds_read_b128 v[236:239], v160 offset:23552
	global_load_lds_dwordx4 v[166:167], off
	s_add_i32 m0, s45, 0x2000
	s_add_u32 s46, s64, 0x100000
	v_lshl_add_u64 v[176:177], s[64:65], 0, v[136:137]
	s_addc_u32 s47, s65, 0
	s_add_i32 s45, s27, s12
	global_load_lds_dwordx4 v[176:177], off
	v_lshl_add_u64 v[240:241], s[46:47], 0, v[132:133]
	s_mov_b32 m0, s45
	v_lshl_add_u64 v[242:243], s[66:67], 0, v[134:135]
	global_load_lds_dwordx4 v[240:241], off
	v_lshl_add_u64 v[240:241], s[46:47], 0, v[136:137]
	s_add_i32 m0, s45, 0x2000
	s_nop 0
	global_load_lds_dwordx4 v[240:241], off
	v_lshl_add_u64 v[240:241], s[66:67], 0, v[130:131]
	s_mov_b32 m0, s13
	s_nop 0
	global_load_lds_dwordx4 v[240:241], off
	s_mov_b32 m0, s18
	s_nop 0
	global_load_lds_dwordx4 v[242:243], off
	s_waitcnt vmcnt(8)
	s_waitcnt lgkmcnt(0)
	s_barrier
; #define PG8_STAGE(bufoff, gbase, voff) do { _Pragma("unroll") for (int _i = 0; _i < 2; ++_i) \
;         __builtin_amdgcn_global_load_lds((const unsigned*)((const char*)(gbase) + (voff)[_i]), (PG8_LAS unsigned*)(lds + (bufoff) + ldsw + _i * 8192), 16, 0, 0); } while (0)
; #define PG8_LDA(dst, b, h) do { _Pragma("unroll") for (int m = 0; m < 4; ++m) _Pragma("unroll") for (int k = 0; k < 2; ++k) dst[m][k] = *(const PG8_LAS bf16x8*)(lds + PG8_SA(b, h) + aoff + m * 2048 + k * 1024); } while (0)
; #define PG8_LDB(dst, b, h) do { _Pragma("unroll") for (int n = 0; n < 2; ++n) _Pragma("unroll") for (int k = 0; k < 2; ++k) dst[n][k] = *(const PG8_LAS bf16x8*)(lds + PG8_SB(b, h) + boff + n * 2048 + k * 1024); } while (0)
; #define PG8_MMA(ai, bj, At, Bt) do { __builtin_amdgcn_s_setprio(1); _Pragma("unroll") for (int m = 0; m < 4; ++m) _Pragma("unroll") for (int n = 0; n < 2; ++n) _Pragma("unroll") for (int k = 0; k < 2; ++k) \
;         acc[ai][bj][m][n] = mma16(Bt[n][k], At[m][k], acc[ai][bj][m][n]); __builtin_amdgcn_s_setprio(0); } while (0)
; #define PG8_WAIT_V(n) asm volatile("s_waitcnt vmcnt(" #n ")" ::: "memory")
; #define PG8_WAIT_L(n) asm volatile("s_waitcnt lgkmcnt(" #n ")" ::: "memory")
; #define PG8_BAR __builtin_amdgcn_s_barrier()
; #define PG8_SCHED __builtin_amdgcn_sched_barrier(0)
; template <class Epi, class Sched, bool ALIGN_EPI = false, bool SP2 = false>
; __device__ __forceinline__ void gemm_phase(PG8_LAS unsigned char* lds, const Gemm g, const Sched& S, const Epi& E) {
;     ...
;             PG8_WAIT_V(8); PG8_WAIT_L(0); PG8_BAR; PG8_MMA(1, 0, At, B0); PG8_MMA(1, 1, At, B1); PG8_BAR; PG8_SCHED;
;             PG8_LDB(B0, 1, 0); PG8_LDB(B1, 1, 1); PG8_SCHED; PG8_LDA(At, 1, 0); PG8_STAGE(PG8_SA(0, 1), a2 + hstepA, voffA);
;             PG8_WAIT_V(8); PG8_WAIT_L(0); PG8_BAR; PG8_MMA(0, 0, At, B0); PG8_MMA(0, 1, At, B1); PG8_BAR; PG8_SCHED;
;             PG8_LDA(At, 1, 1); PG8_STAGE(PG8_SB(1, 0), b3, voffB); PG8_STAGE(PG8_SB(1, 1), b3 + hstepB, voffB); PG8_STAGE(PG8_SA(1, 0), a3, voffA);
	s_setprio 1
	s_waitcnt lgkmcnt(0)
	v_mfma_f32_16x16x32_bf16 v[62:65], v[146:149], v[206:209], v[62:65]
	v_mfma_f32_16x16x32_bf16 v[62:65], v[162:165], v[212:215], v[62:65]
	v_mfma_f32_16x16x32_bf16 v[54:57], v[162:165], v[220:223], v[54:57]
	v_mfma_f32_16x16x32_bf16 v[54:57], v[146:149], v[216:219], v[54:57]
	v_mfma_f32_16x16x32_bf16 v[38:41], v[146:149], v[224:227], v[38:41]
	v_mfma_f32_16x16x32_bf16 v[38:41], v[162:165], v[228:231], v[38:41]
	v_mfma_f32_16x16x32_bf16 v[22:25], v[162:165], v[236:239], v[22:25]
	v_mfma_f32_16x16x32_bf16 v[22:25], v[146:149], v[232:235], v[22:25]
	v_mfma_f32_16x16x32_bf16 v[14:17], v[182:185], v[232:235], v[14:17]
	v_mfma_f32_16x16x32_bf16 v[14:17], v[186:189], v[236:239], v[14:17]
	v_mfma_f32_16x16x32_bf16 v[30:33], v[186:189], v[228:231], v[30:33]
	v_mfma_f32_16x16x32_bf16 v[30:33], v[182:185], v[224:227], v[30:33]
	v_mfma_f32_16x16x32_bf16 v[46:49], v[182:185], v[216:219], v[46:49]
	v_mfma_f32_16x16x32_bf16 v[46:49], v[186:189], v[220:223], v[46:49]
	v_mfma_f32_16x16x32_bf16 v[58:61], v[186:189], v[212:215], v[58:61]
	v_mfma_f32_16x16x32_bf16 v[58:61], v[182:185], v[206:209], v[58:61]
	s_setprio 0
	s_setprio 1
	v_mfma_f32_16x16x32_bf16 v[42:45], v[198:201], v[206:209], v[42:45]
	v_mfma_f32_16x16x32_bf16 v[42:45], v[202:205], v[212:215], v[42:45]
	v_mfma_f32_16x16x32_bf16 v[26:29], v[202:205], v[220:223], v[26:29]
	v_mfma_f32_16x16x32_bf16 v[26:29], v[198:201], v[216:219], v[26:29]
	v_mfma_f32_16x16x32_bf16 v[10:13], v[198:201], v[224:227], v[10:13]
	v_mfma_f32_16x16x32_bf16 v[10:13], v[202:205], v[228:231], v[10:13]
	v_mfma_f32_16x16x32_bf16 v[2:5], v[202:205], v[236:239], v[2:5]
	v_mfma_f32_16x16x32_bf16 v[2:5], v[198:201], v[232:235], v[2:5]
	v_mfma_f32_16x16x32_bf16 v[6:9], v[190:193], v[232:235], v[6:9]
	v_mfma_f32_16x16x32_bf16 v[6:9], v[194:197], v[236:239], v[6:9]
	v_mfma_f32_16x16x32_bf16 v[18:21], v[194:197], v[228:231], v[18:21]
	v_mfma_f32_16x16x32_bf16 v[18:21], v[190:193], v[224:227], v[18:21]
	v_mfma_f32_16x16x32_bf16 v[34:37], v[190:193], v[216:219], v[34:37]
	v_mfma_f32_16x16x32_bf16 v[34:37], v[194:197], v[220:223], v[34:37]
	v_mfma_f32_16x16x32_bf16 v[50:53], v[194:197], v[212:215], v[50:53]
	v_mfma_f32_16x16x32_bf16 v[50:53], v[190:193], v[206:209], v[50:53]
	s_setprio 0
	s_barrier
	s_add_i32 s45, 0, 0x18000
	v_add_u32_e32 v161, s45, v156
	s_add_i32 s49, 0, 0x1c000
	ds_read_b128 v[146:149], v161
	ds_read_b128 v[162:165], v161 offset:1024
	ds_read_b128 v[182:185], v161 offset:2048
	ds_read_b128 v[186:189], v161 offset:3072
	v_add_u32_e32 v161, s49, v156
	ds_read_b128 v[190:193], v161
	ds_read_b128 v[194:197], v161 offset:1024
	ds_read_b128 v[198:201], v161 offset:2048
	ds_read_b128 v[202:205], v161 offset:3072
	s_add_u32 s46, s66, 0x100000
	s_addc_u32 s47, s67, 0
	s_mov_b32 m0, s19
	v_lshl_add_u64 v[244:245], s[46:47], 0, v[130:131]
	ds_read_b128 v[206:209], v160 offset:32768
	ds_read_b128 v[212:215], v160 offset:33792
	ds_read_b128 v[216:219], v160 offset:34816
	ds_read_b128 v[220:223], v160 offset:35840
	ds_read_b128 v[224:227], v160 offset:36864
	ds_read_b128 v[228:231], v160 offset:37888
	ds_read_b128 v[232:235], v160 offset:38912
	ds_read_b128 v[236:239], v160 offset:39936
	global_load_lds_dwordx4 v[244:245], off
	v_lshl_add_u64 v[244:245], s[46:47], 0, v[134:135]
	s_mov_b32 m0, s20
	s_nop 0
	global_load_lds_dwordx4 v[244:245], off
	s_waitcnt vmcnt(8)
	s_waitcnt lgkmcnt(0)
	s_barrier
	s_setprio 1
	s_waitcnt lgkmcnt(0)
	v_mfma_f32_16x16x32_bf16 v[126:129], v[146:149], v[206:209], v[126:129]
	v_mfma_f32_16x16x32_bf16 v[126:129], v[162:165], v[212:215], v[126:129]
	v_mfma_f32_16x16x32_bf16 v[118:121], v[162:165], v[220:223], v[118:121]
	v_mfma_f32_16x16x32_bf16 v[118:121], v[146:149], v[216:219], v[118:121]
	v_mfma_f32_16x16x32_bf16 v[102:105], v[146:149], v[224:227], v[102:105]
	v_mfma_f32_16x16x32_bf16 v[102:105], v[162:165], v[228:231], v[102:105]
	v_mfma_f32_16x16x32_bf16 v[86:89], v[162:165], v[236:239], v[86:89]
	v_mfma_f32_16x16x32_bf16 v[86:89], v[146:149], v[232:235], v[86:89]
	v_mfma_f32_16x16x32_bf16 v[78:81], v[182:185], v[232:235], v[78:81]
	v_mfma_f32_16x16x32_bf16 v[78:81], v[186:189], v[236:239], v[78:81]
	v_mfma_f32_16x16x32_bf16 v[94:97], v[186:189], v[228:231], v[94:97]
	v_mfma_f32_16x16x32_bf16 v[94:97], v[182:185], v[224:227], v[94:97]
	v_mfma_f32_16x16x32_bf16 v[110:113], v[182:185], v[216:219], v[110:113]
	v_mfma_f32_16x16x32_bf16 v[110:113], v[186:189], v[220:223], v[110:113]
	v_mfma_f32_16x16x32_bf16 v[122:125], v[186:189], v[212:215], v[122:125]
	v_mfma_f32_16x16x32_bf16 v[122:125], v[182:185], v[206:209], v[122:125]
	s_setprio 0
	s_setprio 1
	v_mfma_f32_16x16x32_bf16 v[106:109], v[198:201], v[206:209], v[106:109]
	v_mfma_f32_16x16x32_bf16 v[106:109], v[202:205], v[212:215], v[106:109]
	v_mfma_f32_16x16x32_bf16 v[90:93], v[202:205], v[220:223], v[90:93]
	v_mfma_f32_16x16x32_bf16 v[90:93], v[198:201], v[216:219], v[90:93]
	v_mfma_f32_16x16x32_bf16 v[74:77], v[198:201], v[224:227], v[74:77]
	v_mfma_f32_16x16x32_bf16 v[74:77], v[202:205], v[228:231], v[74:77]
	v_mfma_f32_16x16x32_bf16 v[66:69], v[202:205], v[236:239], v[66:69]
	v_mfma_f32_16x16x32_bf16 v[66:69], v[198:201], v[232:235], v[66:69]
	v_mfma_f32_16x16x32_bf16 v[70:73], v[190:193], v[232:235], v[70:73]
	v_mfma_f32_16x16x32_bf16 v[70:73], v[194:197], v[236:239], v[70:73]
	v_mfma_f32_16x16x32_bf16 v[82:85], v[194:197], v[228:231], v[82:85]
	v_mfma_f32_16x16x32_bf16 v[82:85], v[190:193], v[224:227], v[82:85]
	v_mfma_f32_16x16x32_bf16 v[98:101], v[190:193], v[216:219], v[98:101]
	v_mfma_f32_16x16x32_bf16 v[98:101], v[194:197], v[220:223], v[98:101]
	v_mfma_f32_16x16x32_bf16 v[114:117], v[194:197], v[212:215], v[114:117]
	v_mfma_f32_16x16x32_bf16 v[114:117], v[190:193], v[206:209], v[114:117]
	s_setprio 0
	s_barrier
; #define PG8_STAGE(bufoff, gbase, voff) do { _Pragma("unroll") for (int _i = 0; _i < 2; ++_i) \
;         __builtin_amdgcn_global_load_lds((const unsigned*)((const char*)(gbase) + (voff)[_i]), (PG8_LAS unsigned*)(lds + (bufoff) + ldsw + _i * 8192), 16, 0, 0); } while (0)
; #define PG8_LDA(dst, b, h) do { _Pragma("unroll") for (int m = 0; m < 4; ++m) _Pragma("unroll") for (int k = 0; k < 2; ++k) dst[m][k] = *(const PG8_LAS bf16x8*)(lds + PG8_SA(b, h) + aoff + m * 2048 + k * 1024); } while (0)
; #define PG8_MMA(ai, bj, At, Bt) do { __builtin_amdgcn_s_setprio(1); _Pragma("unroll") for (int m = 0; m < 4; ++m) _Pragma("unroll") for (int n = 0; n < 2; ++n) _Pragma("unroll") for (int k = 0; k < 2; ++k) \
;         acc[ai][bj][m][n] = mma16(Bt[n][k], At[m][k], acc[ai][bj][m][n]); __builtin_amdgcn_s_setprio(0); } while (0)
; #define PG8_WAIT_V(n) asm volatile("s_waitcnt vmcnt(" #n ")" ::: "memory")
; #define PG8_WAIT_L(n) asm volatile("s_waitcnt lgkmcnt(" #n ")" ::: "memory")
; #define PG8_BAR __builtin_amdgcn_s_barrier()
; #define PG8_SCHED __builtin_amdgcn_sched_barrier(0)
; template <class Epi, class Sched, bool ALIGN_EPI = false, bool SP2 = false>
; __device__ __forceinline__ void gemm_phase(PG8_LAS unsigned char* lds, const Gemm g, const Sched& S, const Epi& E) {
;     ...
;         for (int t = 0; t < nt; t += 2) {
;             const bool last = (t == nt - 2);
;             const char* a1 = cA + (size_t)(t + 1) * kstep;
;             const char* a2 = last ? nA : cA + (size_t)(t + 2) * kstep; const char* b2 = last ? nB : cB + (size_t)(t + 2) * kstep;
;             const char* a3 = a2 + kstep; const char* b3 = b2 + kstep;
;             if (last && has_next) S.a_ready(nxt);
;     ...
;             PG8_LDA(At, 1, 1); PG8_STAGE(PG8_SB(1, 0), b3, voffB); PG8_STAGE(PG8_SB(1, 1), b3 + hstepB, voffB); PG8_STAGE(PG8_SA(1, 0), a3, voffA);
;             PG8_WAIT_V(8); PG8_WAIT_L(0); PG8_BAR; PG8_MMA(1, 0, At, B0); PG8_MMA(1, 1, At, B1); PG8_BAR; PG8_SCHED;
	s_add_i32 s45, s45, s12
	v_lshl_add_u64 v[166:167], v[166:167], 0, s[40:41]
	s_mov_b32 m0, s45
	ds_read_b128 v[206:209], v160 offset:49152
	ds_read_b128 v[212:215], v160 offset:50176
	ds_read_b128 v[216:219], v160 offset:51200
	ds_read_b128 v[220:223], v160 offset:52224
	ds_read_b128 v[224:227], v160 offset:53248
	ds_read_b128 v[228:231], v160 offset:54272
	ds_read_b128 v[232:235], v160 offset:55296
	ds_read_b128 v[236:239], v160 offset:56320
	global_load_lds_dwordx4 v[166:167], off
	s_add_i32 m0, s45, 0x2000
	s_add_u32 s46, s64, 0x100080
	v_lshl_add_u64 v[166:167], v[176:177], 0, s[40:41]
	s_addc_u32 s47, s65, 0
	s_add_i32 s45, s49, s12
	global_load_lds_dwordx4 v[166:167], off
	v_lshl_add_u64 v[166:167], s[46:47], 0, v[132:133]
	s_mov_b32 m0, s45
	s_nop 0
	global_load_lds_dwordx4 v[166:167], off
	v_lshl_add_u64 v[166:167], s[46:47], 0, v[136:137]
	s_add_i32 m0, s45, 0x2000
	s_nop 0
	global_load_lds_dwordx4 v[166:167], off
	v_lshl_add_u64 v[166:167], v[240:241], 0, s[40:41]
	s_mov_b32 m0, s22
	s_nop 0
	global_load_lds_dwordx4 v[166:167], off
	v_lshl_add_u64 v[166:167], v[242:243], 0, s[40:41]
	s_mov_b32 m0, s23
	s_nop 0
	global_load_lds_dwordx4 v[166:167], off
	s_waitcnt vmcnt(8)
	s_waitcnt lgkmcnt(0)
	s_barrier
	s_setprio 1
	s_waitcnt lgkmcnt(0)
	v_mfma_f32_16x16x32_bf16 v[62:65], v[146:149], v[206:209], v[62:65]
	v_mfma_f32_16x16x32_bf16 v[62:65], v[162:165], v[212:215], v[62:65]
	v_mfma_f32_16x16x32_bf16 v[54:57], v[162:165], v[220:223], v[54:57]
	v_mfma_f32_16x16x32_bf16 v[54:57], v[146:149], v[216:219], v[54:57]
	v_mfma_f32_16x16x32_bf16 v[38:41], v[146:149], v[224:227], v[38:41]
	v_mfma_f32_16x16x32_bf16 v[38:41], v[162:165], v[228:231], v[38:41]
	v_mfma_f32_16x16x32_bf16 v[22:25], v[162:165], v[236:239], v[22:25]
	v_mfma_f32_16x16x32_bf16 v[22:25], v[146:149], v[232:235], v[22:25]
	v_mfma_f32_16x16x32_bf16 v[14:17], v[182:185], v[232:235], v[14:17]
	v_mfma_f32_16x16x32_bf16 v[14:17], v[186:189], v[236:239], v[14:17]
	v_mfma_f32_16x16x32_bf16 v[30:33], v[186:189], v[228:231], v[30:33]
	v_mfma_f32_16x16x32_bf16 v[30:33], v[182:185], v[224:227], v[30:33]
	v_mfma_f32_16x16x32_bf16 v[46:49], v[182:185], v[216:219], v[46:49]
	v_mfma_f32_16x16x32_bf16 v[46:49], v[186:189], v[220:223], v[46:49]
	v_mfma_f32_16x16x32_bf16 v[58:61], v[186:189], v[212:215], v[58:61]
	v_mfma_f32_16x16x32_bf16 v[58:61], v[182:185], v[206:209], v[58:61]
	s_setprio 0
	s_setprio 1
	v_mfma_f32_16x16x32_bf16 v[42:45], v[198:201], v[206:209], v[42:45]
	v_mfma_f32_16x16x32_bf16 v[42:45], v[202:205], v[212:215], v[42:45]
	v_mfma_f32_16x16x32_bf16 v[26:29], v[202:205], v[220:223], v[26:29]
	v_mfma_f32_16x16x32_bf16 v[26:29], v[198:201], v[216:219], v[26:29]
	v_mfma_f32_16x16x32_bf16 v[10:13], v[198:201], v[224:227], v[10:13]
	v_mfma_f32_16x16x32_bf16 v[10:13], v[202:205], v[228:231], v[10:13]
	v_mfma_f32_16x16x32_bf16 v[2:5], v[202:205], v[236:239], v[2:5]
	v_mfma_f32_16x16x32_bf16 v[2:5], v[198:201], v[232:235], v[2:5]
	v_mfma_f32_16x16x32_bf16 v[6:9], v[190:193], v[232:235], v[6:9]
	v_mfma_f32_16x16x32_bf16 v[6:9], v[194:197], v[236:239], v[6:9]
	v_mfma_f32_16x16x32_bf16 v[18:21], v[194:197], v[228:231], v[18:21]
	v_mfma_f32_16x16x32_bf16 v[18:21], v[190:193], v[224:227], v[18:21]
	v_mfma_f32_16x16x32_bf16 v[34:37], v[190:193], v[216:219], v[34:37]
	v_mfma_f32_16x16x32_bf16 v[34:37], v[194:197], v[220:223], v[34:37]
	v_mfma_f32_16x16x32_bf16 v[50:53], v[194:197], v[212:215], v[50:53]
	v_mfma_f32_16x16x32_bf16 v[50:53], v[190:193], v[206:209], v[50:53]
	s_setprio 0
	s_barrier
	s_add_i32 s37, s37, 2
	s_add_u32 s0, s0, 0x100
	s_addc_u32 s1, s1, 0
	s_add_u32 s35, s35, 0x100
	s_addc_u32 s36, s36, 0
	s_cmp_gt_u32 s37, 61
	s_cbranch_scc0 .LBB0_231
	s_and_b64 vcc, exec, s[42:43]
	s_cbranch_vccz .LBB0_234
	s_barrier

; #define PG8_STAGE(bufoff, gbase, voff) do { _Pragma("unroll") for (int _i = 0; _i < 2; ++_i) \
;         __builtin_amdgcn_global_load_lds((const unsigned*)((const char*)(gbase) + (voff)[_i]), (PG8_LAS unsigned*)(lds + (bufoff) + ldsw + _i * 8192), 16, 0, 0); } while (0)
; #define PG8_LDA(dst, b, h) do { _Pragma("unroll") for (int m = 0; m < 4; ++m) _Pragma("unroll") for (int k = 0; k < 2; ++k) dst[m][k] = *(const PG8_LAS bf16x8*)(lds + PG8_SA(b, h) + aoff + m * 2048 + k * 1024); } while (0)
; #define PG8_LDB(dst, b, h) do { _Pragma("unroll") for (int n = 0; n < 2; ++n) _Pragma("unroll") for (int k = 0; k < 2; ++k) dst[n][k] = *(const PG8_LAS bf16x8*)(lds + PG8_SB(b, h) + boff + n * 2048 + k * 1024); } while (0)
; #define PG8_MMA(ai, bj, At, Bt) do { __builtin_amdgcn_s_setprio(1); _Pragma("unroll") for (int m = 0; m < 4; ++m) _Pragma("unroll") for (int n = 0; n < 2; ++n) _Pragma("unroll") for (int k = 0; k < 2; ++k) \
;         acc[ai][bj][m][n] = mma16(Bt[n][k], At[m][k], acc[ai][bj][m][n]); __builtin_amdgcn_s_setprio(0); } while (0)
; #define PG8_WAIT_V(n) asm volatile("s_waitcnt vmcnt(" #n ")" ::: "memory")
; #define PG8_WAIT_L(n) asm volatile("s_waitcnt lgkmcnt(" #n ")" ::: "memory")
; template <class Epi, class Sched, bool ALIGN_EPI = false, bool SP2 = false>
; __device__ __forceinline__ void gemm_phase(PG8_LAS unsigned char* lds, const Gemm g, const Sched& S, const Epi& E) {
;     ...
;         for (int t = 0; t < nt; t += 2) {
;             const bool last = (t == nt - 2);
;             const char* a1 = cA + (size_t)(t + 1) * kstep;
;             const char* a2 = last ? nA : cA + (size_t)(t + 2) * kstep; const char* b2 = last ? nB : cB + (size_t)(t + 2) * kstep;
;             const char* a3 = a2 + kstep; const char* b3 = b2 + kstep;
;             if (last && has_next) S.a_ready(nxt);
;             if constexpr (SP2) {
;             PG8_LDB(B0, 0, 0); PG8_LDB(B1, 0, 1); PG8_SCHED; PG8_LDA(At, 0, 0); PG8_STAGE(PG8_SA(1, 1), a1 + hstepA, voffA);
;             PG8_WAIT_V(8); PG8_WAIT_L(0); PG8_BAR; PG8_MMA(0, 0, At, B0); PG8_MMA(0, 1, At, B1); PG8_BAR; PG8_SCHED;
;             PG8_LDA(At, 0, 1); PG8_STAGE(PG8_SB(0, 0), b2, voffB); PG8_STAGE(PG8_SB(0, 1), b2 + hstepB, voffB); PG8_STAGE(PG8_SA(0, 0), a2, voffA);
;             PG8_WAIT_V(8); PG8_WAIT_L(0); PG8_BAR; PG8_MMA(1, 0, At, B0); PG8_MMA(1, 1, At, B1); PG8_BAR; PG8_SCHED;
.LBB0_249:
	ds_read_b128 v[122:125], v181
	ds_read_b128 v[126:129], v181 offset:1024
	ds_read_b128 v[134:137], v181 offset:2048
	ds_read_b128 v[142:145], v181 offset:3072
	ds_read_b128 v[184:187], v182
	ds_read_b128 v[188:191], v182 offset:1024
	ds_read_b128 v[192:195], v182 offset:2048
	ds_read_b128 v[196:199], v182 offset:3072
	s_add_u32 s51, s0, 0xfff80080
	s_addc_u32 s63, s1, -1
	s_cmp_eq_u32 s50, 28
	s_cselect_b32 s95, s65, s63
	s_cselect_b32 s94, s64, s51
	s_cselect_b32 s91, s36, s47
	s_cselect_b32 s90, s37, s46
	v_lshl_add_u64 v[166:167], s[0:1], 0, v[158:159]
	s_add_i32 m0, s13, 0xc000
	ds_read_b128 v[200:203], v183
	ds_read_b128 v[204:207], v183 offset:1024
	ds_read_b128 v[212:215], v183 offset:2048
	ds_read_b128 v[216:219], v183 offset:3072
	ds_read_b128 v[220:223], v183 offset:4096
	ds_read_b128 v[224:227], v183 offset:5120
	ds_read_b128 v[228:231], v183 offset:6144
	ds_read_b128 v[232:235], v183 offset:7168
	global_load_lds_dwordx4 v[166:167], off
	v_lshl_add_u64 v[166:167], s[0:1], 0, v[160:161]
	s_add_i32 m0, s13, 0xe000
	s_nop 0
	global_load_lds_dwordx4 v[166:167], off
	s_waitcnt vmcnt(8)
	s_waitcnt lgkmcnt(0)
	s_barrier
	s_setprio 1
	s_waitcnt lgkmcnt(0)
	v_mfma_i32_16x16x64_i8 v[138:141], v[122:125], v[200:203], v[138:141]
	v_mfma_i32_16x16x64_i8 v[138:141], v[126:129], v[204:207], v[138:141]
	v_mfma_i32_16x16x64_i8 v[110:113], v[126:129], v[216:219], v[110:113]
	v_mfma_i32_16x16x64_i8 v[110:113], v[122:125], v[212:215], v[110:113]
	v_mfma_i32_16x16x64_i8 v[94:97], v[122:125], v[220:223], v[94:97]
	v_mfma_i32_16x16x64_i8 v[94:97], v[126:129], v[224:227], v[94:97]
	v_mfma_i32_16x16x64_i8 v[78:81], v[126:129], v[232:235], v[78:81]
	v_mfma_i32_16x16x64_i8 v[78:81], v[122:125], v[228:231], v[78:81]
	v_mfma_i32_16x16x64_i8 v[74:77], v[134:137], v[228:231], v[74:77]
	v_mfma_i32_16x16x64_i8 v[74:77], v[142:145], v[232:235], v[74:77]
	v_mfma_i32_16x16x64_i8 v[90:93], v[142:145], v[224:227], v[90:93]
	v_mfma_i32_16x16x64_i8 v[90:93], v[134:137], v[220:223], v[90:93]
	v_mfma_i32_16x16x64_i8 v[106:109], v[134:137], v[212:215], v[106:109]
	v_mfma_i32_16x16x64_i8 v[106:109], v[142:145], v[216:219], v[106:109]
	v_mfma_i32_16x16x64_i8 v[130:133], v[142:145], v[204:207], v[130:133]
	v_mfma_i32_16x16x64_i8 v[130:133], v[134:137], v[200:203], v[130:133]
	s_setprio 0
	s_setprio 1
	v_mfma_i32_16x16x64_i8 v[114:117], v[192:195], v[200:203], v[114:117]
	v_mfma_i32_16x16x64_i8 v[114:117], v[196:199], v[204:207], v[114:117]
	v_mfma_i32_16x16x64_i8 v[98:101], v[196:199], v[216:219], v[98:101]
	v_mfma_i32_16x16x64_i8 v[98:101], v[192:195], v[212:215], v[98:101]
	v_mfma_i32_16x16x64_i8 v[82:85], v[192:195], v[220:223], v[82:85]
	v_mfma_i32_16x16x64_i8 v[82:85], v[196:199], v[224:227], v[82:85]
	v_mfma_i32_16x16x64_i8 v[66:69], v[196:199], v[232:235], v[66:69]
	v_mfma_i32_16x16x64_i8 v[66:69], v[192:195], v[228:231], v[66:69]
	v_mfma_i32_16x16x64_i8 v[70:73], v[184:187], v[228:231], v[70:73]
	v_mfma_i32_16x16x64_i8 v[70:73], v[188:191], v[232:235], v[70:73]
	v_mfma_i32_16x16x64_i8 v[86:89], v[188:191], v[224:227], v[86:89]
	v_mfma_i32_16x16x64_i8 v[86:89], v[184:187], v[220:223], v[86:89]
	v_mfma_i32_16x16x64_i8 v[102:105], v[184:187], v[212:215], v[102:105]
	v_mfma_i32_16x16x64_i8 v[102:105], v[188:191], v[216:219], v[102:105]
	v_mfma_i32_16x16x64_i8 v[118:121], v[188:191], v[204:207], v[118:121]
	v_mfma_i32_16x16x64_i8 v[118:121], v[184:187], v[200:203], v[118:121]
	s_setprio 0
	s_barrier
	s_add_i32 s51, s27, s7
	v_lshl_add_u64 v[166:167], s[90:91], 0, v[148:149]
	s_mov_b32 m0, s51
	ds_read_b128 v[200:203], v183 offset:16384
	ds_read_b128 v[204:207], v183 offset:17408
	ds_read_b128 v[212:215], v183 offset:18432
	ds_read_b128 v[216:219], v183 offset:19456
	ds_read_b128 v[220:223], v183 offset:20480
	ds_read_b128 v[224:227], v183 offset:21504
	ds_read_b128 v[228:231], v183 offset:22528
	ds_read_b128 v[232:235], v183 offset:23552
	global_load_lds_dwordx4 v[166:167], off
	s_add_i32 m0, s51, 0x2000
	s_add_u32 s68, s90, 0x80000
	v_lshl_add_u64 v[208:209], s[90:91], 0, v[152:153]
	s_addc_u32 s69, s91, 0
	s_add_i32 s51, s28, s7
	global_load_lds_dwordx4 v[208:209], off
	v_lshl_add_u64 v[236:237], s[68:69], 0, v[148:149]
	s_mov_b32 m0, s51
	v_lshl_add_u64 v[238:239], s[94:95], 0, v[150:151]
	global_load_lds_dwordx4 v[236:237], off
	v_lshl_add_u64 v[236:237], s[68:69], 0, v[152:153]
	s_add_i32 m0, s51, 0x2000
	s_nop 0
	global_load_lds_dwordx4 v[236:237], off
	v_lshl_add_u64 v[236:237], s[94:95], 0, v[146:147]
	s_mov_b32 m0, s13
	s_nop 0
	global_load_lds_dwordx4 v[236:237], off
	s_mov_b32 m0, s18
	s_nop 0
	global_load_lds_dwordx4 v[238:239], off
	s_waitcnt vmcnt(8)
	s_waitcnt lgkmcnt(0)
	s_barrier
; #define PG8_STAGE(bufoff, gbase, voff) do { _Pragma("unroll") for (int _i = 0; _i < 2; ++_i) \
;         __builtin_amdgcn_global_load_lds((const unsigned*)((const char*)(gbase) + (voff)[_i]), (PG8_LAS unsigned*)(lds + (bufoff) + ldsw + _i * 8192), 16, 0, 0); } while (0)
; #define PG8_LDA(dst, b, h) do { _Pragma("unroll") for (int m = 0; m < 4; ++m) _Pragma("unroll") for (int k = 0; k < 2; ++k) dst[m][k] = *(const PG8_LAS bf16x8*)(lds + PG8_SA(b, h) + aoff + m * 2048 + k * 1024); } while (0)
; #define PG8_LDB(dst, b, h) do { _Pragma("unroll") for (int n = 0; n < 2; ++n) _Pragma("unroll") for (int k = 0; k < 2; ++k) dst[n][k] = *(const PG8_LAS bf16x8*)(lds + PG8_SB(b, h) + boff + n * 2048 + k * 1024); } while (0)
; #define PG8_MMA(ai, bj, At, Bt) do { __builtin_amdgcn_s_setprio(1); _Pragma("unroll") for (int m = 0; m < 4; ++m) _Pragma("unroll") for (int n = 0; n < 2; ++n) _Pragma("unroll") for (int k = 0; k < 2; ++k) \
;         acc[ai][bj][m][n] = mma16(Bt[n][k], At[m][k], acc[ai][bj][m][n]); __builtin_amdgcn_s_setprio(0); } while (0)
; #define PG8_WAIT_V(n) asm volatile("s_waitcnt vmcnt(" #n ")" ::: "memory")
; #define PG8_WAIT_L(n) asm volatile("s_waitcnt lgkmcnt(" #n ")" ::: "memory")
; #define PG8_BAR __builtin_amdgcn_s_barrier()
; #define PG8_SCHED __builtin_amdgcn_sched_barrier(0)
; template <class Epi, class Sched, bool ALIGN_EPI = false, bool SP2 = false>
; __device__ __forceinline__ void gemm_phase(PG8_LAS unsigned char* lds, const Gemm g, const Sched& S, const Epi& E) {
;     ...
;             PG8_WAIT_V(8); PG8_WAIT_L(0); PG8_BAR; PG8_MMA(1, 0, At, B0); PG8_MMA(1, 1, At, B1); PG8_BAR; PG8_SCHED;
;             PG8_LDB(B0, 1, 0); PG8_LDB(B1, 1, 1); PG8_SCHED; PG8_LDA(At, 1, 0); PG8_STAGE(PG8_SA(0, 1), a2 + hstepA, voffA);
;             PG8_WAIT_V(8); PG8_WAIT_L(0); PG8_BAR; PG8_MMA(0, 0, At, B0); PG8_MMA(0, 1, At, B1); PG8_BAR; PG8_SCHED;
;             PG8_LDA(At, 1, 1); PG8_STAGE(PG8_SB(1, 0), b3, voffB); PG8_STAGE(PG8_SB(1, 1), b3 + hstepB, voffB); PG8_STAGE(PG8_SA(1, 0), a3, voffA);
	s_setprio 1
	s_waitcnt lgkmcnt(0)
	v_mfma_i32_16x16x64_i8 v[62:65], v[122:125], v[200:203], v[62:65]
	v_mfma_i32_16x16x64_i8 v[62:65], v[126:129], v[204:207], v[62:65]
	v_mfma_i32_16x16x64_i8 v[46:49], v[126:129], v[216:219], v[46:49]
	v_mfma_i32_16x16x64_i8 v[46:49], v[122:125], v[212:215], v[46:49]
	v_mfma_i32_16x16x64_i8 v[30:33], v[122:125], v[220:223], v[30:33]
	v_mfma_i32_16x16x64_i8 v[30:33], v[126:129], v[224:227], v[30:33]
	v_mfma_i32_16x16x64_i8 v[14:17], v[126:129], v[232:235], v[14:17]
	v_mfma_i32_16x16x64_i8 v[14:17], v[122:125], v[228:231], v[14:17]
	v_mfma_i32_16x16x64_i8 v[10:13], v[134:137], v[228:231], v[10:13]
	v_mfma_i32_16x16x64_i8 v[10:13], v[142:145], v[232:235], v[10:13]
	v_mfma_i32_16x16x64_i8 v[26:29], v[142:145], v[224:227], v[26:29]
	v_mfma_i32_16x16x64_i8 v[26:29], v[134:137], v[220:223], v[26:29]
	v_mfma_i32_16x16x64_i8 v[42:45], v[134:137], v[212:215], v[42:45]
	v_mfma_i32_16x16x64_i8 v[42:45], v[142:145], v[216:219], v[42:45]
	v_mfma_i32_16x16x64_i8 v[58:61], v[142:145], v[204:207], v[58:61]
	v_mfma_i32_16x16x64_i8 v[58:61], v[134:137], v[200:203], v[58:61]
	s_setprio 0
	s_setprio 1
	v_mfma_i32_16x16x64_i8 v[50:53], v[192:195], v[200:203], v[50:53]
	v_mfma_i32_16x16x64_i8 v[50:53], v[196:199], v[204:207], v[50:53]
	v_mfma_i32_16x16x64_i8 v[34:37], v[196:199], v[216:219], v[34:37]
	v_mfma_i32_16x16x64_i8 v[34:37], v[192:195], v[212:215], v[34:37]
	v_mfma_i32_16x16x64_i8 v[18:21], v[192:195], v[220:223], v[18:21]
	v_mfma_i32_16x16x64_i8 v[18:21], v[196:199], v[224:227], v[18:21]
	v_mfma_i32_16x16x64_i8 v[2:5], v[196:199], v[232:235], v[2:5]
	v_mfma_i32_16x16x64_i8 v[2:5], v[192:195], v[228:231], v[2:5]
	v_mfma_i32_16x16x64_i8 v[6:9], v[184:187], v[228:231], v[6:9]
	v_mfma_i32_16x16x64_i8 v[6:9], v[188:191], v[232:235], v[6:9]
	v_mfma_i32_16x16x64_i8 v[22:25], v[188:191], v[224:227], v[22:25]
	v_mfma_i32_16x16x64_i8 v[22:25], v[184:187], v[220:223], v[22:25]
	v_mfma_i32_16x16x64_i8 v[38:41], v[184:187], v[212:215], v[38:41]
	v_mfma_i32_16x16x64_i8 v[38:41], v[188:191], v[216:219], v[38:41]
	v_mfma_i32_16x16x64_i8 v[54:57], v[188:191], v[204:207], v[54:57]
	v_mfma_i32_16x16x64_i8 v[54:57], v[184:187], v[200:203], v[54:57]
	s_setprio 0
	s_barrier
	s_add_i32 s51, 0, 0x18000
	s_add_i32 s63, 0, 0x1c000
	v_add_u32_e32 v142, s51, v176
	v_add_u32_e32 v196, s63, v176
	ds_read_b128 v[122:125], v142
	ds_read_b128 v[126:129], v142 offset:1024
	ds_read_b128 v[134:137], v142 offset:2048
	ds_read_b128 v[142:145], v142 offset:3072
	ds_read_b128 v[184:187], v196
	ds_read_b128 v[188:191], v196 offset:1024
	ds_read_b128 v[192:195], v196 offset:2048
	ds_read_b128 v[196:199], v196 offset:3072
	s_add_u32 s68, s94, 0x80000
	s_addc_u32 s69, s95, 0
	s_mov_b32 m0, s19
	v_lshl_add_u64 v[240:241], s[68:69], 0, v[146:147]
	ds_read_b128 v[200:203], v183 offset:32768
	ds_read_b128 v[204:207], v183 offset:33792
	ds_read_b128 v[212:215], v183 offset:34816
	ds_read_b128 v[216:219], v183 offset:35840
	ds_read_b128 v[220:223], v183 offset:36864
	ds_read_b128 v[224:227], v183 offset:37888
	ds_read_b128 v[228:231], v183 offset:38912
	ds_read_b128 v[232:235], v183 offset:39936
	global_load_lds_dwordx4 v[240:241], off
	v_lshl_add_u64 v[240:241], s[68:69], 0, v[150:151]
	s_mov_b32 m0, s20
	s_nop 0
	global_load_lds_dwordx4 v[240:241], off
	s_waitcnt vmcnt(8)
	s_waitcnt lgkmcnt(0)
	s_barrier
	s_setprio 1
	s_waitcnt lgkmcnt(0)
	v_mfma_i32_16x16x64_i8 v[138:141], v[122:125], v[200:203], v[138:141]
	v_mfma_i32_16x16x64_i8 v[138:141], v[126:129], v[204:207], v[138:141]
	v_mfma_i32_16x16x64_i8 v[110:113], v[126:129], v[216:219], v[110:113]
	v_mfma_i32_16x16x64_i8 v[110:113], v[122:125], v[212:215], v[110:113]
	v_mfma_i32_16x16x64_i8 v[94:97], v[122:125], v[220:223], v[94:97]
	v_mfma_i32_16x16x64_i8 v[94:97], v[126:129], v[224:227], v[94:97]
	v_mfma_i32_16x16x64_i8 v[78:81], v[126:129], v[232:235], v[78:81]
	v_mfma_i32_16x16x64_i8 v[78:81], v[122:125], v[228:231], v[78:81]
	v_mfma_i32_16x16x64_i8 v[74:77], v[134:137], v[228:231], v[74:77]
	v_mfma_i32_16x16x64_i8 v[74:77], v[142:145], v[232:235], v[74:77]
	v_mfma_i32_16x16x64_i8 v[90:93], v[142:145], v[224:227], v[90:93]
	v_mfma_i32_16x16x64_i8 v[90:93], v[134:137], v[220:223], v[90:93]
	v_mfma_i32_16x16x64_i8 v[106:109], v[134:137], v[212:215], v[106:109]
	v_mfma_i32_16x16x64_i8 v[106:109], v[142:145], v[216:219], v[106:109]
	v_mfma_i32_16x16x64_i8 v[130:133], v[142:145], v[204:207], v[130:133]
	v_mfma_i32_16x16x64_i8 v[130:133], v[134:137], v[200:203], v[130:133]
	s_setprio 0
	s_setprio 1
	v_mfma_i32_16x16x64_i8 v[114:117], v[192:195], v[200:203], v[114:117]
	v_mfma_i32_16x16x64_i8 v[114:117], v[196:199], v[204:207], v[114:117]
	v_mfma_i32_16x16x64_i8 v[98:101], v[196:199], v[216:219], v[98:101]
	v_mfma_i32_16x16x64_i8 v[98:101], v[192:195], v[212:215], v[98:101]
	v_mfma_i32_16x16x64_i8 v[82:85], v[192:195], v[220:223], v[82:85]
	v_mfma_i32_16x16x64_i8 v[82:85], v[196:199], v[224:227], v[82:85]
	v_mfma_i32_16x16x64_i8 v[66:69], v[196:199], v[232:235], v[66:69]
	v_mfma_i32_16x16x64_i8 v[66:69], v[192:195], v[228:231], v[66:69]
	v_mfma_i32_16x16x64_i8 v[70:73], v[184:187], v[228:231], v[70:73]
	v_mfma_i32_16x16x64_i8 v[70:73], v[188:191], v[232:235], v[70:73]
	v_mfma_i32_16x16x64_i8 v[86:89], v[188:191], v[224:227], v[86:89]
	v_mfma_i32_16x16x64_i8 v[86:89], v[184:187], v[220:223], v[86:89]
	v_mfma_i32_16x16x64_i8 v[102:105], v[184:187], v[212:215], v[102:105]
	v_mfma_i32_16x16x64_i8 v[102:105], v[188:191], v[216:219], v[102:105]
	v_mfma_i32_16x16x64_i8 v[118:121], v[188:191], v[204:207], v[118:121]
	v_mfma_i32_16x16x64_i8 v[118:121], v[184:187], v[200:203], v[118:121]
	s_setprio 0
	s_barrier
; #define PG8_STAGE(bufoff, gbase, voff) do { _Pragma("unroll") for (int _i = 0; _i < 2; ++_i) \
;         __builtin_amdgcn_global_load_lds((const unsigned*)((const char*)(gbase) + (voff)[_i]), (PG8_LAS unsigned*)(lds + (bufoff) + ldsw + _i * 8192), 16, 0, 0); } while (0)
; #define PG8_LDA(dst, b, h) do { _Pragma("unroll") for (int m = 0; m < 4; ++m) _Pragma("unroll") for (int k = 0; k < 2; ++k) dst[m][k] = *(const PG8_LAS bf16x8*)(lds + PG8_SA(b, h) + aoff + m * 2048 + k * 1024); } while (0)
; #define PG8_MMA(ai, bj, At, Bt) do { __builtin_amdgcn_s_setprio(1); _Pragma("unroll") for (int m = 0; m < 4; ++m) _Pragma("unroll") for (int n = 0; n < 2; ++n) _Pragma("unroll") for (int k = 0; k < 2; ++k) \
;         acc[ai][bj][m][n] = mma16(Bt[n][k], At[m][k], acc[ai][bj][m][n]); __builtin_amdgcn_s_setprio(0); } while (0)
; #define PG8_WAIT_V(n) asm volatile("s_waitcnt vmcnt(" #n ")" ::: "memory")
; #define PG8_WAIT_L(n) asm volatile("s_waitcnt lgkmcnt(" #n ")" ::: "memory")
; #define PG8_BAR __builtin_amdgcn_s_barrier()
; #define PG8_SCHED __builtin_amdgcn_sched_barrier(0)
; template <class Epi, class Sched, bool ALIGN_EPI = false, bool SP2 = false>
; __device__ __forceinline__ void gemm_phase(PG8_LAS unsigned char* lds, const Gemm g, const Sched& S, const Epi& E) {
;     ...
;         for (int t = 0; t < nt; t += 2) {
;             const bool last = (t == nt - 2);
;             const char* a1 = cA + (size_t)(t + 1) * kstep;
;             const char* a2 = last ? nA : cA + (size_t)(t + 2) * kstep; const char* b2 = last ? nB : cB + (size_t)(t + 2) * kstep;
;             const char* a3 = a2 + kstep; const char* b3 = b2 + kstep;
;             if (last && has_next) S.a_ready(nxt);
;     ...
;             PG8_LDA(At, 1, 1); PG8_STAGE(PG8_SB(1, 0), b3, voffB); PG8_STAGE(PG8_SB(1, 1), b3 + hstepB, voffB); PG8_STAGE(PG8_SA(1, 0), a3, voffA);
;             PG8_WAIT_V(8); PG8_WAIT_L(0); PG8_BAR; PG8_MMA(1, 0, At, B0); PG8_MMA(1, 1, At, B1); PG8_BAR; PG8_SCHED;
	s_add_i32 s51, s51, s7
	v_lshl_add_u64 v[166:167], v[166:167], 0, s[48:49]
	s_mov_b32 m0, s51
	ds_read_b128 v[200:203], v183 offset:49152
	ds_read_b128 v[204:207], v183 offset:50176
	ds_read_b128 v[212:215], v183 offset:51200
	ds_read_b128 v[216:219], v183 offset:52224
	ds_read_b128 v[220:223], v183 offset:53248
	ds_read_b128 v[224:227], v183 offset:54272
	ds_read_b128 v[228:231], v183 offset:55296
	ds_read_b128 v[232:235], v183 offset:56320
	global_load_lds_dwordx4 v[166:167], off
	s_add_i32 m0, s51, 0x2000
	s_add_u32 s68, s90, 0x80080
	v_lshl_add_u64 v[166:167], v[208:209], 0, s[48:49]
	s_addc_u32 s69, s91, 0
	s_add_i32 s51, s63, s7
	global_load_lds_dwordx4 v[166:167], off
	v_lshl_add_u64 v[166:167], s[68:69], 0, v[148:149]
	s_mov_b32 m0, s51
	s_nop 0
	global_load_lds_dwordx4 v[166:167], off
	v_lshl_add_u64 v[166:167], s[68:69], 0, v[152:153]
	s_add_i32 m0, s51, 0x2000
	s_nop 0
	global_load_lds_dwordx4 v[166:167], off
	v_lshl_add_u64 v[166:167], v[236:237], 0, s[48:49]
	s_mov_b32 m0, s23
	s_nop 0
	global_load_lds_dwordx4 v[166:167], off
	v_lshl_add_u64 v[166:167], v[238:239], 0, s[48:49]
	s_mov_b32 m0, s24
	s_nop 0
	global_load_lds_dwordx4 v[166:167], off
	s_waitcnt vmcnt(8)
	s_waitcnt lgkmcnt(0)
	s_barrier
	s_setprio 1
	s_waitcnt lgkmcnt(0)
	v_mfma_i32_16x16x64_i8 v[62:65], v[122:125], v[200:203], v[62:65]
	v_mfma_i32_16x16x64_i8 v[62:65], v[126:129], v[204:207], v[62:65]
	v_mfma_i32_16x16x64_i8 v[46:49], v[126:129], v[216:219], v[46:49]
	v_mfma_i32_16x16x64_i8 v[46:49], v[122:125], v[212:215], v[46:49]
	v_mfma_i32_16x16x64_i8 v[30:33], v[122:125], v[220:223], v[30:33]
	v_mfma_i32_16x16x64_i8 v[30:33], v[126:129], v[224:227], v[30:33]
	v_mfma_i32_16x16x64_i8 v[14:17], v[126:129], v[232:235], v[14:17]
	v_mfma_i32_16x16x64_i8 v[14:17], v[122:125], v[228:231], v[14:17]
	v_mfma_i32_16x16x64_i8 v[10:13], v[134:137], v[228:231], v[10:13]
	v_mfma_i32_16x16x64_i8 v[10:13], v[142:145], v[232:235], v[10:13]
	v_mfma_i32_16x16x64_i8 v[26:29], v[142:145], v[224:227], v[26:29]
	v_mfma_i32_16x16x64_i8 v[26:29], v[134:137], v[220:223], v[26:29]
	v_mfma_i32_16x16x64_i8 v[42:45], v[134:137], v[212:215], v[42:45]
	v_mfma_i32_16x16x64_i8 v[42:45], v[142:145], v[216:219], v[42:45]
	v_mfma_i32_16x16x64_i8 v[58:61], v[142:145], v[204:207], v[58:61]
	v_mfma_i32_16x16x64_i8 v[58:61], v[134:137], v[200:203], v[58:61]
	s_setprio 0
	s_setprio 1
	v_mfma_i32_16x16x64_i8 v[50:53], v[192:195], v[200:203], v[50:53]
	v_mfma_i32_16x16x64_i8 v[50:53], v[196:199], v[204:207], v[50:53]
	v_mfma_i32_16x16x64_i8 v[34:37], v[196:199], v[216:219], v[34:37]
	v_mfma_i32_16x16x64_i8 v[34:37], v[192:195], v[212:215], v[34:37]
	v_mfma_i32_16x16x64_i8 v[18:21], v[192:195], v[220:223], v[18:21]
	v_mfma_i32_16x16x64_i8 v[18:21], v[196:199], v[224:227], v[18:21]
	v_mfma_i32_16x16x64_i8 v[2:5], v[196:199], v[232:235], v[2:5]
	v_mfma_i32_16x16x64_i8 v[2:5], v[192:195], v[228:231], v[2:5]
	v_mfma_i32_16x16x64_i8 v[6:9], v[184:187], v[228:231], v[6:9]
	v_mfma_i32_16x16x64_i8 v[6:9], v[188:191], v[232:235], v[6:9]
	v_mfma_i32_16x16x64_i8 v[22:25], v[188:191], v[224:227], v[22:25]
	v_mfma_i32_16x16x64_i8 v[22:25], v[184:187], v[220:223], v[22:25]
	v_mfma_i32_16x16x64_i8 v[38:41], v[184:187], v[212:215], v[38:41]
	v_mfma_i32_16x16x64_i8 v[38:41], v[188:191], v[216:219], v[38:41]
	v_mfma_i32_16x16x64_i8 v[54:57], v[188:191], v[204:207], v[54:57]
	v_mfma_i32_16x16x64_i8 v[54:57], v[184:187], v[200:203], v[54:57]
	s_setprio 0
	s_barrier
	s_add_i32 s50, s50, 2
	s_add_u32 s0, s0, 0x100
	s_addc_u32 s1, s1, 0
	s_add_u32 s46, s46, 0x100
	s_addc_u32 s47, s47, 0
	s_cmp_gt_u32 s50, 29
	s_cbranch_scc0 .LBB0_249
	s_and_b64 vcc, exec, s[54:55]
	s_cbranch_vccz .LBB0_252
	s_barrier

; #define PG8_STAGE(bufoff, gbase, voff) do { _Pragma("unroll") for (int _i = 0; _i < 2; ++_i) \
;         __builtin_amdgcn_global_load_lds((const unsigned*)((const char*)(gbase) + (voff)[_i]), (PG8_LAS unsigned*)(lds + (bufoff) + ldsw + _i * 8192), 16, 0, 0); } while (0)
; #define PG8_LDA(dst, b, h) do { _Pragma("unroll") for (int m = 0; m < 4; ++m) _Pragma("unroll") for (int k = 0; k < 2; ++k) dst[m][k] = *(const PG8_LAS bf16x8*)(lds + PG8_SA(b, h) + aoff + m * 2048 + k * 1024); } while (0)
; #define PG8_LDB(dst, b, h) do { _Pragma("unroll") for (int n = 0; n < 2; ++n) _Pragma("unroll") for (int k = 0; k < 2; ++k) dst[n][k] = *(const PG8_LAS bf16x8*)(lds + PG8_SB(b, h) + boff + n * 2048 + k * 1024); } while (0)
; #define PG8_MMA(ai, bj, At, Bt) do { __builtin_amdgcn_s_setprio(1); _Pragma("unroll") for (int m = 0; m < 4; ++m) _Pragma("unroll") for (int n = 0; n < 2; ++n) _Pragma("unroll") for (int k = 0; k < 2; ++k) \
;         acc[ai][bj][m][n] = mma16(Bt[n][k], At[m][k], acc[ai][bj][m][n]); __builtin_amdgcn_s_setprio(0); } while (0)
; #define PG8_WAIT_V(n) asm volatile("s_waitcnt vmcnt(" #n ")" ::: "memory")
; #define PG8_WAIT_L(n) asm volatile("s_waitcnt lgkmcnt(" #n ")" ::: "memory")
; template <class Epi, class Sched, bool ALIGN_EPI = false, bool SP2 = false>
; __device__ __forceinline__ void gemm_phase(PG8_LAS unsigned char* lds, const Gemm g, const Sched& S, const Epi& E) {
;     ...
;         for (int t = 0; t < nt; t += 2) {
;             const bool last = (t == nt - 2);
;             const char* a1 = cA + (size_t)(t + 1) * kstep;
;             const char* a2 = last ? nA : cA + (size_t)(t + 2) * kstep; const char* b2 = last ? nB : cB + (size_t)(t + 2) * kstep;
;             const char* a3 = a2 + kstep; const char* b3 = b2 + kstep;
;             if (last && has_next) S.a_ready(nxt);
;             if constexpr (SP2) {
;             PG8_LDB(B0, 0, 0); PG8_LDB(B1, 0, 1); PG8_SCHED; PG8_LDA(At, 0, 0); PG8_STAGE(PG8_SA(1, 1), a1 + hstepA, voffA);
;             PG8_WAIT_V(8); PG8_WAIT_L(0); PG8_BAR; PG8_MMA(0, 0, At, B0); PG8_MMA(0, 1, At, B1); PG8_BAR; PG8_SCHED;
;             PG8_LDA(At, 0, 1); PG8_STAGE(PG8_SB(0, 0), b2, voffB); PG8_STAGE(PG8_SB(0, 1), b2 + hstepB, voffB); PG8_STAGE(PG8_SA(0, 0), a2, voffA);
;             PG8_WAIT_V(8); PG8_WAIT_L(0); PG8_BAR; PG8_MMA(1, 0, At, B0); PG8_MMA(1, 1, At, B1); PG8_BAR; PG8_SCHED;
.LBB0_275:
	ds_read_b128 v[122:125], v169
	ds_read_b128 v[126:129], v169 offset:1024
	ds_read_b128 v[134:137], v169 offset:2048
	ds_read_b128 v[142:145], v169 offset:3072
	ds_read_b128 v[182:185], v170
	ds_read_b128 v[186:189], v170 offset:1024
	ds_read_b128 v[190:193], v170 offset:2048
	ds_read_b128 v[194:197], v170 offset:3072
	s_add_u32 s51, s0, 0xfff80080
	s_addc_u32 s63, s1, -1
	s_cmp_eq_u32 s50, 28
	s_cselect_b32 s67, s55, s63
	s_cselect_b32 s66, s54, s51
	s_cselect_b32 s65, s37, s49
	s_cselect_b32 s64, s46, s47
	v_lshl_add_u64 v[166:167], s[0:1], 0, v[158:159]
	s_add_i32 m0, s18, 0xc000
	ds_read_b128 v[198:201], v171
	ds_read_b128 v[202:205], v171 offset:1024
	ds_read_b128 v[206:209], v171 offset:2048
	ds_read_b128 v[212:215], v171 offset:3072
	ds_read_b128 v[216:219], v171 offset:4096
	ds_read_b128 v[220:223], v171 offset:5120
	ds_read_b128 v[224:227], v171 offset:6144
	ds_read_b128 v[228:231], v171 offset:7168
	global_load_lds_dwordx4 v[166:167], off
	v_lshl_add_u64 v[166:167], s[0:1], 0, v[160:161]
	s_add_i32 m0, s18, 0xe000
	s_nop 0
	global_load_lds_dwordx4 v[166:167], off
	s_waitcnt vmcnt(8)
	s_waitcnt lgkmcnt(0)
	s_barrier
	s_setprio 1
	s_waitcnt lgkmcnt(0)
	v_mfma_i32_16x16x64_i8 v[138:141], v[122:125], v[198:201], v[138:141]
	v_mfma_i32_16x16x64_i8 v[138:141], v[126:129], v[202:205], v[138:141]
	v_mfma_i32_16x16x64_i8 v[110:113], v[126:129], v[212:215], v[110:113]
	v_mfma_i32_16x16x64_i8 v[110:113], v[122:125], v[206:209], v[110:113]
	v_mfma_i32_16x16x64_i8 v[94:97], v[122:125], v[216:219], v[94:97]
	v_mfma_i32_16x16x64_i8 v[94:97], v[126:129], v[220:223], v[94:97]
	v_mfma_i32_16x16x64_i8 v[78:81], v[126:129], v[228:231], v[78:81]
	v_mfma_i32_16x16x64_i8 v[78:81], v[122:125], v[224:227], v[78:81]
	v_mfma_i32_16x16x64_i8 v[74:77], v[134:137], v[224:227], v[74:77]
	v_mfma_i32_16x16x64_i8 v[74:77], v[142:145], v[228:231], v[74:77]
	v_mfma_i32_16x16x64_i8 v[90:93], v[142:145], v[220:223], v[90:93]
	v_mfma_i32_16x16x64_i8 v[90:93], v[134:137], v[216:219], v[90:93]
	v_mfma_i32_16x16x64_i8 v[106:109], v[134:137], v[206:209], v[106:109]
	v_mfma_i32_16x16x64_i8 v[106:109], v[142:145], v[212:215], v[106:109]
	v_mfma_i32_16x16x64_i8 v[130:133], v[142:145], v[202:205], v[130:133]
	v_mfma_i32_16x16x64_i8 v[130:133], v[134:137], v[198:201], v[130:133]
	s_setprio 0
	s_setprio 1
	v_mfma_i32_16x16x64_i8 v[114:117], v[190:193], v[198:201], v[114:117]
	v_mfma_i32_16x16x64_i8 v[114:117], v[194:197], v[202:205], v[114:117]
	v_mfma_i32_16x16x64_i8 v[98:101], v[194:197], v[212:215], v[98:101]
	v_mfma_i32_16x16x64_i8 v[98:101], v[190:193], v[206:209], v[98:101]
	v_mfma_i32_16x16x64_i8 v[82:85], v[190:193], v[216:219], v[82:85]
	v_mfma_i32_16x16x64_i8 v[82:85], v[194:197], v[220:223], v[82:85]
	v_mfma_i32_16x16x64_i8 v[66:69], v[194:197], v[228:231], v[66:69]
	v_mfma_i32_16x16x64_i8 v[66:69], v[190:193], v[224:227], v[66:69]
	v_mfma_i32_16x16x64_i8 v[70:73], v[182:185], v[224:227], v[70:73]
	v_mfma_i32_16x16x64_i8 v[70:73], v[186:189], v[228:231], v[70:73]
	v_mfma_i32_16x16x64_i8 v[86:89], v[186:189], v[220:223], v[86:89]
	v_mfma_i32_16x16x64_i8 v[86:89], v[182:185], v[216:219], v[86:89]
	v_mfma_i32_16x16x64_i8 v[102:105], v[182:185], v[206:209], v[102:105]
	v_mfma_i32_16x16x64_i8 v[102:105], v[186:189], v[212:215], v[102:105]
	v_mfma_i32_16x16x64_i8 v[118:121], v[186:189], v[202:205], v[118:121]
	v_mfma_i32_16x16x64_i8 v[118:121], v[182:185], v[198:201], v[118:121]
	s_setprio 0
	s_barrier
	s_add_i32 s51, s28, s12
	v_lshl_add_u64 v[166:167], s[64:65], 0, v[148:149]
	s_mov_b32 m0, s51
	ds_read_b128 v[198:201], v171 offset:16384
	ds_read_b128 v[202:205], v171 offset:17408
	ds_read_b128 v[206:209], v171 offset:18432
	ds_read_b128 v[212:215], v171 offset:19456
	ds_read_b128 v[216:219], v171 offset:20480
	ds_read_b128 v[220:223], v171 offset:21504
	ds_read_b128 v[224:227], v171 offset:22528
	ds_read_b128 v[228:231], v171 offset:23552
	global_load_lds_dwordx4 v[166:167], off
	s_add_i32 m0, s51, 0x2000
	s_add_u32 s68, s64, 0x80000
	v_lshl_add_u64 v[176:177], s[64:65], 0, v[152:153]
	s_addc_u32 s69, s65, 0
	s_add_i32 s51, s29, s12
	global_load_lds_dwordx4 v[176:177], off
	v_lshl_add_u64 v[232:233], s[68:69], 0, v[148:149]
	s_mov_b32 m0, s51
	v_lshl_add_u64 v[234:235], s[66:67], 0, v[150:151]
	global_load_lds_dwordx4 v[232:233], off
	v_lshl_add_u64 v[232:233], s[68:69], 0, v[152:153]
	s_add_i32 m0, s51, 0x2000
	s_nop 0
	global_load_lds_dwordx4 v[232:233], off
	v_lshl_add_u64 v[232:233], s[66:67], 0, v[146:147]
	s_mov_b32 m0, s18
	s_nop 0
	global_load_lds_dwordx4 v[232:233], off
	s_mov_b32 m0, s19
	s_nop 0
	global_load_lds_dwordx4 v[234:235], off
	s_waitcnt vmcnt(8)
	s_waitcnt lgkmcnt(0)
	s_barrier
; #define PG8_STAGE(bufoff, gbase, voff) do { _Pragma("unroll") for (int _i = 0; _i < 2; ++_i) \
;         __builtin_amdgcn_global_load_lds((const unsigned*)((const char*)(gbase) + (voff)[_i]), (PG8_LAS unsigned*)(lds + (bufoff) + ldsw + _i * 8192), 16, 0, 0); } while (0)
; #define PG8_LDA(dst, b, h) do { _Pragma("unroll") for (int m = 0; m < 4; ++m) _Pragma("unroll") for (int k = 0; k < 2; ++k) dst[m][k] = *(const PG8_LAS bf16x8*)(lds + PG8_SA(b, h) + aoff + m * 2048 + k * 1024); } while (0)
; #define PG8_LDB(dst, b, h) do { _Pragma("unroll") for (int n = 0; n < 2; ++n) _Pragma("unroll") for (int k = 0; k < 2; ++k) dst[n][k] = *(const PG8_LAS bf16x8*)(lds + PG8_SB(b, h) + boff + n * 2048 + k * 1024); } while (0)
; #define PG8_MMA(ai, bj, At, Bt) do { __builtin_amdgcn_s_setprio(1); _Pragma("unroll") for (int m = 0; m < 4; ++m) _Pragma("unroll") for (int n = 0; n < 2; ++n) _Pragma("unroll") for (int k = 0; k < 2; ++k) \
;         acc[ai][bj][m][n] = mma16(Bt[n][k], At[m][k], acc[ai][bj][m][n]); __builtin_amdgcn_s_setprio(0); } while (0)
; #define PG8_WAIT_V(n) asm volatile("s_waitcnt vmcnt(" #n ")" ::: "memory")
; #define PG8_WAIT_L(n) asm volatile("s_waitcnt lgkmcnt(" #n ")" ::: "memory")
; #define PG8_BAR __builtin_amdgcn_s_barrier()
; #define PG8_SCHED __builtin_amdgcn_sched_barrier(0)
; template <class Epi, class Sched, bool ALIGN_EPI = false, bool SP2 = false>
; __device__ __forceinline__ void gemm_phase(PG8_LAS unsigned char* lds, const Gemm g, const Sched& S, const Epi& E) {
;     ...
;             PG8_WAIT_V(8); PG8_WAIT_L(0); PG8_BAR; PG8_MMA(1, 0, At, B0); PG8_MMA(1, 1, At, B1); PG8_BAR; PG8_SCHED;
;             PG8_LDB(B0, 1, 0); PG8_LDB(B1, 1, 1); PG8_SCHED; PG8_LDA(At, 1, 0); PG8_STAGE(PG8_SA(0, 1), a2 + hstepA, voffA);
;             PG8_WAIT_V(8); PG8_WAIT_L(0); PG8_BAR; PG8_MMA(0, 0, At, B0); PG8_MMA(0, 1, At, B1); PG8_BAR; PG8_SCHED;
;             PG8_LDA(At, 1, 1); PG8_STAGE(PG8_SB(1, 0), b3, voffB); PG8_STAGE(PG8_SB(1, 1), b3 + hstepB, voffB); PG8_STAGE(PG8_SA(1, 0), a3, voffA);
	s_setprio 1
	s_waitcnt lgkmcnt(0)
	v_mfma_i32_16x16x64_i8 v[62:65], v[122:125], v[198:201], v[62:65]
	v_mfma_i32_16x16x64_i8 v[62:65], v[126:129], v[202:205], v[62:65]
	v_mfma_i32_16x16x64_i8 v[46:49], v[126:129], v[212:215], v[46:49]
	v_mfma_i32_16x16x64_i8 v[46:49], v[122:125], v[206:209], v[46:49]
	v_mfma_i32_16x16x64_i8 v[30:33], v[122:125], v[216:219], v[30:33]
	v_mfma_i32_16x16x64_i8 v[30:33], v[126:129], v[220:223], v[30:33]
	v_mfma_i32_16x16x64_i8 v[14:17], v[126:129], v[228:231], v[14:17]
	v_mfma_i32_16x16x64_i8 v[14:17], v[122:125], v[224:227], v[14:17]
	v_mfma_i32_16x16x64_i8 v[10:13], v[134:137], v[224:227], v[10:13]
	v_mfma_i32_16x16x64_i8 v[10:13], v[142:145], v[228:231], v[10:13]
	v_mfma_i32_16x16x64_i8 v[26:29], v[142:145], v[220:223], v[26:29]
	v_mfma_i32_16x16x64_i8 v[26:29], v[134:137], v[216:219], v[26:29]
	v_mfma_i32_16x16x64_i8 v[42:45], v[134:137], v[206:209], v[42:45]
	v_mfma_i32_16x16x64_i8 v[42:45], v[142:145], v[212:215], v[42:45]
	v_mfma_i32_16x16x64_i8 v[58:61], v[142:145], v[202:205], v[58:61]
	v_mfma_i32_16x16x64_i8 v[58:61], v[134:137], v[198:201], v[58:61]
	s_setprio 0
	s_setprio 1
	v_mfma_i32_16x16x64_i8 v[50:53], v[190:193], v[198:201], v[50:53]
	v_mfma_i32_16x16x64_i8 v[50:53], v[194:197], v[202:205], v[50:53]
	v_mfma_i32_16x16x64_i8 v[34:37], v[194:197], v[212:215], v[34:37]
	v_mfma_i32_16x16x64_i8 v[34:37], v[190:193], v[206:209], v[34:37]
	v_mfma_i32_16x16x64_i8 v[18:21], v[190:193], v[216:219], v[18:21]
	v_mfma_i32_16x16x64_i8 v[18:21], v[194:197], v[220:223], v[18:21]
	v_mfma_i32_16x16x64_i8 v[2:5], v[194:197], v[228:231], v[2:5]
	v_mfma_i32_16x16x64_i8 v[2:5], v[190:193], v[224:227], v[2:5]
	v_mfma_i32_16x16x64_i8 v[6:9], v[182:185], v[224:227], v[6:9]
	v_mfma_i32_16x16x64_i8 v[6:9], v[186:189], v[228:231], v[6:9]
	v_mfma_i32_16x16x64_i8 v[22:25], v[186:189], v[220:223], v[22:25]
	v_mfma_i32_16x16x64_i8 v[22:25], v[182:185], v[216:219], v[22:25]
	v_mfma_i32_16x16x64_i8 v[38:41], v[182:185], v[206:209], v[38:41]
	v_mfma_i32_16x16x64_i8 v[38:41], v[186:189], v[212:215], v[38:41]
	v_mfma_i32_16x16x64_i8 v[54:57], v[186:189], v[202:205], v[54:57]
	v_mfma_i32_16x16x64_i8 v[54:57], v[182:185], v[198:201], v[54:57]
	s_setprio 0
	s_barrier
	s_add_i32 s51, 0, 0x18000
	s_add_i32 s63, 0, 0x1c000
	v_add_u32_e32 v142, s51, v173
	v_add_u32_e32 v172, s63, v173
	ds_read_b128 v[122:125], v142
	ds_read_b128 v[126:129], v142 offset:1024
	ds_read_b128 v[134:137], v142 offset:2048
	ds_read_b128 v[142:145], v142 offset:3072
	ds_read_b128 v[182:185], v172
	ds_read_b128 v[186:189], v172 offset:1024
	ds_read_b128 v[190:193], v172 offset:2048
	ds_read_b128 v[194:197], v172 offset:3072
	s_add_u32 s66, s66, 0x80000
	s_addc_u32 s67, s67, 0
	s_mov_b32 m0, s20
	v_lshl_add_u64 v[236:237], s[66:67], 0, v[146:147]
	ds_read_b128 v[198:201], v171 offset:32768
	ds_read_b128 v[202:205], v171 offset:33792
	ds_read_b128 v[206:209], v171 offset:34816
	ds_read_b128 v[212:215], v171 offset:35840
	ds_read_b128 v[216:219], v171 offset:36864
	ds_read_b128 v[220:223], v171 offset:37888
	ds_read_b128 v[224:227], v171 offset:38912
	ds_read_b128 v[228:231], v171 offset:39936
	global_load_lds_dwordx4 v[236:237], off
	v_lshl_add_u64 v[236:237], s[66:67], 0, v[150:151]
	s_mov_b32 m0, s21
	s_nop 0
	global_load_lds_dwordx4 v[236:237], off
	s_waitcnt vmcnt(8)
	s_waitcnt lgkmcnt(0)
	s_barrier
	s_setprio 1
	s_waitcnt lgkmcnt(0)
	v_mfma_i32_16x16x64_i8 v[138:141], v[122:125], v[198:201], v[138:141]
	v_mfma_i32_16x16x64_i8 v[138:141], v[126:129], v[202:205], v[138:141]
	v_mfma_i32_16x16x64_i8 v[110:113], v[126:129], v[212:215], v[110:113]
	v_mfma_i32_16x16x64_i8 v[110:113], v[122:125], v[206:209], v[110:113]
	v_mfma_i32_16x16x64_i8 v[94:97], v[122:125], v[216:219], v[94:97]
	v_mfma_i32_16x16x64_i8 v[94:97], v[126:129], v[220:223], v[94:97]
	v_mfma_i32_16x16x64_i8 v[78:81], v[126:129], v[228:231], v[78:81]
	v_mfma_i32_16x16x64_i8 v[78:81], v[122:125], v[224:227], v[78:81]
	v_mfma_i32_16x16x64_i8 v[74:77], v[134:137], v[224:227], v[74:77]
	v_mfma_i32_16x16x64_i8 v[74:77], v[142:145], v[228:231], v[74:77]
	v_mfma_i32_16x16x64_i8 v[90:93], v[142:145], v[220:223], v[90:93]
	v_mfma_i32_16x16x64_i8 v[90:93], v[134:137], v[216:219], v[90:93]
	v_mfma_i32_16x16x64_i8 v[106:109], v[134:137], v[206:209], v[106:109]
	v_mfma_i32_16x16x64_i8 v[106:109], v[142:145], v[212:215], v[106:109]
	v_mfma_i32_16x16x64_i8 v[130:133], v[142:145], v[202:205], v[130:133]
	v_mfma_i32_16x16x64_i8 v[130:133], v[134:137], v[198:201], v[130:133]
	s_setprio 0
	s_setprio 1
	v_mfma_i32_16x16x64_i8 v[114:117], v[190:193], v[198:201], v[114:117]
	v_mfma_i32_16x16x64_i8 v[114:117], v[194:197], v[202:205], v[114:117]
	v_mfma_i32_16x16x64_i8 v[98:101], v[194:197], v[212:215], v[98:101]
	v_mfma_i32_16x16x64_i8 v[98:101], v[190:193], v[206:209], v[98:101]
	v_mfma_i32_16x16x64_i8 v[82:85], v[190:193], v[216:219], v[82:85]
	v_mfma_i32_16x16x64_i8 v[82:85], v[194:197], v[220:223], v[82:85]
	v_mfma_i32_16x16x64_i8 v[66:69], v[194:197], v[228:231], v[66:69]
	v_mfma_i32_16x16x64_i8 v[66:69], v[190:193], v[224:227], v[66:69]
	v_mfma_i32_16x16x64_i8 v[70:73], v[182:185], v[224:227], v[70:73]
	v_mfma_i32_16x16x64_i8 v[70:73], v[186:189], v[228:231], v[70:73]
	v_mfma_i32_16x16x64_i8 v[86:89], v[186:189], v[220:223], v[86:89]
	v_mfma_i32_16x16x64_i8 v[86:89], v[182:185], v[216:219], v[86:89]
	v_mfma_i32_16x16x64_i8 v[102:105], v[182:185], v[206:209], v[102:105]
	v_mfma_i32_16x16x64_i8 v[102:105], v[186:189], v[212:215], v[102:105]
	v_mfma_i32_16x16x64_i8 v[118:121], v[186:189], v[202:205], v[118:121]
	v_mfma_i32_16x16x64_i8 v[118:121], v[182:185], v[198:201], v[118:121]
	s_setprio 0
	s_barrier
; #define PG8_STAGE(bufoff, gbase, voff) do { _Pragma("unroll") for (int _i = 0; _i < 2; ++_i) \
;         __builtin_amdgcn_global_load_lds((const unsigned*)((const char*)(gbase) + (voff)[_i]), (PG8_LAS unsigned*)(lds + (bufoff) + ldsw + _i * 8192), 16, 0, 0); } while (0)
; #define PG8_LDA(dst, b, h) do { _Pragma("unroll") for (int m = 0; m < 4; ++m) _Pragma("unroll") for (int k = 0; k < 2; ++k) dst[m][k] = *(const PG8_LAS bf16x8*)(lds + PG8_SA(b, h) + aoff + m * 2048 + k * 1024); } while (0)
; #define PG8_MMA(ai, bj, At, Bt) do { __builtin_amdgcn_s_setprio(1); _Pragma("unroll") for (int m = 0; m < 4; ++m) _Pragma("unroll") for (int n = 0; n < 2; ++n) _Pragma("unroll") for (int k = 0; k < 2; ++k) \
;         acc[ai][bj][m][n] = mma16(Bt[n][k], At[m][k], acc[ai][bj][m][n]); __builtin_amdgcn_s_setprio(0); } while (0)
; #define PG8_WAIT_V(n) asm volatile("s_waitcnt vmcnt(" #n ")" ::: "memory")
; #define PG8_WAIT_L(n) asm volatile("s_waitcnt lgkmcnt(" #n ")" ::: "memory")
; #define PG8_BAR __builtin_amdgcn_s_barrier()
; #define PG8_SCHED __builtin_amdgcn_sched_barrier(0)
; template <class Epi, class Sched, bool ALIGN_EPI = false, bool SP2 = false>
; __device__ __forceinline__ void gemm_phase(PG8_LAS unsigned char* lds, const Gemm g, const Sched& S, const Epi& E) {
;     ...
;         for (int t = 0; t < nt; t += 2) {
;             const bool last = (t == nt - 2);
;             const char* a1 = cA + (size_t)(t + 1) * kstep;
;             const char* a2 = last ? nA : cA + (size_t)(t + 2) * kstep; const char* b2 = last ? nB : cB + (size_t)(t + 2) * kstep;
;             const char* a3 = a2 + kstep; const char* b3 = b2 + kstep;
;             if (last && has_next) S.a_ready(nxt);
;     ...
;             PG8_LDA(At, 1, 1); PG8_STAGE(PG8_SB(1, 0), b3, voffB); PG8_STAGE(PG8_SB(1, 1), b3 + hstepB, voffB); PG8_STAGE(PG8_SA(1, 0), a3, voffA);
;             PG8_WAIT_V(8); PG8_WAIT_L(0); PG8_BAR; PG8_MMA(1, 0, At, B0); PG8_MMA(1, 1, At, B1); PG8_BAR; PG8_SCHED;
	s_add_i32 s51, s51, s12
	v_lshl_add_u64 v[166:167], v[166:167], 0, s[42:43]
	s_mov_b32 m0, s51
	ds_read_b128 v[198:201], v171 offset:49152
	ds_read_b128 v[202:205], v171 offset:50176
	ds_read_b128 v[206:209], v171 offset:51200
	ds_read_b128 v[212:215], v171 offset:52224
	ds_read_b128 v[216:219], v171 offset:53248
	ds_read_b128 v[220:223], v171 offset:54272
	ds_read_b128 v[224:227], v171 offset:55296
	ds_read_b128 v[228:231], v171 offset:56320
	global_load_lds_dwordx4 v[166:167], off
	s_add_i32 m0, s51, 0x2000
	s_add_u32 s64, s64, 0x80080
	v_lshl_add_u64 v[166:167], v[176:177], 0, s[42:43]
	s_addc_u32 s65, s65, 0
	s_add_i32 s51, s63, s12
	global_load_lds_dwordx4 v[166:167], off
	v_lshl_add_u64 v[166:167], s[64:65], 0, v[148:149]
	s_mov_b32 m0, s51
	s_nop 0
	global_load_lds_dwordx4 v[166:167], off
	v_lshl_add_u64 v[166:167], s[64:65], 0, v[152:153]
	s_add_i32 m0, s51, 0x2000
	s_nop 0
	global_load_lds_dwordx4 v[166:167], off
	v_lshl_add_u64 v[166:167], v[232:233], 0, s[42:43]
	s_mov_b32 m0, s24
	s_nop 0
	global_load_lds_dwordx4 v[166:167], off
	v_lshl_add_u64 v[166:167], v[234:235], 0, s[42:43]
	s_mov_b32 m0, s25
	s_nop 0
	global_load_lds_dwordx4 v[166:167], off
	s_waitcnt vmcnt(8)
	s_waitcnt lgkmcnt(0)
	s_barrier
	s_setprio 1
	s_waitcnt lgkmcnt(0)
	v_mfma_i32_16x16x64_i8 v[62:65], v[122:125], v[198:201], v[62:65]
	v_mfma_i32_16x16x64_i8 v[62:65], v[126:129], v[202:205], v[62:65]
	v_mfma_i32_16x16x64_i8 v[46:49], v[126:129], v[212:215], v[46:49]
	v_mfma_i32_16x16x64_i8 v[46:49], v[122:125], v[206:209], v[46:49]
	v_mfma_i32_16x16x64_i8 v[30:33], v[122:125], v[216:219], v[30:33]
	v_mfma_i32_16x16x64_i8 v[30:33], v[126:129], v[220:223], v[30:33]
	v_mfma_i32_16x16x64_i8 v[14:17], v[126:129], v[228:231], v[14:17]
	v_mfma_i32_16x16x64_i8 v[14:17], v[122:125], v[224:227], v[14:17]
	v_mfma_i32_16x16x64_i8 v[10:13], v[134:137], v[224:227], v[10:13]
	v_mfma_i32_16x16x64_i8 v[10:13], v[142:145], v[228:231], v[10:13]
	v_mfma_i32_16x16x64_i8 v[26:29], v[142:145], v[220:223], v[26:29]
	v_mfma_i32_16x16x64_i8 v[26:29], v[134:137], v[216:219], v[26:29]
	v_mfma_i32_16x16x64_i8 v[42:45], v[134:137], v[206:209], v[42:45]
	v_mfma_i32_16x16x64_i8 v[42:45], v[142:145], v[212:215], v[42:45]
	v_mfma_i32_16x16x64_i8 v[58:61], v[142:145], v[202:205], v[58:61]
	v_mfma_i32_16x16x64_i8 v[58:61], v[134:137], v[198:201], v[58:61]
	s_setprio 0
	s_setprio 1
	v_mfma_i32_16x16x64_i8 v[50:53], v[190:193], v[198:201], v[50:53]
	v_mfma_i32_16x16x64_i8 v[50:53], v[194:197], v[202:205], v[50:53]
	v_mfma_i32_16x16x64_i8 v[34:37], v[194:197], v[212:215], v[34:37]
	v_mfma_i32_16x16x64_i8 v[34:37], v[190:193], v[206:209], v[34:37]
	v_mfma_i32_16x16x64_i8 v[18:21], v[190:193], v[216:219], v[18:21]
	v_mfma_i32_16x16x64_i8 v[18:21], v[194:197], v[220:223], v[18:21]
	v_mfma_i32_16x16x64_i8 v[2:5], v[194:197], v[228:231], v[2:5]
	v_mfma_i32_16x16x64_i8 v[2:5], v[190:193], v[224:227], v[2:5]
	v_mfma_i32_16x16x64_i8 v[6:9], v[182:185], v[224:227], v[6:9]
	v_mfma_i32_16x16x64_i8 v[6:9], v[186:189], v[228:231], v[6:9]
	v_mfma_i32_16x16x64_i8 v[22:25], v[186:189], v[220:223], v[22:25]
	v_mfma_i32_16x16x64_i8 v[22:25], v[182:185], v[216:219], v[22:25]
	v_mfma_i32_16x16x64_i8 v[38:41], v[182:185], v[206:209], v[38:41]
	v_mfma_i32_16x16x64_i8 v[38:41], v[186:189], v[212:215], v[38:41]
	v_mfma_i32_16x16x64_i8 v[54:57], v[186:189], v[202:205], v[54:57]
	v_mfma_i32_16x16x64_i8 v[54:57], v[182:185], v[198:201], v[54:57]
	s_setprio 0
	s_barrier
	s_add_i32 s50, s50, 2
	s_add_u32 s0, s0, 0x100
	s_addc_u32 s1, s1, 0
	s_add_u32 s47, s47, 0x100
	s_addc_u32 s49, s49, 0
	s_cmp_gt_u32 s50, 29
	s_cbranch_scc0 .LBB0_275
	s_and_b64 vcc, exec, s[44:45]
	s_cbranch_vccz .LBB0_278
	s_barrier

; #define PG8_STAGE(bufoff, gbase, voff) do { _Pragma("unroll") for (int _i = 0; _i < 2; ++_i) \
;         __builtin_amdgcn_global_load_lds((const unsigned*)((const char*)(gbase) + (voff)[_i]), (PG8_LAS unsigned*)(lds + (bufoff) + ldsw + _i * 8192), 16, 0, 0); } while (0)
; #define PG8_LDA(dst, b, h) do { _Pragma("unroll") for (int m = 0; m < 4; ++m) _Pragma("unroll") for (int k = 0; k < 2; ++k) dst[m][k] = *(const PG8_LAS bf16x8*)(lds + PG8_SA(b, h) + aoff + m * 2048 + k * 1024); } while (0)
; #define PG8_LDB(dst, b, h) do { _Pragma("unroll") for (int n = 0; n < 2; ++n) _Pragma("unroll") for (int k = 0; k < 2; ++k) dst[n][k] = *(const PG8_LAS bf16x8*)(lds + PG8_SB(b, h) + boff + n * 2048 + k * 1024); } while (0)
; #define PG8_MMA(ai, bj, At, Bt) do { __builtin_amdgcn_s_setprio(1); _Pragma("unroll") for (int m = 0; m < 4; ++m) _Pragma("unroll") for (int n = 0; n < 2; ++n) _Pragma("unroll") for (int k = 0; k < 2; ++k) \
;         acc[ai][bj][m][n] = mma16(Bt[n][k], At[m][k], acc[ai][bj][m][n]); __builtin_amdgcn_s_setprio(0); } while (0)
; #define PG8_WAIT_V(n) asm volatile("s_waitcnt vmcnt(" #n ")" ::: "memory")
; #define PG8_WAIT_L(n) asm volatile("s_waitcnt lgkmcnt(" #n ")" ::: "memory")
; template <class Epi, class Sched, bool ALIGN_EPI = false, bool SP2 = false>
; __device__ __forceinline__ void gemm_phase(PG8_LAS unsigned char* lds, const Gemm g, const Sched& S, const Epi& E) {
;     ...
;         for (int t = 0; t < nt; t += 2) {
;             const bool last = (t == nt - 2);
;             const char* a1 = cA + (size_t)(t + 1) * kstep;
;             const char* a2 = last ? nA : cA + (size_t)(t + 2) * kstep; const char* b2 = last ? nB : cB + (size_t)(t + 2) * kstep;
;             const char* a3 = a2 + kstep; const char* b3 = b2 + kstep;
;             if (last && has_next) S.a_ready(nxt);
;             if constexpr (SP2) {
;             PG8_LDB(B0, 0, 0); PG8_LDB(B1, 0, 1); PG8_SCHED; PG8_LDA(At, 0, 0); PG8_STAGE(PG8_SA(1, 1), a1 + hstepA, voffA);
;             PG8_WAIT_V(8); PG8_WAIT_L(0); PG8_BAR; PG8_MMA(0, 0, At, B0); PG8_MMA(0, 1, At, B1); PG8_BAR; PG8_SCHED;
;             PG8_LDA(At, 0, 1); PG8_STAGE(PG8_SB(0, 0), b2, voffB); PG8_STAGE(PG8_SB(0, 1), b2 + hstepB, voffB); PG8_STAGE(PG8_SA(0, 0), a2, voffA);
;             PG8_WAIT_V(8); PG8_WAIT_L(0); PG8_BAR; PG8_MMA(1, 0, At, B0); PG8_MMA(1, 1, At, B1); PG8_BAR; PG8_SCHED;
.LBB0_389:
	ds_read_b128 v[154:157], v150
	ds_read_b128 v[158:161], v150 offset:1024
	ds_read_b128 v[162:165], v150 offset:2048
	ds_read_b128 v[166:169], v150 offset:3072
	ds_read_b128 v[170:173], v151
	ds_read_b128 v[174:177], v151 offset:1024
	ds_read_b128 v[182:185], v151 offset:2048
	ds_read_b128 v[186:189], v151 offset:3072
	s_add_u32 s33, s0, 0xfff00080
	s_addc_u32 s35, s1, -1
	s_cmp_eq_u32 s29, 12
	s_cselect_b32 s59, s49, s35
	s_cselect_b32 s58, s48, s33
	s_cselect_b32 s55, s25, s28
	s_cselect_b32 s54, s26, s27
	v_lshl_add_u64 v[146:147], s[0:1], 0, v[138:139]
	s_add_i32 m0, s12, 0xc000
	ds_read_b128 v[190:193], v152
	ds_read_b128 v[194:197], v152 offset:1024
	ds_read_b128 v[198:201], v152 offset:2048
	ds_read_b128 v[202:205], v152 offset:3072
	ds_read_b128 v[206:209], v152 offset:4096
	ds_read_b128 v[212:215], v152 offset:5120
	ds_read_b128 v[216:219], v152 offset:6144
	ds_read_b128 v[220:223], v152 offset:7168
	global_load_lds_dwordx4 v[146:147], off
	v_lshl_add_u64 v[146:147], s[0:1], 0, v[140:141]
	s_add_i32 m0, s12, 0xe000
	s_nop 0
	global_load_lds_dwordx4 v[146:147], off
	s_waitcnt vmcnt(8)
	s_waitcnt lgkmcnt(0)
	s_barrier
	s_setprio 1
	s_waitcnt lgkmcnt(0)
	v_mfma_f32_16x16x32_bf16 v[126:129], v[154:157], v[190:193], v[126:129]
	v_mfma_f32_16x16x32_bf16 v[126:129], v[158:161], v[194:197], v[126:129]
	v_mfma_f32_16x16x32_bf16 v[118:121], v[158:161], v[202:205], v[118:121]
	v_mfma_f32_16x16x32_bf16 v[118:121], v[154:157], v[198:201], v[118:121]
	v_mfma_f32_16x16x32_bf16 v[102:105], v[154:157], v[206:209], v[102:105]
	v_mfma_f32_16x16x32_bf16 v[102:105], v[158:161], v[212:215], v[102:105]
	v_mfma_f32_16x16x32_bf16 v[86:89], v[158:161], v[220:223], v[86:89]
	v_mfma_f32_16x16x32_bf16 v[86:89], v[154:157], v[216:219], v[86:89]
	v_mfma_f32_16x16x32_bf16 v[78:81], v[162:165], v[216:219], v[78:81]
	v_mfma_f32_16x16x32_bf16 v[78:81], v[166:169], v[220:223], v[78:81]
	v_mfma_f32_16x16x32_bf16 v[94:97], v[166:169], v[212:215], v[94:97]
	v_mfma_f32_16x16x32_bf16 v[94:97], v[162:165], v[206:209], v[94:97]
	v_mfma_f32_16x16x32_bf16 v[110:113], v[162:165], v[198:201], v[110:113]
	v_mfma_f32_16x16x32_bf16 v[110:113], v[166:169], v[202:205], v[110:113]
	v_mfma_f32_16x16x32_bf16 v[122:125], v[166:169], v[194:197], v[122:125]
	v_mfma_f32_16x16x32_bf16 v[122:125], v[162:165], v[190:193], v[122:125]
	s_setprio 0
	s_setprio 1
	v_mfma_f32_16x16x32_bf16 v[106:109], v[182:185], v[190:193], v[106:109]
	v_mfma_f32_16x16x32_bf16 v[106:109], v[186:189], v[194:197], v[106:109]
	v_mfma_f32_16x16x32_bf16 v[90:93], v[186:189], v[202:205], v[90:93]
	v_mfma_f32_16x16x32_bf16 v[90:93], v[182:185], v[198:201], v[90:93]
	v_mfma_f32_16x16x32_bf16 v[74:77], v[182:185], v[206:209], v[74:77]
	v_mfma_f32_16x16x32_bf16 v[74:77], v[186:189], v[212:215], v[74:77]
	v_mfma_f32_16x16x32_bf16 v[66:69], v[186:189], v[220:223], v[66:69]
	v_mfma_f32_16x16x32_bf16 v[66:69], v[182:185], v[216:219], v[66:69]
	v_mfma_f32_16x16x32_bf16 v[70:73], v[170:173], v[216:219], v[70:73]
	v_mfma_f32_16x16x32_bf16 v[70:73], v[174:177], v[220:223], v[70:73]
	v_mfma_f32_16x16x32_bf16 v[82:85], v[174:177], v[212:215], v[82:85]
	v_mfma_f32_16x16x32_bf16 v[82:85], v[170:173], v[206:209], v[82:85]
	v_mfma_f32_16x16x32_bf16 v[98:101], v[170:173], v[198:201], v[98:101]
	v_mfma_f32_16x16x32_bf16 v[98:101], v[174:177], v[202:205], v[98:101]
	v_mfma_f32_16x16x32_bf16 v[114:117], v[174:177], v[194:197], v[114:117]
	v_mfma_f32_16x16x32_bf16 v[114:117], v[170:173], v[190:193], v[114:117]
	s_setprio 0
	s_barrier
	s_add_i32 s33, s22, s7
	v_lshl_add_u64 v[146:147], s[54:55], 0, v[132:133]
	s_mov_b32 m0, s33
	ds_read_b128 v[190:193], v152 offset:16384
	ds_read_b128 v[194:197], v152 offset:17408
	ds_read_b128 v[198:201], v152 offset:18432
	ds_read_b128 v[202:205], v152 offset:19456
	ds_read_b128 v[206:209], v152 offset:20480
	ds_read_b128 v[212:215], v152 offset:21504
	ds_read_b128 v[216:219], v152 offset:22528
	ds_read_b128 v[220:223], v152 offset:23552
	global_load_lds_dwordx4 v[146:147], off
	s_add_i32 m0, s33, 0x2000
	s_add_u32 s36, s54, 0x40000
	v_lshl_add_u64 v[224:225], s[54:55], 0, v[136:137]
	s_addc_u32 s37, s55, 0
	s_add_i32 s33, s23, s7
	global_load_lds_dwordx4 v[224:225], off
	v_lshl_add_u64 v[226:227], s[36:37], 0, v[132:133]
	s_mov_b32 m0, s33
	v_lshl_add_u64 v[228:229], s[58:59], 0, v[134:135]
	global_load_lds_dwordx4 v[226:227], off
	v_lshl_add_u64 v[226:227], s[36:37], 0, v[136:137]
	s_add_i32 m0, s33, 0x2000
	s_nop 0
	global_load_lds_dwordx4 v[226:227], off
	v_lshl_add_u64 v[226:227], s[58:59], 0, v[130:131]
	s_mov_b32 m0, s12
	s_nop 0
	global_load_lds_dwordx4 v[226:227], off
	s_mov_b32 m0, s13
	s_nop 0
	global_load_lds_dwordx4 v[228:229], off
	s_waitcnt vmcnt(8)
	s_waitcnt lgkmcnt(0)
	s_barrier
; #define PG8_STAGE(bufoff, gbase, voff) do { _Pragma("unroll") for (int _i = 0; _i < 2; ++_i) \
;         __builtin_amdgcn_global_load_lds((const unsigned*)((const char*)(gbase) + (voff)[_i]), (PG8_LAS unsigned*)(lds + (bufoff) + ldsw + _i * 8192), 16, 0, 0); } while (0)
; #define PG8_LDA(dst, b, h) do { _Pragma("unroll") for (int m = 0; m < 4; ++m) _Pragma("unroll") for (int k = 0; k < 2; ++k) dst[m][k] = *(const PG8_LAS bf16x8*)(lds + PG8_SA(b, h) + aoff + m * 2048 + k * 1024); } while (0)
; #define PG8_LDB(dst, b, h) do { _Pragma("unroll") for (int n = 0; n < 2; ++n) _Pragma("unroll") for (int k = 0; k < 2; ++k) dst[n][k] = *(const PG8_LAS bf16x8*)(lds + PG8_SB(b, h) + boff + n * 2048 + k * 1024); } while (0)
; #define PG8_MMA(ai, bj, At, Bt) do { __builtin_amdgcn_s_setprio(1); _Pragma("unroll") for (int m = 0; m < 4; ++m) _Pragma("unroll") for (int n = 0; n < 2; ++n) _Pragma("unroll") for (int k = 0; k < 2; ++k) \
;         acc[ai][bj][m][n] = mma16(Bt[n][k], At[m][k], acc[ai][bj][m][n]); __builtin_amdgcn_s_setprio(0); } while (0)
; #define PG8_WAIT_V(n) asm volatile("s_waitcnt vmcnt(" #n ")" ::: "memory")
; #define PG8_WAIT_L(n) asm volatile("s_waitcnt lgkmcnt(" #n ")" ::: "memory")
; #define PG8_BAR __builtin_amdgcn_s_barrier()
; #define PG8_SCHED __builtin_amdgcn_sched_barrier(0)
; template <class Epi, class Sched, bool ALIGN_EPI = false, bool SP2 = false>
; __device__ __forceinline__ void gemm_phase(PG8_LAS unsigned char* lds, const Gemm g, const Sched& S, const Epi& E) {
;     ...
;             PG8_WAIT_V(8); PG8_WAIT_L(0); PG8_BAR; PG8_MMA(1, 0, At, B0); PG8_MMA(1, 1, At, B1); PG8_BAR; PG8_SCHED;
;             PG8_LDB(B0, 1, 0); PG8_LDB(B1, 1, 1); PG8_SCHED; PG8_LDA(At, 1, 0); PG8_STAGE(PG8_SA(0, 1), a2 + hstepA, voffA);
;             PG8_WAIT_V(8); PG8_WAIT_L(0); PG8_BAR; PG8_MMA(0, 0, At, B0); PG8_MMA(0, 1, At, B1); PG8_BAR; PG8_SCHED;
	s_setprio 1
	s_waitcnt lgkmcnt(0)
	v_mfma_f32_16x16x32_bf16 v[62:65], v[154:157], v[190:193], v[62:65]
	v_mfma_f32_16x16x32_bf16 v[62:65], v[158:161], v[194:197], v[62:65]
	v_mfma_f32_16x16x32_bf16 v[54:57], v[158:161], v[202:205], v[54:57]
	v_mfma_f32_16x16x32_bf16 v[54:57], v[154:157], v[198:201], v[54:57]
	v_mfma_f32_16x16x32_bf16 v[38:41], v[154:157], v[206:209], v[38:41]
	v_mfma_f32_16x16x32_bf16 v[38:41], v[158:161], v[212:215], v[38:41]
	v_mfma_f32_16x16x32_bf16 v[22:25], v[158:161], v[220:223], v[22:25]
	v_mfma_f32_16x16x32_bf16 v[22:25], v[154:157], v[216:219], v[22:25]
	v_mfma_f32_16x16x32_bf16 v[14:17], v[162:165], v[216:219], v[14:17]
	v_mfma_f32_16x16x32_bf16 v[14:17], v[166:169], v[220:223], v[14:17]
	v_mfma_f32_16x16x32_bf16 v[30:33], v[166:169], v[212:215], v[30:33]
	v_mfma_f32_16x16x32_bf16 v[30:33], v[162:165], v[206:209], v[30:33]
	v_mfma_f32_16x16x32_bf16 v[46:49], v[162:165], v[198:201], v[46:49]
	v_mfma_f32_16x16x32_bf16 v[46:49], v[166:169], v[202:205], v[46:49]
	v_mfma_f32_16x16x32_bf16 v[58:61], v[166:169], v[194:197], v[58:61]
	v_mfma_f32_16x16x32_bf16 v[58:61], v[162:165], v[190:193], v[58:61]
	s_setprio 0
	s_setprio 1
	v_mfma_f32_16x16x32_bf16 v[42:45], v[182:185], v[190:193], v[42:45]
	v_mfma_f32_16x16x32_bf16 v[42:45], v[186:189], v[194:197], v[42:45]
	v_mfma_f32_16x16x32_bf16 v[26:29], v[186:189], v[202:205], v[26:29]
	v_mfma_f32_16x16x32_bf16 v[26:29], v[182:185], v[198:201], v[26:29]
	v_mfma_f32_16x16x32_bf16 v[10:13], v[182:185], v[206:209], v[10:13]
	v_mfma_f32_16x16x32_bf16 v[10:13], v[186:189], v[212:215], v[10:13]
	v_mfma_f32_16x16x32_bf16 v[2:5], v[186:189], v[220:223], v[2:5]
	v_mfma_f32_16x16x32_bf16 v[2:5], v[182:185], v[216:219], v[2:5]
	v_mfma_f32_16x16x32_bf16 v[6:9], v[170:173], v[216:219], v[6:9]
	v_mfma_f32_16x16x32_bf16 v[6:9], v[174:177], v[220:223], v[6:9]
	v_mfma_f32_16x16x32_bf16 v[18:21], v[174:177], v[212:215], v[18:21]
	v_mfma_f32_16x16x32_bf16 v[18:21], v[170:173], v[206:209], v[18:21]
	v_mfma_f32_16x16x32_bf16 v[34:37], v[170:173], v[198:201], v[34:37]
	v_mfma_f32_16x16x32_bf16 v[34:37], v[174:177], v[202:205], v[34:37]
	v_mfma_f32_16x16x32_bf16 v[50:53], v[174:177], v[194:197], v[50:53]
	v_mfma_f32_16x16x32_bf16 v[50:53], v[170:173], v[190:193], v[50:53]
	s_setprio 0
	s_barrier
	s_add_i32 s33, 0, 0x18000
	v_add_u32_e32 v153, s33, v148
	s_add_i32 s35, 0, 0x1c000
	ds_read_b128 v[154:157], v153
	ds_read_b128 v[158:161], v153 offset:1024
	ds_read_b128 v[162:165], v153 offset:2048
	ds_read_b128 v[166:169], v153 offset:3072
	v_add_u32_e32 v153, s35, v148
	ds_read_b128 v[170:173], v153
	ds_read_b128 v[174:177], v153 offset:1024
	ds_read_b128 v[182:185], v153 offset:2048
	ds_read_b128 v[186:189], v153 offset:3072
	s_add_u32 s36, s58, 0x100000
	s_addc_u32 s37, s59, 0
	s_mov_b32 m0, s16
	v_lshl_add_u64 v[230:231], s[36:37], 0, v[130:131]
	ds_read_b128 v[190:193], v152 offset:32768
	ds_read_b128 v[194:197], v152 offset:33792
	ds_read_b128 v[198:201], v152 offset:34816
	ds_read_b128 v[202:205], v152 offset:35840
	ds_read_b128 v[206:209], v152 offset:36864
	ds_read_b128 v[212:215], v152 offset:37888
	ds_read_b128 v[216:219], v152 offset:38912
	ds_read_b128 v[220:223], v152 offset:39936
	global_load_lds_dwordx4 v[230:231], off
	v_lshl_add_u64 v[230:231], s[36:37], 0, v[134:135]
	s_mov_b32 m0, s17
	s_nop 0
	global_load_lds_dwordx4 v[230:231], off
	s_waitcnt vmcnt(8)
	s_waitcnt lgkmcnt(0)
	s_barrier
	s_setprio 1
	s_waitcnt lgkmcnt(0)
	v_mfma_f32_16x16x32_bf16 v[126:129], v[154:157], v[190:193], v[126:129]
	v_mfma_f32_16x16x32_bf16 v[126:129], v[158:161], v[194:197], v[126:129]
	v_mfma_f32_16x16x32_bf16 v[118:121], v[158:161], v[202:205], v[118:121]
	v_mfma_f32_16x16x32_bf16 v[118:121], v[154:157], v[198:201], v[118:121]
	v_mfma_f32_16x16x32_bf16 v[102:105], v[154:157], v[206:209], v[102:105]
	v_mfma_f32_16x16x32_bf16 v[102:105], v[158:161], v[212:215], v[102:105]
	v_mfma_f32_16x16x32_bf16 v[86:89], v[158:161], v[220:223], v[86:89]
	v_mfma_f32_16x16x32_bf16 v[86:89], v[154:157], v[216:219], v[86:89]
	v_mfma_f32_16x16x32_bf16 v[78:81], v[162:165], v[216:219], v[78:81]
	v_mfma_f32_16x16x32_bf16 v[78:81], v[166:169], v[220:223], v[78:81]
	v_mfma_f32_16x16x32_bf16 v[94:97], v[166:169], v[212:215], v[94:97]
	v_mfma_f32_16x16x32_bf16 v[94:97], v[162:165], v[206:209], v[94:97]
	v_mfma_f32_16x16x32_bf16 v[110:113], v[162:165], v[198:201], v[110:113]
	v_mfma_f32_16x16x32_bf16 v[110:113], v[166:169], v[202:205], v[110:113]
	v_mfma_f32_16x16x32_bf16 v[122:125], v[166:169], v[194:197], v[122:125]
	v_mfma_f32_16x16x32_bf16 v[122:125], v[162:165], v[190:193], v[122:125]
	s_setprio 0
	s_setprio 1
	v_mfma_f32_16x16x32_bf16 v[106:109], v[182:185], v[190:193], v[106:109]
	v_mfma_f32_16x16x32_bf16 v[106:109], v[186:189], v[194:197], v[106:109]
	v_mfma_f32_16x16x32_bf16 v[90:93], v[186:189], v[202:205], v[90:93]
	v_mfma_f32_16x16x32_bf16 v[90:93], v[182:185], v[198:201], v[90:93]
	v_mfma_f32_16x16x32_bf16 v[74:77], v[182:185], v[206:209], v[74:77]
	v_mfma_f32_16x16x32_bf16 v[74:77], v[186:189], v[212:215], v[74:77]
	v_mfma_f32_16x16x32_bf16 v[66:69], v[186:189], v[220:223], v[66:69]
	v_mfma_f32_16x16x32_bf16 v[66:69], v[182:185], v[216:219], v[66:69]
	v_mfma_f32_16x16x32_bf16 v[70:73], v[170:173], v[216:219], v[70:73]
	v_mfma_f32_16x16x32_bf16 v[70:73], v[174:177], v[220:223], v[70:73]
	v_mfma_f32_16x16x32_bf16 v[82:85], v[174:177], v[212:215], v[82:85]
	v_mfma_f32_16x16x32_bf16 v[82:85], v[170:173], v[206:209], v[82:85]
	v_mfma_f32_16x16x32_bf16 v[98:101], v[170:173], v[198:201], v[98:101]
	v_mfma_f32_16x16x32_bf16 v[98:101], v[174:177], v[202:205], v[98:101]
	v_mfma_f32_16x16x32_bf16 v[114:117], v[174:177], v[194:197], v[114:117]
	v_mfma_f32_16x16x32_bf16 v[114:117], v[170:173], v[190:193], v[114:117]
	s_setprio 0
	s_barrier
; #define PG8_STAGE(bufoff, gbase, voff) do { _Pragma("unroll") for (int _i = 0; _i < 2; ++_i) \
;         __builtin_amdgcn_global_load_lds((const unsigned*)((const char*)(gbase) + (voff)[_i]), (PG8_LAS unsigned*)(lds + (bufoff) + ldsw + _i * 8192), 16, 0, 0); } while (0)
; #define PG8_LDA(dst, b, h) do { _Pragma("unroll") for (int m = 0; m < 4; ++m) _Pragma("unroll") for (int k = 0; k < 2; ++k) dst[m][k] = *(const PG8_LAS bf16x8*)(lds + PG8_SA(b, h) + aoff + m * 2048 + k * 1024); } while (0)
; #define PG8_MMA(ai, bj, At, Bt) do { __builtin_amdgcn_s_setprio(1); _Pragma("unroll") for (int m = 0; m < 4; ++m) _Pragma("unroll") for (int n = 0; n < 2; ++n) _Pragma("unroll") for (int k = 0; k < 2; ++k) \
;         acc[ai][bj][m][n] = mma16(Bt[n][k], At[m][k], acc[ai][bj][m][n]); __builtin_amdgcn_s_setprio(0); } while (0)
; #define PG8_WAIT_V(n) asm volatile("s_waitcnt vmcnt(" #n ")" ::: "memory")
; #define PG8_WAIT_L(n) asm volatile("s_waitcnt lgkmcnt(" #n ")" ::: "memory")
; #define PG8_BAR __builtin_amdgcn_s_barrier()
; #define PG8_SCHED __builtin_amdgcn_sched_barrier(0)
; template <class Epi, class Sched, bool ALIGN_EPI = false, bool SP2 = false>
; __device__ __forceinline__ void gemm_phase(PG8_LAS unsigned char* lds, const Gemm g, const Sched& S, const Epi& E) {
;     ...
;             PG8_LDA(At, 1, 1); PG8_STAGE(PG8_SB(1, 0), b3, voffB); PG8_STAGE(PG8_SB(1, 1), b3 + hstepB, voffB); PG8_STAGE(PG8_SA(1, 0), a3, voffA);
;             PG8_WAIT_V(8); PG8_WAIT_L(0); PG8_BAR; PG8_MMA(1, 0, At, B0); PG8_MMA(1, 1, At, B1); PG8_BAR; PG8_SCHED;
;     ...
;         if constexpr (ALIGN_EPI) { if (wr == 0) PG8_BAR; }
	s_add_i32 s33, s33, s7
	v_lshl_add_u64 v[146:147], v[146:147], 0, s[38:39]
	s_mov_b32 m0, s33
	ds_read_b128 v[190:193], v152 offset:49152
	ds_read_b128 v[194:197], v152 offset:50176
	ds_read_b128 v[198:201], v152 offset:51200
	ds_read_b128 v[202:205], v152 offset:52224
	ds_read_b128 v[206:209], v152 offset:53248
	ds_read_b128 v[212:215], v152 offset:54272
	ds_read_b128 v[216:219], v152 offset:55296
	ds_read_b128 v[220:223], v152 offset:56320
	global_load_lds_dwordx4 v[146:147], off
	s_add_i32 m0, s33, 0x2000
	s_add_u32 s36, s54, 0x40080
	v_lshl_add_u64 v[146:147], v[224:225], 0, s[38:39]
	s_addc_u32 s37, s55, 0
	s_add_i32 s33, s35, s7
	global_load_lds_dwordx4 v[146:147], off
	v_lshl_add_u64 v[146:147], s[36:37], 0, v[132:133]
	s_mov_b32 m0, s33
	s_nop 0
	global_load_lds_dwordx4 v[146:147], off
	v_lshl_add_u64 v[146:147], s[36:37], 0, v[136:137]
	s_add_i32 m0, s33, 0x2000
	s_nop 0
	global_load_lds_dwordx4 v[146:147], off
	v_lshl_add_u64 v[146:147], v[226:227], 0, s[38:39]
	s_mov_b32 m0, s19
	s_nop 0
	global_load_lds_dwordx4 v[146:147], off
	v_lshl_add_u64 v[146:147], v[228:229], 0, s[38:39]
	s_mov_b32 m0, s20
	s_nop 0
	global_load_lds_dwordx4 v[146:147], off
	s_waitcnt vmcnt(8)
	s_waitcnt lgkmcnt(0)
	s_barrier
	s_setprio 1
	s_waitcnt lgkmcnt(0)
	v_mfma_f32_16x16x32_bf16 v[62:65], v[154:157], v[190:193], v[62:65]
	v_mfma_f32_16x16x32_bf16 v[62:65], v[158:161], v[194:197], v[62:65]
	v_mfma_f32_16x16x32_bf16 v[54:57], v[158:161], v[202:205], v[54:57]
	v_mfma_f32_16x16x32_bf16 v[54:57], v[154:157], v[198:201], v[54:57]
	v_mfma_f32_16x16x32_bf16 v[38:41], v[154:157], v[206:209], v[38:41]
	v_mfma_f32_16x16x32_bf16 v[38:41], v[158:161], v[212:215], v[38:41]
	v_mfma_f32_16x16x32_bf16 v[22:25], v[158:161], v[220:223], v[22:25]
	v_mfma_f32_16x16x32_bf16 v[22:25], v[154:157], v[216:219], v[22:25]
	v_mfma_f32_16x16x32_bf16 v[14:17], v[162:165], v[216:219], v[14:17]
	v_mfma_f32_16x16x32_bf16 v[14:17], v[166:169], v[220:223], v[14:17]
	v_mfma_f32_16x16x32_bf16 v[30:33], v[166:169], v[212:215], v[30:33]
	v_mfma_f32_16x16x32_bf16 v[30:33], v[162:165], v[206:209], v[30:33]
	v_mfma_f32_16x16x32_bf16 v[46:49], v[162:165], v[198:201], v[46:49]
	v_mfma_f32_16x16x32_bf16 v[46:49], v[166:169], v[202:205], v[46:49]
	v_mfma_f32_16x16x32_bf16 v[58:61], v[166:169], v[194:197], v[58:61]
	v_mfma_f32_16x16x32_bf16 v[58:61], v[162:165], v[190:193], v[58:61]
	s_setprio 0
	s_setprio 1
	v_mfma_f32_16x16x32_bf16 v[42:45], v[182:185], v[190:193], v[42:45]
	v_mfma_f32_16x16x32_bf16 v[42:45], v[186:189], v[194:197], v[42:45]
	v_mfma_f32_16x16x32_bf16 v[26:29], v[186:189], v[202:205], v[26:29]
	v_mfma_f32_16x16x32_bf16 v[26:29], v[182:185], v[198:201], v[26:29]
	v_mfma_f32_16x16x32_bf16 v[10:13], v[182:185], v[206:209], v[10:13]
	v_mfma_f32_16x16x32_bf16 v[10:13], v[186:189], v[212:215], v[10:13]
	v_mfma_f32_16x16x32_bf16 v[2:5], v[186:189], v[220:223], v[2:5]
	v_mfma_f32_16x16x32_bf16 v[2:5], v[182:185], v[216:219], v[2:5]
	v_mfma_f32_16x16x32_bf16 v[6:9], v[170:173], v[216:219], v[6:9]
	v_mfma_f32_16x16x32_bf16 v[6:9], v[174:177], v[220:223], v[6:9]
	v_mfma_f32_16x16x32_bf16 v[18:21], v[174:177], v[212:215], v[18:21]
	v_mfma_f32_16x16x32_bf16 v[18:21], v[170:173], v[206:209], v[18:21]
	v_mfma_f32_16x16x32_bf16 v[34:37], v[170:173], v[198:201], v[34:37]
	v_mfma_f32_16x16x32_bf16 v[34:37], v[174:177], v[202:205], v[34:37]
	v_mfma_f32_16x16x32_bf16 v[50:53], v[174:177], v[194:197], v[50:53]
	v_mfma_f32_16x16x32_bf16 v[50:53], v[170:173], v[190:193], v[50:53]
	s_setprio 0
	s_barrier
	s_add_i32 s29, s29, 2
	s_add_u32 s0, s0, 0x100
	s_addc_u32 s1, s1, 0
	s_add_u32 s27, s27, 0x100
	s_addc_u32 s28, s28, 0
	s_cmp_gt_u32 s29, 13
	s_cbranch_scc0 .LBB0_389
	s_and_b64 vcc, exec, s[40:41]
	s_cbranch_vccz .LBB0_392
	s_barrier

; #define PG8_STAGE(bufoff, gbase, voff) do { _Pragma("unroll") for (int _i = 0; _i < 2; ++_i) \
;         __builtin_amdgcn_global_load_lds((const unsigned*)((const char*)(gbase) + (voff)[_i]), (PG8_LAS unsigned*)(lds + (bufoff) + ldsw + _i * 8192), 16, 0, 0); } while (0)
; #define PG8_LDA(dst, b, h) do { _Pragma("unroll") for (int m = 0; m < 4; ++m) _Pragma("unroll") for (int k = 0; k < 2; ++k) dst[m][k] = *(const PG8_LAS bf16x8*)(lds + PG8_SA(b, h) + aoff + m * 2048 + k * 1024); } while (0)
; #define PG8_LDB(dst, b, h) do { _Pragma("unroll") for (int n = 0; n < 2; ++n) _Pragma("unroll") for (int k = 0; k < 2; ++k) dst[n][k] = *(const PG8_LAS bf16x8*)(lds + PG8_SB(b, h) + boff + n * 2048 + k * 1024); } while (0)
; #define PG8_MMA(ai, bj, At, Bt) do { __builtin_amdgcn_s_setprio(1); _Pragma("unroll") for (int m = 0; m < 4; ++m) _Pragma("unroll") for (int n = 0; n < 2; ++n) _Pragma("unroll") for (int k = 0; k < 2; ++k) \
;         acc[ai][bj][m][n] = mma16(Bt[n][k], At[m][k], acc[ai][bj][m][n]); __builtin_amdgcn_s_setprio(0); } while (0)
; #define PG8_WAIT_V(n) asm volatile("s_waitcnt vmcnt(" #n ")" ::: "memory")
; #define PG8_WAIT_L(n) asm volatile("s_waitcnt lgkmcnt(" #n ")" ::: "memory")
; #define PG8_BAR __builtin_amdgcn_s_barrier()
; #define PG8_SCHED __builtin_amdgcn_sched_barrier(0)
; template <class Epi, class Sched, bool ALIGN_EPI = false, bool SP2 = false>
; __device__ __forceinline__ void gemm_phase(PG8_LAS unsigned char* lds, const Gemm g, const Sched& S, const Epi& E) {
;     ...
;             const bool last = (t == nt - 2);
;             const char* a1 = cA + (size_t)(t + 1) * kstep;
;             const char* a2 = last ? nA : cA + (size_t)(t + 2) * kstep; const char* b2 = last ? nB : cB + (size_t)(t + 2) * kstep;
;             const char* a3 = a2 + kstep; const char* b3 = b2 + kstep;
;             if (last && has_next) S.a_ready(nxt);
;             if constexpr (SP2) {
;             PG8_LDB(B0, 0, 0); PG8_LDB(B1, 0, 1); PG8_SCHED; PG8_LDA(At, 0, 0); PG8_STAGE(PG8_SA(1, 1), a1 + hstepA, voffA);
;             PG8_WAIT_V(8); PG8_WAIT_L(0); PG8_BAR; PG8_MMA(0, 0, At, B0); PG8_MMA(0, 1, At, B1); PG8_BAR; PG8_SCHED;
;             PG8_LDA(At, 0, 1); PG8_STAGE(PG8_SB(0, 0), b2, voffB); PG8_STAGE(PG8_SB(0, 1), b2 + hstepB, voffB); PG8_STAGE(PG8_SA(0, 0), a2, voffA);
.LBB0_555:
	ds_read_b128 v[82:85], v181
	ds_read_b128 v[86:89], v181 offset:1024
	ds_read_b128 v[138:141], v181 offset:2048
	ds_read_b128 v[142:145], v181 offset:3072
	ds_read_b128 v[146:149], v213
	ds_read_b128 v[150:153], v213 offset:1024
	ds_read_b128 v[154:157], v213 offset:2048
	ds_read_b128 v[158:161], v213 offset:3072
	s_add_u32 s47, s62, 0xfff80080
	s_addc_u32 s61, s63, -1
	s_cmp_eq_u32 s46, 28
	s_cselect_b32 s67, s28, s61
	s_cselect_b32 s66, s29, s47
	s_cselect_b32 s65, s33, s37
	s_cselect_b32 s64, s35, s36
	v_lshl_add_u64 v[194:195], s[62:63], 0, v[174:175]
	s_add_i32 m0, s11, 0xc000
	ds_read_b128 v[186:189], v214
	ds_read_b128 v[190:193], v214 offset:1024
	ds_read_b128 v[216:219], v214 offset:2048
	ds_read_b128 v[220:223], v214 offset:3072
	ds_read_b128 v[224:227], v214 offset:4096
	ds_read_b128 v[228:231], v214 offset:5120
	ds_read_b128 v[232:235], v214 offset:6144
	ds_read_b128 v[236:239], v214 offset:7168
	global_load_lds_dwordx4 v[194:195], off
	v_lshl_add_u64 v[194:195], s[62:63], 0, v[176:177]
	s_add_i32 m0, s11, 0xe000
	s_nop 0
	global_load_lds_dwordx4 v[194:195], off
	s_waitcnt vmcnt(8)
	s_waitcnt lgkmcnt(0)
	s_barrier
	s_setprio 1
	s_waitcnt lgkmcnt(0)
	v_mfma_i32_16x16x64_i8 v[70:73], v[82:85], v[186:189], v[70:73]
	v_mfma_i32_16x16x64_i8 v[70:73], v[86:89], v[190:193], v[70:73]
	v_mfma_i32_16x16x64_i8 v[126:129], v[86:89], v[220:223], v[126:129]
	v_mfma_i32_16x16x64_i8 v[126:129], v[82:85], v[216:219], v[126:129]
	v_mfma_i32_16x16x64_i8 v[110:113], v[82:85], v[224:227], v[110:113]
	v_mfma_i32_16x16x64_i8 v[110:113], v[86:89], v[228:231], v[110:113]
	v_mfma_i32_16x16x64_i8 v[94:97], v[86:89], v[236:239], v[94:97]
	v_mfma_i32_16x16x64_i8 v[94:97], v[82:85], v[232:235], v[94:97]
	v_mfma_i32_16x16x64_i8 v[90:93], v[138:141], v[232:235], v[90:93]
	v_mfma_i32_16x16x64_i8 v[90:93], v[142:145], v[236:239], v[90:93]
	v_mfma_i32_16x16x64_i8 v[106:109], v[142:145], v[228:231], v[106:109]
	v_mfma_i32_16x16x64_i8 v[106:109], v[138:141], v[224:227], v[106:109]
	v_mfma_i32_16x16x64_i8 v[122:125], v[138:141], v[216:219], v[122:125]
	v_mfma_i32_16x16x64_i8 v[122:125], v[142:145], v[220:223], v[122:125]
	v_mfma_i32_16x16x64_i8 v[66:69], v[142:145], v[190:193], v[66:69]
	v_mfma_i32_16x16x64_i8 v[66:69], v[138:141], v[186:189], v[66:69]
	s_setprio 0
	s_setprio 1
	v_mfma_i32_16x16x64_i8 v[130:133], v[154:157], v[186:189], v[130:133]
	v_mfma_i32_16x16x64_i8 v[130:133], v[158:161], v[190:193], v[130:133]
	v_mfma_i32_16x16x64_i8 v[114:117], v[158:161], v[220:223], v[114:117]
	v_mfma_i32_16x16x64_i8 v[114:117], v[154:157], v[216:219], v[114:117]
	v_mfma_i32_16x16x64_i8 v[98:101], v[154:157], v[224:227], v[98:101]
	v_mfma_i32_16x16x64_i8 v[98:101], v[158:161], v[228:231], v[98:101]
	v_mfma_i32_16x16x64_i8 v[74:77], v[158:161], v[236:239], v[74:77]
	v_mfma_i32_16x16x64_i8 v[74:77], v[154:157], v[232:235], v[74:77]
	v_mfma_i32_16x16x64_i8 v[78:81], v[146:149], v[232:235], v[78:81]
	v_mfma_i32_16x16x64_i8 v[78:81], v[150:153], v[236:239], v[78:81]
	v_mfma_i32_16x16x64_i8 v[102:105], v[150:153], v[228:231], v[102:105]
	v_mfma_i32_16x16x64_i8 v[102:105], v[146:149], v[224:227], v[102:105]
	v_mfma_i32_16x16x64_i8 v[118:121], v[146:149], v[216:219], v[118:121]
	v_mfma_i32_16x16x64_i8 v[118:121], v[150:153], v[220:223], v[118:121]
	v_mfma_i32_16x16x64_i8 v[134:137], v[150:153], v[190:193], v[134:137]
	v_mfma_i32_16x16x64_i8 v[134:137], v[146:149], v[186:189], v[134:137]
	s_setprio 0
	s_barrier
	s_add_i32 s47, s23, s7
	v_lshl_add_u64 v[194:195], s[64:65], 0, v[164:165]
	s_mov_b32 m0, s47
	ds_read_b128 v[186:189], v214 offset:16384
	ds_read_b128 v[190:193], v214 offset:17408
	ds_read_b128 v[216:219], v214 offset:18432
	ds_read_b128 v[220:223], v214 offset:19456
	ds_read_b128 v[224:227], v214 offset:20480
	ds_read_b128 v[228:231], v214 offset:21504
	ds_read_b128 v[232:235], v214 offset:22528
	ds_read_b128 v[236:239], v214 offset:23552
	global_load_lds_dwordx4 v[194:195], off
	s_add_i32 m0, s47, 0x2000
	s_add_u32 s68, s64, 0x80000
	v_lshl_add_u64 v[240:241], s[64:65], 0, v[168:169]
	s_addc_u32 s69, s65, 0
	s_add_i32 s47, s24, s7
	global_load_lds_dwordx4 v[240:241], off
	v_lshl_add_u64 v[242:243], s[68:69], 0, v[164:165]
	s_mov_b32 m0, s47
	v_lshl_add_u64 v[244:245], s[66:67], 0, v[166:167]
	global_load_lds_dwordx4 v[242:243], off
	v_lshl_add_u64 v[242:243], s[68:69], 0, v[168:169]
	s_add_i32 m0, s47, 0x2000
	s_nop 0
	global_load_lds_dwordx4 v[242:243], off
	v_lshl_add_u64 v[242:243], s[66:67], 0, v[162:163]
	s_mov_b32 m0, s11
	s_nop 0
	global_load_lds_dwordx4 v[242:243], off
	s_mov_b32 m0, s12
	s_nop 0
	global_load_lds_dwordx4 v[244:245], off
	s_waitcnt vmcnt(8)
	s_waitcnt lgkmcnt(0)
	s_barrier
; #define PG8_STAGE(bufoff, gbase, voff) do { _Pragma("unroll") for (int _i = 0; _i < 2; ++_i) \
;         __builtin_amdgcn_global_load_lds((const unsigned*)((const char*)(gbase) + (voff)[_i]), (PG8_LAS unsigned*)(lds + (bufoff) + ldsw + _i * 8192), 16, 0, 0); } while (0)
; #define PG8_LDA(dst, b, h) do { _Pragma("unroll") for (int m = 0; m < 4; ++m) _Pragma("unroll") for (int k = 0; k < 2; ++k) dst[m][k] = *(const PG8_LAS bf16x8*)(lds + PG8_SA(b, h) + aoff + m * 2048 + k * 1024); } while (0)
; #define PG8_LDB(dst, b, h) do { _Pragma("unroll") for (int n = 0; n < 2; ++n) _Pragma("unroll") for (int k = 0; k < 2; ++k) dst[n][k] = *(const PG8_LAS bf16x8*)(lds + PG8_SB(b, h) + boff + n * 2048 + k * 1024); } while (0)
; #define PG8_MMA(ai, bj, At, Bt) do { __builtin_amdgcn_s_setprio(1); _Pragma("unroll") for (int m = 0; m < 4; ++m) _Pragma("unroll") for (int n = 0; n < 2; ++n) _Pragma("unroll") for (int k = 0; k < 2; ++k) \
;         acc[ai][bj][m][n] = mma16(Bt[n][k], At[m][k], acc[ai][bj][m][n]); __builtin_amdgcn_s_setprio(0); } while (0)
; #define PG8_WAIT_V(n) asm volatile("s_waitcnt vmcnt(" #n ")" ::: "memory")
; #define PG8_WAIT_L(n) asm volatile("s_waitcnt lgkmcnt(" #n ")" ::: "memory")
; #define PG8_BAR __builtin_amdgcn_s_barrier()
; #define PG8_SCHED __builtin_amdgcn_sched_barrier(0)
; template <class Epi, class Sched, bool ALIGN_EPI = false, bool SP2 = false>
; __device__ __forceinline__ void gemm_phase(PG8_LAS unsigned char* lds, const Gemm g, const Sched& S, const Epi& E) {
;     ...
;             PG8_WAIT_V(8); PG8_WAIT_L(0); PG8_BAR; PG8_MMA(1, 0, At, B0); PG8_MMA(1, 1, At, B1); PG8_BAR; PG8_SCHED;
;             PG8_LDB(B0, 1, 0); PG8_LDB(B1, 1, 1); PG8_SCHED; PG8_LDA(At, 1, 0); PG8_STAGE(PG8_SA(0, 1), a2 + hstepA, voffA);
;             PG8_WAIT_V(8); PG8_WAIT_L(0); PG8_BAR; PG8_MMA(0, 0, At, B0); PG8_MMA(0, 1, At, B1); PG8_BAR; PG8_SCHED;
	s_setprio 1
	s_waitcnt lgkmcnt(0)
	v_mfma_i32_16x16x64_i8 v[62:65], v[82:85], v[186:189], v[62:65]
	v_mfma_i32_16x16x64_i8 v[62:65], v[86:89], v[190:193], v[62:65]
	v_mfma_i32_16x16x64_i8 v[46:49], v[86:89], v[220:223], v[46:49]
	v_mfma_i32_16x16x64_i8 v[46:49], v[82:85], v[216:219], v[46:49]
	v_mfma_i32_16x16x64_i8 v[30:33], v[82:85], v[224:227], v[30:33]
	v_mfma_i32_16x16x64_i8 v[30:33], v[86:89], v[228:231], v[30:33]
	v_mfma_i32_16x16x64_i8 v[14:17], v[86:89], v[236:239], v[14:17]
	v_mfma_i32_16x16x64_i8 v[14:17], v[82:85], v[232:235], v[14:17]
	v_mfma_i32_16x16x64_i8 v[10:13], v[138:141], v[232:235], v[10:13]
	v_mfma_i32_16x16x64_i8 v[10:13], v[142:145], v[236:239], v[10:13]
	v_mfma_i32_16x16x64_i8 v[26:29], v[142:145], v[228:231], v[26:29]
	v_mfma_i32_16x16x64_i8 v[26:29], v[138:141], v[224:227], v[26:29]
	v_mfma_i32_16x16x64_i8 v[42:45], v[138:141], v[216:219], v[42:45]
	v_mfma_i32_16x16x64_i8 v[42:45], v[142:145], v[220:223], v[42:45]
	v_mfma_i32_16x16x64_i8 v[58:61], v[142:145], v[190:193], v[58:61]
	v_mfma_i32_16x16x64_i8 v[58:61], v[138:141], v[186:189], v[58:61]
	s_setprio 0
	s_setprio 1
	v_mfma_i32_16x16x64_i8 v[50:53], v[154:157], v[186:189], v[50:53]
	v_mfma_i32_16x16x64_i8 v[50:53], v[158:161], v[190:193], v[50:53]
	v_mfma_i32_16x16x64_i8 v[34:37], v[158:161], v[220:223], v[34:37]
	v_mfma_i32_16x16x64_i8 v[34:37], v[154:157], v[216:219], v[34:37]
	v_mfma_i32_16x16x64_i8 v[18:21], v[154:157], v[224:227], v[18:21]
	v_mfma_i32_16x16x64_i8 v[18:21], v[158:161], v[228:231], v[18:21]
	v_mfma_i32_16x16x64_i8 v[2:5], v[158:161], v[236:239], v[2:5]
	v_mfma_i32_16x16x64_i8 v[2:5], v[154:157], v[232:235], v[2:5]
	v_mfma_i32_16x16x64_i8 v[6:9], v[146:149], v[232:235], v[6:9]
	v_mfma_i32_16x16x64_i8 v[6:9], v[150:153], v[236:239], v[6:9]
	v_mfma_i32_16x16x64_i8 v[22:25], v[150:153], v[228:231], v[22:25]
	v_mfma_i32_16x16x64_i8 v[22:25], v[146:149], v[224:227], v[22:25]
	v_mfma_i32_16x16x64_i8 v[38:41], v[146:149], v[216:219], v[38:41]
	v_mfma_i32_16x16x64_i8 v[38:41], v[150:153], v[220:223], v[38:41]
	v_mfma_i32_16x16x64_i8 v[54:57], v[150:153], v[190:193], v[54:57]
	v_mfma_i32_16x16x64_i8 v[54:57], v[146:149], v[186:189], v[54:57]
	s_setprio 0
	s_barrier
	s_add_i32 s47, 0, 0x18000
	s_add_i32 s61, 0, 0x1c000
	v_add_u32_e32 v142, s47, v209
	v_add_u32_e32 v158, s61, v209
	ds_read_b128 v[82:85], v142
	ds_read_b128 v[86:89], v142 offset:1024
	ds_read_b128 v[138:141], v142 offset:2048
	ds_read_b128 v[142:145], v142 offset:3072
	ds_read_b128 v[146:149], v158
	ds_read_b128 v[150:153], v158 offset:1024
	ds_read_b128 v[154:157], v158 offset:2048
	ds_read_b128 v[158:161], v158 offset:3072
	s_add_u32 s66, s66, 0x80000
	s_addc_u32 s67, s67, 0
	s_mov_b32 m0, s13
	v_lshl_add_u64 v[246:247], s[66:67], 0, v[162:163]
	ds_read_b128 v[186:189], v214 offset:32768
	ds_read_b128 v[190:193], v214 offset:33792
	ds_read_b128 v[216:219], v214 offset:34816
	ds_read_b128 v[220:223], v214 offset:35840
	ds_read_b128 v[224:227], v214 offset:36864
	ds_read_b128 v[228:231], v214 offset:37888
	ds_read_b128 v[232:235], v214 offset:38912
	ds_read_b128 v[236:239], v214 offset:39936
	global_load_lds_dwordx4 v[246:247], off
	v_lshl_add_u64 v[246:247], s[66:67], 0, v[166:167]
	s_mov_b32 m0, s16
	s_nop 0
	global_load_lds_dwordx4 v[246:247], off
	s_waitcnt vmcnt(8)
	s_waitcnt lgkmcnt(0)
	s_barrier
	s_setprio 1
	s_waitcnt lgkmcnt(0)
	v_mfma_i32_16x16x64_i8 v[70:73], v[82:85], v[186:189], v[70:73]
	v_mfma_i32_16x16x64_i8 v[70:73], v[86:89], v[190:193], v[70:73]
	v_mfma_i32_16x16x64_i8 v[126:129], v[86:89], v[220:223], v[126:129]
	v_mfma_i32_16x16x64_i8 v[126:129], v[82:85], v[216:219], v[126:129]
	v_mfma_i32_16x16x64_i8 v[110:113], v[82:85], v[224:227], v[110:113]
	v_mfma_i32_16x16x64_i8 v[110:113], v[86:89], v[228:231], v[110:113]
	v_mfma_i32_16x16x64_i8 v[94:97], v[86:89], v[236:239], v[94:97]
	v_mfma_i32_16x16x64_i8 v[94:97], v[82:85], v[232:235], v[94:97]
	v_mfma_i32_16x16x64_i8 v[90:93], v[138:141], v[232:235], v[90:93]
	v_mfma_i32_16x16x64_i8 v[90:93], v[142:145], v[236:239], v[90:93]
	v_mfma_i32_16x16x64_i8 v[106:109], v[142:145], v[228:231], v[106:109]
	v_mfma_i32_16x16x64_i8 v[106:109], v[138:141], v[224:227], v[106:109]
	v_mfma_i32_16x16x64_i8 v[122:125], v[138:141], v[216:219], v[122:125]
	v_mfma_i32_16x16x64_i8 v[122:125], v[142:145], v[220:223], v[122:125]
	v_mfma_i32_16x16x64_i8 v[66:69], v[142:145], v[190:193], v[66:69]
	v_mfma_i32_16x16x64_i8 v[66:69], v[138:141], v[186:189], v[66:69]
	s_setprio 0
	s_setprio 1
	v_mfma_i32_16x16x64_i8 v[130:133], v[154:157], v[186:189], v[130:133]
	v_mfma_i32_16x16x64_i8 v[130:133], v[158:161], v[190:193], v[130:133]
	v_mfma_i32_16x16x64_i8 v[114:117], v[158:161], v[220:223], v[114:117]
	v_mfma_i32_16x16x64_i8 v[114:117], v[154:157], v[216:219], v[114:117]
	v_mfma_i32_16x16x64_i8 v[98:101], v[154:157], v[224:227], v[98:101]
	v_mfma_i32_16x16x64_i8 v[98:101], v[158:161], v[228:231], v[98:101]
	v_mfma_i32_16x16x64_i8 v[74:77], v[158:161], v[236:239], v[74:77]
	v_mfma_i32_16x16x64_i8 v[74:77], v[154:157], v[232:235], v[74:77]
	v_mfma_i32_16x16x64_i8 v[78:81], v[146:149], v[232:235], v[78:81]
	v_mfma_i32_16x16x64_i8 v[78:81], v[150:153], v[236:239], v[78:81]
	v_mfma_i32_16x16x64_i8 v[102:105], v[150:153], v[228:231], v[102:105]
	v_mfma_i32_16x16x64_i8 v[102:105], v[146:149], v[224:227], v[102:105]
	v_mfma_i32_16x16x64_i8 v[118:121], v[146:149], v[216:219], v[118:121]
	v_mfma_i32_16x16x64_i8 v[118:121], v[150:153], v[220:223], v[118:121]
	v_mfma_i32_16x16x64_i8 v[134:137], v[150:153], v[190:193], v[134:137]
	v_mfma_i32_16x16x64_i8 v[134:137], v[146:149], v[186:189], v[134:137]
	s_setprio 0
	s_barrier
; #define PG8_STAGE(bufoff, gbase, voff) do { _Pragma("unroll") for (int _i = 0; _i < 2; ++_i) \
;         __builtin_amdgcn_global_load_lds((const unsigned*)((const char*)(gbase) + (voff)[_i]), (PG8_LAS unsigned*)(lds + (bufoff) + ldsw + _i * 8192), 16, 0, 0); } while (0)
; #define PG8_LDA(dst, b, h) do { _Pragma("unroll") for (int m = 0; m < 4; ++m) _Pragma("unroll") for (int k = 0; k < 2; ++k) dst[m][k] = *(const PG8_LAS bf16x8*)(lds + PG8_SA(b, h) + aoff + m * 2048 + k * 1024); } while (0)
; #define PG8_MMA(ai, bj, At, Bt) do { __builtin_amdgcn_s_setprio(1); _Pragma("unroll") for (int m = 0; m < 4; ++m) _Pragma("unroll") for (int n = 0; n < 2; ++n) _Pragma("unroll") for (int k = 0; k < 2; ++k) \
;         acc[ai][bj][m][n] = mma16(Bt[n][k], At[m][k], acc[ai][bj][m][n]); __builtin_amdgcn_s_setprio(0); } while (0)
; #define PG8_WAIT_V(n) asm volatile("s_waitcnt vmcnt(" #n ")" ::: "memory")
; #define PG8_WAIT_L(n) asm volatile("s_waitcnt lgkmcnt(" #n ")" ::: "memory")
; #define PG8_BAR __builtin_amdgcn_s_barrier()
; #define PG8_SCHED __builtin_amdgcn_sched_barrier(0)
; template <class Epi, class Sched, bool ALIGN_EPI = false, bool SP2 = false>
; __device__ __forceinline__ void gemm_phase(PG8_LAS unsigned char* lds, const Gemm g, const Sched& S, const Epi& E) {
;     ...
;             PG8_LDA(At, 1, 1); PG8_STAGE(PG8_SB(1, 0), b3, voffB); PG8_STAGE(PG8_SB(1, 1), b3 + hstepB, voffB); PG8_STAGE(PG8_SA(1, 0), a3, voffA);
;             PG8_WAIT_V(8); PG8_WAIT_L(0); PG8_BAR; PG8_MMA(1, 0, At, B0); PG8_MMA(1, 1, At, B1); PG8_BAR; PG8_SCHED;
;     ...
;         if constexpr (ALIGN_EPI) { if (wr == 0) PG8_BAR; }
	s_add_i32 s47, s47, s7
	v_lshl_add_u64 v[194:195], v[194:195], 0, s[50:51]
	s_mov_b32 m0, s47
	ds_read_b128 v[186:189], v214 offset:49152
	ds_read_b128 v[190:193], v214 offset:50176
	ds_read_b128 v[216:219], v214 offset:51200
	ds_read_b128 v[220:223], v214 offset:52224
	ds_read_b128 v[224:227], v214 offset:53248
	ds_read_b128 v[228:231], v214 offset:54272
	ds_read_b128 v[232:235], v214 offset:55296
	ds_read_b128 v[236:239], v214 offset:56320
	global_load_lds_dwordx4 v[194:195], off
	s_add_i32 m0, s47, 0x2000
	s_add_u32 s64, s64, 0x80080
	v_lshl_add_u64 v[194:195], v[240:241], 0, s[50:51]
	s_addc_u32 s65, s65, 0
	s_add_i32 s47, s61, s7
	global_load_lds_dwordx4 v[194:195], off
	v_lshl_add_u64 v[194:195], s[64:65], 0, v[164:165]
	s_mov_b32 m0, s47
	s_nop 0
	global_load_lds_dwordx4 v[194:195], off
	v_lshl_add_u64 v[194:195], s[64:65], 0, v[168:169]
	s_add_i32 m0, s47, 0x2000
	s_nop 0
	global_load_lds_dwordx4 v[194:195], off
	v_lshl_add_u64 v[194:195], v[242:243], 0, s[50:51]
	s_mov_b32 m0, s19
	s_nop 0
	global_load_lds_dwordx4 v[194:195], off
	v_lshl_add_u64 v[194:195], v[244:245], 0, s[50:51]
	s_mov_b32 m0, s20
	s_nop 0
	global_load_lds_dwordx4 v[194:195], off
	s_waitcnt vmcnt(8)
	s_waitcnt lgkmcnt(0)
	s_barrier
	s_setprio 1
	s_waitcnt lgkmcnt(0)
	v_mfma_i32_16x16x64_i8 v[62:65], v[82:85], v[186:189], v[62:65]
	v_mfma_i32_16x16x64_i8 v[62:65], v[86:89], v[190:193], v[62:65]
	v_mfma_i32_16x16x64_i8 v[46:49], v[86:89], v[220:223], v[46:49]
	v_mfma_i32_16x16x64_i8 v[46:49], v[82:85], v[216:219], v[46:49]
	v_mfma_i32_16x16x64_i8 v[30:33], v[82:85], v[224:227], v[30:33]
	v_mfma_i32_16x16x64_i8 v[30:33], v[86:89], v[228:231], v[30:33]
	v_mfma_i32_16x16x64_i8 v[14:17], v[86:89], v[236:239], v[14:17]
	v_mfma_i32_16x16x64_i8 v[14:17], v[82:85], v[232:235], v[14:17]
	v_mfma_i32_16x16x64_i8 v[10:13], v[138:141], v[232:235], v[10:13]
	v_mfma_i32_16x16x64_i8 v[10:13], v[142:145], v[236:239], v[10:13]
	v_mfma_i32_16x16x64_i8 v[26:29], v[142:145], v[228:231], v[26:29]
	v_mfma_i32_16x16x64_i8 v[26:29], v[138:141], v[224:227], v[26:29]
	v_mfma_i32_16x16x64_i8 v[42:45], v[138:141], v[216:219], v[42:45]
	v_mfma_i32_16x16x64_i8 v[42:45], v[142:145], v[220:223], v[42:45]
	v_mfma_i32_16x16x64_i8 v[58:61], v[142:145], v[190:193], v[58:61]
	v_mfma_i32_16x16x64_i8 v[58:61], v[138:141], v[186:189], v[58:61]
	s_setprio 0
	s_setprio 1
	v_mfma_i32_16x16x64_i8 v[50:53], v[154:157], v[186:189], v[50:53]
	v_mfma_i32_16x16x64_i8 v[50:53], v[158:161], v[190:193], v[50:53]
	v_mfma_i32_16x16x64_i8 v[34:37], v[158:161], v[220:223], v[34:37]
	v_mfma_i32_16x16x64_i8 v[34:37], v[154:157], v[216:219], v[34:37]
	v_mfma_i32_16x16x64_i8 v[18:21], v[154:157], v[224:227], v[18:21]
	v_mfma_i32_16x16x64_i8 v[18:21], v[158:161], v[228:231], v[18:21]
	v_mfma_i32_16x16x64_i8 v[2:5], v[158:161], v[236:239], v[2:5]
	v_mfma_i32_16x16x64_i8 v[2:5], v[154:157], v[232:235], v[2:5]
	v_mfma_i32_16x16x64_i8 v[6:9], v[146:149], v[232:235], v[6:9]
	v_mfma_i32_16x16x64_i8 v[6:9], v[150:153], v[236:239], v[6:9]
	v_mfma_i32_16x16x64_i8 v[22:25], v[150:153], v[228:231], v[22:25]
	v_mfma_i32_16x16x64_i8 v[22:25], v[146:149], v[224:227], v[22:25]
	v_mfma_i32_16x16x64_i8 v[38:41], v[146:149], v[216:219], v[38:41]
	v_mfma_i32_16x16x64_i8 v[38:41], v[150:153], v[220:223], v[38:41]
	v_mfma_i32_16x16x64_i8 v[54:57], v[150:153], v[190:193], v[54:57]
	v_mfma_i32_16x16x64_i8 v[54:57], v[146:149], v[186:189], v[54:57]
	s_setprio 0
	s_barrier
	s_add_i32 s46, s46, 2
	s_add_u32 s62, s62, 0x100
	s_addc_u32 s63, s63, 0
	s_add_u32 s36, s36, 0x100
	s_addc_u32 s37, s37, 0
	s_cmp_gt_u32 s46, 29
	s_cbranch_scc0 .LBB0_555
	s_and_b64 vcc, exec, s[52:53]
	s_cbranch_vccz .LBB0_558
	s_barrier

; #define PG8_STAGE(bufoff, gbase, voff) do { _Pragma("unroll") for (int _i = 0; _i < 2; ++_i) \
;         __builtin_amdgcn_global_load_lds((const unsigned*)((const char*)(gbase) + (voff)[_i]), (PG8_LAS unsigned*)(lds + (bufoff) + ldsw + _i * 8192), 16, 0, 0); } while (0)
; #define PG8_LDA(dst, b, h) do { _Pragma("unroll") for (int m = 0; m < 4; ++m) _Pragma("unroll") for (int k = 0; k < 2; ++k) dst[m][k] = *(const PG8_LAS bf16x8*)(lds + PG8_SA(b, h) + aoff + m * 2048 + k * 1024); } while (0)
; #define PG8_LDB(dst, b, h) do { _Pragma("unroll") for (int n = 0; n < 2; ++n) _Pragma("unroll") for (int k = 0; k < 2; ++k) dst[n][k] = *(const PG8_LAS bf16x8*)(lds + PG8_SB(b, h) + boff + n * 2048 + k * 1024); } while (0)
; #define PG8_MMA(ai, bj, At, Bt) do { __builtin_amdgcn_s_setprio(1); _Pragma("unroll") for (int m = 0; m < 4; ++m) _Pragma("unroll") for (int n = 0; n < 2; ++n) _Pragma("unroll") for (int k = 0; k < 2; ++k) \
;         acc[ai][bj][m][n] = mma16(Bt[n][k], At[m][k], acc[ai][bj][m][n]); __builtin_amdgcn_s_setprio(0); } while (0)
; #define PG8_WAIT_V(n) asm volatile("s_waitcnt vmcnt(" #n ")" ::: "memory")
; #define PG8_WAIT_L(n) asm volatile("s_waitcnt lgkmcnt(" #n ")" ::: "memory")
; #define PG8_BAR __builtin_amdgcn_s_barrier()
; #define PG8_SCHED __builtin_amdgcn_sched_barrier(0)
; template <class Epi, class Sched, bool ALIGN_EPI = false, bool SP2 = false>
; __device__ __forceinline__ void gemm_phase(PG8_LAS unsigned char* lds, const Gemm g, const Sched& S, const Epi& E) {
;     ...
;             const bool last = (t == nt - 2);
;             const char* a1 = cA + (size_t)(t + 1) * kstep;
;             const char* a2 = last ? nA : cA + (size_t)(t + 2) * kstep; const char* b2 = last ? nB : cB + (size_t)(t + 2) * kstep;
;             const char* a3 = a2 + kstep; const char* b3 = b2 + kstep;
;             if (last && has_next) S.a_ready(nxt);
;             if constexpr (SP2) {
;             PG8_LDB(B0, 0, 0); PG8_LDB(B1, 0, 1); PG8_SCHED; PG8_LDA(At, 0, 0); PG8_STAGE(PG8_SA(1, 1), a1 + hstepA, voffA);
;             PG8_WAIT_V(8); PG8_WAIT_L(0); PG8_BAR; PG8_MMA(0, 0, At, B0); PG8_MMA(0, 1, At, B1); PG8_BAR; PG8_SCHED;
;             PG8_LDA(At, 0, 1); PG8_STAGE(PG8_SB(0, 0), b2, voffB); PG8_STAGE(PG8_SB(0, 1), b2 + hstepB, voffB); PG8_STAGE(PG8_SA(0, 0), a2, voffA);
.LBB0_579:
	ds_read_b128 v[130:133], v1
	ds_read_b128 v[134:137], v1 offset:1024
	ds_read_b128 v[138:141], v1 offset:2048
	ds_read_b128 v[142:145], v1 offset:3072
	ds_read_b128 v[146:149], v214
	ds_read_b128 v[150:153], v214 offset:1024
	ds_read_b128 v[154:157], v214 offset:2048
	ds_read_b128 v[158:161], v214 offset:3072
	s_add_u32 s35, s56, 0xfff00080
	s_addc_u32 s36, s57, -1
	s_cmp_eq_u32 s33, 60
	s_cselect_b32 s61, s24, s36
	s_cselect_b32 s60, s25, s35
	s_cselect_b32 s59, s26, s29
	s_cselect_b32 s58, s27, s28
	v_lshl_add_u64 v[220:221], s[56:57], 0, v[190:191]
	s_add_i32 m0, s8, 0xc000
	ds_read_b128 v[162:165], v215
	ds_read_b128 v[166:169], v215 offset:1024
	ds_read_b128 v[170:173], v215 offset:2048
	ds_read_b128 v[174:177], v215 offset:3072
	ds_read_b128 v[198:201], v215 offset:4096
	ds_read_b128 v[202:205], v215 offset:5120
	ds_read_b128 v[206:209], v215 offset:6144
	ds_read_b128 v[216:219], v215 offset:7168
	global_load_lds_dwordx4 v[220:221], off
	v_lshl_add_u64 v[220:221], s[56:57], 0, v[192:193]
	s_add_i32 m0, s8, 0xe000
	s_nop 0
	global_load_lds_dwordx4 v[220:221], off
	s_waitcnt vmcnt(8)
	s_waitcnt lgkmcnt(0)
	s_barrier
	s_setprio 1
	s_waitcnt lgkmcnt(0)
	v_mfma_f32_16x16x32_bf16 v[126:129], v[130:133], v[162:165], v[126:129]
	v_mfma_f32_16x16x32_bf16 v[126:129], v[134:137], v[166:169], v[126:129]
	v_mfma_f32_16x16x32_bf16 v[110:113], v[134:137], v[174:177], v[110:113]
	v_mfma_f32_16x16x32_bf16 v[110:113], v[130:133], v[170:173], v[110:113]
	v_mfma_f32_16x16x32_bf16 v[94:97], v[130:133], v[198:201], v[94:97]
	v_mfma_f32_16x16x32_bf16 v[94:97], v[134:137], v[202:205], v[94:97]
	v_mfma_f32_16x16x32_bf16 v[78:81], v[134:137], v[216:219], v[78:81]
	v_mfma_f32_16x16x32_bf16 v[78:81], v[130:133], v[206:209], v[78:81]
	v_mfma_f32_16x16x32_bf16 v[74:77], v[138:141], v[206:209], v[74:77]
	v_mfma_f32_16x16x32_bf16 v[74:77], v[142:145], v[216:219], v[74:77]
	v_mfma_f32_16x16x32_bf16 v[90:93], v[142:145], v[202:205], v[90:93]
	v_mfma_f32_16x16x32_bf16 v[90:93], v[138:141], v[198:201], v[90:93]
	v_mfma_f32_16x16x32_bf16 v[106:109], v[138:141], v[170:173], v[106:109]
	v_mfma_f32_16x16x32_bf16 v[106:109], v[142:145], v[174:177], v[106:109]
	v_mfma_f32_16x16x32_bf16 v[122:125], v[142:145], v[166:169], v[122:125]
	v_mfma_f32_16x16x32_bf16 v[122:125], v[138:141], v[162:165], v[122:125]
	s_setprio 0
	s_setprio 1
	v_mfma_f32_16x16x32_bf16 v[114:117], v[154:157], v[162:165], v[114:117]
	v_mfma_f32_16x16x32_bf16 v[114:117], v[158:161], v[166:169], v[114:117]
	v_mfma_f32_16x16x32_bf16 v[98:101], v[158:161], v[174:177], v[98:101]
	v_mfma_f32_16x16x32_bf16 v[98:101], v[154:157], v[170:173], v[98:101]
	v_mfma_f32_16x16x32_bf16 v[82:85], v[154:157], v[198:201], v[82:85]
	v_mfma_f32_16x16x32_bf16 v[82:85], v[158:161], v[202:205], v[82:85]
	v_mfma_f32_16x16x32_bf16 v[66:69], v[158:161], v[216:219], v[66:69]
	v_mfma_f32_16x16x32_bf16 v[66:69], v[154:157], v[206:209], v[66:69]
	v_mfma_f32_16x16x32_bf16 v[70:73], v[146:149], v[206:209], v[70:73]
	v_mfma_f32_16x16x32_bf16 v[70:73], v[150:153], v[216:219], v[70:73]
	v_mfma_f32_16x16x32_bf16 v[86:89], v[150:153], v[202:205], v[86:89]
	v_mfma_f32_16x16x32_bf16 v[86:89], v[146:149], v[198:201], v[86:89]
	v_mfma_f32_16x16x32_bf16 v[102:105], v[146:149], v[170:173], v[102:105]
	v_mfma_f32_16x16x32_bf16 v[102:105], v[150:153], v[174:177], v[102:105]
	v_mfma_f32_16x16x32_bf16 v[118:121], v[150:153], v[166:169], v[118:121]
	v_mfma_f32_16x16x32_bf16 v[118:121], v[146:149], v[162:165], v[118:121]
	s_setprio 0
	s_barrier
	s_add_i32 s35, s21, s7
	v_lshl_add_u64 v[220:221], s[58:59], 0, v[184:185]
	s_mov_b32 m0, s35
	ds_read_b128 v[162:165], v215 offset:16384
	ds_read_b128 v[166:169], v215 offset:17408
	ds_read_b128 v[170:173], v215 offset:18432
	ds_read_b128 v[174:177], v215 offset:19456
	ds_read_b128 v[198:201], v215 offset:20480
	ds_read_b128 v[202:205], v215 offset:21504
	ds_read_b128 v[206:209], v215 offset:22528
	ds_read_b128 v[216:219], v215 offset:23552
	global_load_lds_dwordx4 v[220:221], off
	s_add_i32 m0, s35, 0x2000
	s_add_u32 s36, s58, 0x100000
	v_lshl_add_u64 v[222:223], s[58:59], 0, v[188:189]
	s_addc_u32 s37, s59, 0
	s_add_i32 s35, s22, s7
	global_load_lds_dwordx4 v[222:223], off
	v_lshl_add_u64 v[224:225], s[36:37], 0, v[184:185]
	s_mov_b32 m0, s35
	v_lshl_add_u64 v[226:227], s[60:61], 0, v[186:187]
	global_load_lds_dwordx4 v[224:225], off
	v_lshl_add_u64 v[224:225], s[36:37], 0, v[188:189]
	s_add_i32 m0, s35, 0x2000
	s_nop 0
	global_load_lds_dwordx4 v[224:225], off
	v_lshl_add_u64 v[224:225], s[60:61], 0, v[182:183]
	s_mov_b32 m0, s8
	s_nop 0
	global_load_lds_dwordx4 v[224:225], off
	s_mov_b32 m0, s11
	s_nop 0
	global_load_lds_dwordx4 v[226:227], off
	s_waitcnt vmcnt(8)
	s_waitcnt lgkmcnt(0)
	s_barrier
; #define PG8_STAGE(bufoff, gbase, voff) do { _Pragma("unroll") for (int _i = 0; _i < 2; ++_i) \
;         __builtin_amdgcn_global_load_lds((const unsigned*)((const char*)(gbase) + (voff)[_i]), (PG8_LAS unsigned*)(lds + (bufoff) + ldsw + _i * 8192), 16, 0, 0); } while (0)
; #define PG8_LDA(dst, b, h) do { _Pragma("unroll") for (int m = 0; m < 4; ++m) _Pragma("unroll") for (int k = 0; k < 2; ++k) dst[m][k] = *(const PG8_LAS bf16x8*)(lds + PG8_SA(b, h) + aoff + m * 2048 + k * 1024); } while (0)
; #define PG8_LDB(dst, b, h) do { _Pragma("unroll") for (int n = 0; n < 2; ++n) _Pragma("unroll") for (int k = 0; k < 2; ++k) dst[n][k] = *(const PG8_LAS bf16x8*)(lds + PG8_SB(b, h) + boff + n * 2048 + k * 1024); } while (0)
; #define PG8_MMA(ai, bj, At, Bt) do { __builtin_amdgcn_s_setprio(1); _Pragma("unroll") for (int m = 0; m < 4; ++m) _Pragma("unroll") for (int n = 0; n < 2; ++n) _Pragma("unroll") for (int k = 0; k < 2; ++k) \
;         acc[ai][bj][m][n] = mma16(Bt[n][k], At[m][k], acc[ai][bj][m][n]); __builtin_amdgcn_s_setprio(0); } while (0)
; #define PG8_WAIT_V(n) asm volatile("s_waitcnt vmcnt(" #n ")" ::: "memory")
; #define PG8_WAIT_L(n) asm volatile("s_waitcnt lgkmcnt(" #n ")" ::: "memory")
; #define PG8_BAR __builtin_amdgcn_s_barrier()
; #define PG8_SCHED __builtin_amdgcn_sched_barrier(0)
; template <class Epi, class Sched, bool ALIGN_EPI = false, bool SP2 = false>
; __device__ __forceinline__ void gemm_phase(PG8_LAS unsigned char* lds, const Gemm g, const Sched& S, const Epi& E) {
;     ...
;             PG8_WAIT_V(8); PG8_WAIT_L(0); PG8_BAR; PG8_MMA(1, 0, At, B0); PG8_MMA(1, 1, At, B1); PG8_BAR; PG8_SCHED;
;             PG8_LDB(B0, 1, 0); PG8_LDB(B1, 1, 1); PG8_SCHED; PG8_LDA(At, 1, 0); PG8_STAGE(PG8_SA(0, 1), a2 + hstepA, voffA);
;             PG8_WAIT_V(8); PG8_WAIT_L(0); PG8_BAR; PG8_MMA(0, 0, At, B0); PG8_MMA(0, 1, At, B1); PG8_BAR; PG8_SCHED;
	s_setprio 1
	s_waitcnt lgkmcnt(0)
	v_mfma_f32_16x16x32_bf16 v[62:65], v[130:133], v[162:165], v[62:65]
	v_mfma_f32_16x16x32_bf16 v[62:65], v[134:137], v[166:169], v[62:65]
	v_mfma_f32_16x16x32_bf16 v[46:49], v[134:137], v[174:177], v[46:49]
	v_mfma_f32_16x16x32_bf16 v[46:49], v[130:133], v[170:173], v[46:49]
	v_mfma_f32_16x16x32_bf16 v[30:33], v[130:133], v[198:201], v[30:33]
	v_mfma_f32_16x16x32_bf16 v[30:33], v[134:137], v[202:205], v[30:33]
	v_mfma_f32_16x16x32_bf16 v[14:17], v[134:137], v[216:219], v[14:17]
	v_mfma_f32_16x16x32_bf16 v[14:17], v[130:133], v[206:209], v[14:17]
	v_mfma_f32_16x16x32_bf16 v[10:13], v[138:141], v[206:209], v[10:13]
	v_mfma_f32_16x16x32_bf16 v[10:13], v[142:145], v[216:219], v[10:13]
	v_mfma_f32_16x16x32_bf16 v[26:29], v[142:145], v[202:205], v[26:29]
	v_mfma_f32_16x16x32_bf16 v[26:29], v[138:141], v[198:201], v[26:29]
	v_mfma_f32_16x16x32_bf16 v[42:45], v[138:141], v[170:173], v[42:45]
	v_mfma_f32_16x16x32_bf16 v[42:45], v[142:145], v[174:177], v[42:45]
	v_mfma_f32_16x16x32_bf16 v[58:61], v[142:145], v[166:169], v[58:61]
	v_mfma_f32_16x16x32_bf16 v[58:61], v[138:141], v[162:165], v[58:61]
	s_setprio 0
	s_setprio 1
	v_mfma_f32_16x16x32_bf16 v[50:53], v[154:157], v[162:165], v[50:53]
	v_mfma_f32_16x16x32_bf16 v[50:53], v[158:161], v[166:169], v[50:53]
	v_mfma_f32_16x16x32_bf16 v[34:37], v[158:161], v[174:177], v[34:37]
	v_mfma_f32_16x16x32_bf16 v[34:37], v[154:157], v[170:173], v[34:37]
	v_mfma_f32_16x16x32_bf16 v[18:21], v[154:157], v[198:201], v[18:21]
	v_mfma_f32_16x16x32_bf16 v[18:21], v[158:161], v[202:205], v[18:21]
	v_mfma_f32_16x16x32_bf16 v[2:5], v[158:161], v[216:219], v[2:5]
	v_mfma_f32_16x16x32_bf16 v[2:5], v[154:157], v[206:209], v[2:5]
	v_mfma_f32_16x16x32_bf16 v[6:9], v[146:149], v[206:209], v[6:9]
	v_mfma_f32_16x16x32_bf16 v[6:9], v[150:153], v[216:219], v[6:9]
	v_mfma_f32_16x16x32_bf16 v[22:25], v[150:153], v[202:205], v[22:25]
	v_mfma_f32_16x16x32_bf16 v[22:25], v[146:149], v[198:201], v[22:25]
	v_mfma_f32_16x16x32_bf16 v[38:41], v[146:149], v[170:173], v[38:41]
	v_mfma_f32_16x16x32_bf16 v[38:41], v[150:153], v[174:177], v[38:41]
	v_mfma_f32_16x16x32_bf16 v[54:57], v[150:153], v[166:169], v[54:57]
	v_mfma_f32_16x16x32_bf16 v[54:57], v[146:149], v[162:165], v[54:57]
	s_setprio 0
	s_barrier
	s_add_i32 s35, 0, 0x18000
	s_add_i32 s43, 0, 0x1c000
	v_add_u32_e32 v142, s35, v212
	v_add_u32_e32 v158, s43, v212
	ds_read_b128 v[130:133], v142
	ds_read_b128 v[134:137], v142 offset:1024
	ds_read_b128 v[138:141], v142 offset:2048
	ds_read_b128 v[142:145], v142 offset:3072
	ds_read_b128 v[146:149], v158
	ds_read_b128 v[150:153], v158 offset:1024
	ds_read_b128 v[154:157], v158 offset:2048
	ds_read_b128 v[158:161], v158 offset:3072
	s_add_u32 s36, s60, 0x100000
	s_addc_u32 s37, s61, 0
	s_mov_b32 m0, s12
	v_lshl_add_u64 v[228:229], s[36:37], 0, v[182:183]
	ds_read_b128 v[162:165], v215 offset:32768
	ds_read_b128 v[166:169], v215 offset:33792
	ds_read_b128 v[170:173], v215 offset:34816
	ds_read_b128 v[174:177], v215 offset:35840
	ds_read_b128 v[198:201], v215 offset:36864
	ds_read_b128 v[202:205], v215 offset:37888
	ds_read_b128 v[206:209], v215 offset:38912
	ds_read_b128 v[216:219], v215 offset:39936
	global_load_lds_dwordx4 v[228:229], off
	v_lshl_add_u64 v[228:229], s[36:37], 0, v[186:187]
	s_mov_b32 m0, s13
	s_nop 0
	global_load_lds_dwordx4 v[228:229], off
	s_waitcnt vmcnt(8)
	s_waitcnt lgkmcnt(0)
	s_barrier
	s_setprio 1
	s_waitcnt lgkmcnt(0)
	v_mfma_f32_16x16x32_bf16 v[126:129], v[130:133], v[162:165], v[126:129]
	v_mfma_f32_16x16x32_bf16 v[126:129], v[134:137], v[166:169], v[126:129]
	v_mfma_f32_16x16x32_bf16 v[110:113], v[134:137], v[174:177], v[110:113]
	v_mfma_f32_16x16x32_bf16 v[110:113], v[130:133], v[170:173], v[110:113]
	v_mfma_f32_16x16x32_bf16 v[94:97], v[130:133], v[198:201], v[94:97]
	v_mfma_f32_16x16x32_bf16 v[94:97], v[134:137], v[202:205], v[94:97]
	v_mfma_f32_16x16x32_bf16 v[78:81], v[134:137], v[216:219], v[78:81]
	v_mfma_f32_16x16x32_bf16 v[78:81], v[130:133], v[206:209], v[78:81]
	v_mfma_f32_16x16x32_bf16 v[74:77], v[138:141], v[206:209], v[74:77]
	v_mfma_f32_16x16x32_bf16 v[74:77], v[142:145], v[216:219], v[74:77]
	v_mfma_f32_16x16x32_bf16 v[90:93], v[142:145], v[202:205], v[90:93]
	v_mfma_f32_16x16x32_bf16 v[90:93], v[138:141], v[198:201], v[90:93]
	v_mfma_f32_16x16x32_bf16 v[106:109], v[138:141], v[170:173], v[106:109]
	v_mfma_f32_16x16x32_bf16 v[106:109], v[142:145], v[174:177], v[106:109]
	v_mfma_f32_16x16x32_bf16 v[122:125], v[142:145], v[166:169], v[122:125]
	v_mfma_f32_16x16x32_bf16 v[122:125], v[138:141], v[162:165], v[122:125]
	s_setprio 0
	s_setprio 1
	v_mfma_f32_16x16x32_bf16 v[114:117], v[154:157], v[162:165], v[114:117]
	v_mfma_f32_16x16x32_bf16 v[114:117], v[158:161], v[166:169], v[114:117]
	v_mfma_f32_16x16x32_bf16 v[98:101], v[158:161], v[174:177], v[98:101]
	v_mfma_f32_16x16x32_bf16 v[98:101], v[154:157], v[170:173], v[98:101]
	v_mfma_f32_16x16x32_bf16 v[82:85], v[154:157], v[198:201], v[82:85]
	v_mfma_f32_16x16x32_bf16 v[82:85], v[158:161], v[202:205], v[82:85]
	v_mfma_f32_16x16x32_bf16 v[66:69], v[158:161], v[216:219], v[66:69]
	v_mfma_f32_16x16x32_bf16 v[66:69], v[154:157], v[206:209], v[66:69]
	v_mfma_f32_16x16x32_bf16 v[70:73], v[146:149], v[206:209], v[70:73]
	v_mfma_f32_16x16x32_bf16 v[70:73], v[150:153], v[216:219], v[70:73]
	v_mfma_f32_16x16x32_bf16 v[86:89], v[150:153], v[202:205], v[86:89]
	v_mfma_f32_16x16x32_bf16 v[86:89], v[146:149], v[198:201], v[86:89]
	v_mfma_f32_16x16x32_bf16 v[102:105], v[146:149], v[170:173], v[102:105]
	v_mfma_f32_16x16x32_bf16 v[102:105], v[150:153], v[174:177], v[102:105]
	v_mfma_f32_16x16x32_bf16 v[118:121], v[150:153], v[166:169], v[118:121]
	v_mfma_f32_16x16x32_bf16 v[118:121], v[146:149], v[162:165], v[118:121]
	s_setprio 0
	s_barrier
; #define PG8_STAGE(bufoff, gbase, voff) do { _Pragma("unroll") for (int _i = 0; _i < 2; ++_i) \
;         __builtin_amdgcn_global_load_lds((const unsigned*)((const char*)(gbase) + (voff)[_i]), (PG8_LAS unsigned*)(lds + (bufoff) + ldsw + _i * 8192), 16, 0, 0); } while (0)
; #define PG8_LDA(dst, b, h) do { _Pragma("unroll") for (int m = 0; m < 4; ++m) _Pragma("unroll") for (int k = 0; k < 2; ++k) dst[m][k] = *(const PG8_LAS bf16x8*)(lds + PG8_SA(b, h) + aoff + m * 2048 + k * 1024); } while (0)
; #define PG8_MMA(ai, bj, At, Bt) do { __builtin_amdgcn_s_setprio(1); _Pragma("unroll") for (int m = 0; m < 4; ++m) _Pragma("unroll") for (int n = 0; n < 2; ++n) _Pragma("unroll") for (int k = 0; k < 2; ++k) \
;         acc[ai][bj][m][n] = mma16(Bt[n][k], At[m][k], acc[ai][bj][m][n]); __builtin_amdgcn_s_setprio(0); } while (0)
; #define PG8_WAIT_V(n) asm volatile("s_waitcnt vmcnt(" #n ")" ::: "memory")
; #define PG8_WAIT_L(n) asm volatile("s_waitcnt lgkmcnt(" #n ")" ::: "memory")
; #define PG8_BAR __builtin_amdgcn_s_barrier()
; #define PG8_SCHED __builtin_amdgcn_sched_barrier(0)
; template <class Epi, class Sched, bool ALIGN_EPI = false, bool SP2 = false>
; __device__ __forceinline__ void gemm_phase(PG8_LAS unsigned char* lds, const Gemm g, const Sched& S, const Epi& E) {
;     ...
;             PG8_LDA(At, 1, 1); PG8_STAGE(PG8_SB(1, 0), b3, voffB); PG8_STAGE(PG8_SB(1, 1), b3 + hstepB, voffB); PG8_STAGE(PG8_SA(1, 0), a3, voffA);
;             PG8_WAIT_V(8); PG8_WAIT_L(0); PG8_BAR; PG8_MMA(1, 0, At, B0); PG8_MMA(1, 1, At, B1); PG8_BAR; PG8_SCHED;
;     ...
;         if constexpr (ALIGN_EPI) { if (wr == 0) PG8_BAR; }
	s_add_i32 s35, s35, s7
	v_lshl_add_u64 v[220:221], v[220:221], 0, s[38:39]
	s_mov_b32 m0, s35
	ds_read_b128 v[162:165], v215 offset:49152
	ds_read_b128 v[166:169], v215 offset:50176
	ds_read_b128 v[170:173], v215 offset:51200
	ds_read_b128 v[174:177], v215 offset:52224
	ds_read_b128 v[198:201], v215 offset:53248
	ds_read_b128 v[202:205], v215 offset:54272
	ds_read_b128 v[206:209], v215 offset:55296
	ds_read_b128 v[216:219], v215 offset:56320
	global_load_lds_dwordx4 v[220:221], off
	s_add_i32 m0, s35, 0x2000
	s_add_u32 s36, s58, 0x100080
	v_lshl_add_u64 v[220:221], v[222:223], 0, s[38:39]
	s_addc_u32 s37, s59, 0
	s_add_i32 s35, s43, s7
	global_load_lds_dwordx4 v[220:221], off
	v_lshl_add_u64 v[220:221], s[36:37], 0, v[184:185]
	s_mov_b32 m0, s35
	s_nop 0
	global_load_lds_dwordx4 v[220:221], off
	v_lshl_add_u64 v[220:221], s[36:37], 0, v[188:189]
	s_add_i32 m0, s35, 0x2000
	s_nop 0
	global_load_lds_dwordx4 v[220:221], off
	v_lshl_add_u64 v[220:221], v[224:225], 0, s[38:39]
	s_mov_b32 m0, s17
	s_nop 0
	global_load_lds_dwordx4 v[220:221], off
	v_lshl_add_u64 v[220:221], v[226:227], 0, s[38:39]
	s_mov_b32 m0, s18
	s_nop 0
	global_load_lds_dwordx4 v[220:221], off
	s_waitcnt vmcnt(8)
	s_waitcnt lgkmcnt(0)
	s_barrier
	s_setprio 1
	s_waitcnt lgkmcnt(0)
	v_mfma_f32_16x16x32_bf16 v[62:65], v[130:133], v[162:165], v[62:65]
	v_mfma_f32_16x16x32_bf16 v[62:65], v[134:137], v[166:169], v[62:65]
	v_mfma_f32_16x16x32_bf16 v[46:49], v[134:137], v[174:177], v[46:49]
	v_mfma_f32_16x16x32_bf16 v[46:49], v[130:133], v[170:173], v[46:49]
	v_mfma_f32_16x16x32_bf16 v[30:33], v[130:133], v[198:201], v[30:33]
	v_mfma_f32_16x16x32_bf16 v[30:33], v[134:137], v[202:205], v[30:33]
	v_mfma_f32_16x16x32_bf16 v[14:17], v[134:137], v[216:219], v[14:17]
	v_mfma_f32_16x16x32_bf16 v[14:17], v[130:133], v[206:209], v[14:17]
	v_mfma_f32_16x16x32_bf16 v[10:13], v[138:141], v[206:209], v[10:13]
	v_mfma_f32_16x16x32_bf16 v[10:13], v[142:145], v[216:219], v[10:13]
	v_mfma_f32_16x16x32_bf16 v[26:29], v[142:145], v[202:205], v[26:29]
	v_mfma_f32_16x16x32_bf16 v[26:29], v[138:141], v[198:201], v[26:29]
	v_mfma_f32_16x16x32_bf16 v[42:45], v[138:141], v[170:173], v[42:45]
	v_mfma_f32_16x16x32_bf16 v[42:45], v[142:145], v[174:177], v[42:45]
	v_mfma_f32_16x16x32_bf16 v[58:61], v[142:145], v[166:169], v[58:61]
	v_mfma_f32_16x16x32_bf16 v[58:61], v[138:141], v[162:165], v[58:61]
	s_setprio 0
	s_setprio 1
	v_mfma_f32_16x16x32_bf16 v[50:53], v[154:157], v[162:165], v[50:53]
	v_mfma_f32_16x16x32_bf16 v[50:53], v[158:161], v[166:169], v[50:53]
	v_mfma_f32_16x16x32_bf16 v[34:37], v[158:161], v[174:177], v[34:37]
	v_mfma_f32_16x16x32_bf16 v[34:37], v[154:157], v[170:173], v[34:37]
	v_mfma_f32_16x16x32_bf16 v[18:21], v[154:157], v[198:201], v[18:21]
	v_mfma_f32_16x16x32_bf16 v[18:21], v[158:161], v[202:205], v[18:21]
	v_mfma_f32_16x16x32_bf16 v[2:5], v[158:161], v[216:219], v[2:5]
	v_mfma_f32_16x16x32_bf16 v[2:5], v[154:157], v[206:209], v[2:5]
	v_mfma_f32_16x16x32_bf16 v[6:9], v[146:149], v[206:209], v[6:9]
	v_mfma_f32_16x16x32_bf16 v[6:9], v[150:153], v[216:219], v[6:9]
	v_mfma_f32_16x16x32_bf16 v[22:25], v[150:153], v[202:205], v[22:25]
	v_mfma_f32_16x16x32_bf16 v[22:25], v[146:149], v[198:201], v[22:25]
	v_mfma_f32_16x16x32_bf16 v[38:41], v[146:149], v[170:173], v[38:41]
	v_mfma_f32_16x16x32_bf16 v[38:41], v[150:153], v[174:177], v[38:41]
	v_mfma_f32_16x16x32_bf16 v[54:57], v[150:153], v[166:169], v[54:57]
	v_mfma_f32_16x16x32_bf16 v[54:57], v[146:149], v[162:165], v[54:57]
	s_setprio 0
	s_barrier
	s_add_i32 s33, s33, 2
	s_add_u32 s56, s56, 0x100
	s_addc_u32 s57, s57, 0
	s_add_u32 s28, s28, 0x100
	s_addc_u32 s29, s29, 0
	s_cmp_gt_u32 s33, 61
	s_cbranch_scc0 .LBB0_579
	s_and_b64 vcc, exec, s[40:41]
	s_cbranch_vccz .LBB0_582
	s_barrier

; #define PG8_STAGE(bufoff, gbase, voff) do { _Pragma("unroll") for (int _i = 0; _i < 2; ++_i) \
;         __builtin_amdgcn_global_load_lds((const unsigned*)((const char*)(gbase) + (voff)[_i]), (PG8_LAS unsigned*)(lds + (bufoff) + ldsw + _i * 8192), 16, 0, 0); } while (0)
; #define PG8_LDA(dst, b, h) do { _Pragma("unroll") for (int m = 0; m < 4; ++m) _Pragma("unroll") for (int k = 0; k < 2; ++k) dst[m][k] = *(const PG8_LAS bf16x8*)(lds + PG8_SA(b, h) + aoff + m * 2048 + k * 1024); } while (0)
; #define PG8_LDB(dst, b, h) do { _Pragma("unroll") for (int n = 0; n < 2; ++n) _Pragma("unroll") for (int k = 0; k < 2; ++k) dst[n][k] = *(const PG8_LAS bf16x8*)(lds + PG8_SB(b, h) + boff + n * 2048 + k * 1024); } while (0)
; #define PG8_MMA(ai, bj, At, Bt) do { __builtin_amdgcn_s_setprio(1); _Pragma("unroll") for (int m = 0; m < 4; ++m) _Pragma("unroll") for (int n = 0; n < 2; ++n) _Pragma("unroll") for (int k = 0; k < 2; ++k) \
;         acc[ai][bj][m][n] = mma16(Bt[n][k], At[m][k], acc[ai][bj][m][n]); __builtin_amdgcn_s_setprio(0); } while (0)
; #define PG8_WAIT_V(n) asm volatile("s_waitcnt vmcnt(" #n ")" ::: "memory")
; #define PG8_WAIT_L(n) asm volatile("s_waitcnt lgkmcnt(" #n ")" ::: "memory")
; #define PG8_BAR __builtin_amdgcn_s_barrier()
; #define PG8_SCHED __builtin_amdgcn_sched_barrier(0)
; template <class Epi, class Sched, bool ALIGN_EPI = false, bool SP2 = false>
; __device__ __forceinline__ void gemm_phase(PG8_LAS unsigned char* lds, const Gemm g, const Sched& S, const Epi& E) {
;     ...
;             const bool last = (t == nt - 2);
;             const char* a1 = cA + (size_t)(t + 1) * kstep;
;             const char* a2 = last ? nA : cA + (size_t)(t + 2) * kstep; const char* b2 = last ? nB : cB + (size_t)(t + 2) * kstep;
;             const char* a3 = a2 + kstep; const char* b3 = b2 + kstep;
;             if (last && has_next) S.a_ready(nxt);
;             if constexpr (SP2) {
;             PG8_LDB(B0, 0, 0); PG8_LDB(B1, 0, 1); PG8_SCHED; PG8_LDA(At, 0, 0); PG8_STAGE(PG8_SA(1, 1), a1 + hstepA, voffA);
;             PG8_WAIT_V(8); PG8_WAIT_L(0); PG8_BAR; PG8_MMA(0, 0, At, B0); PG8_MMA(0, 1, At, B1); PG8_BAR; PG8_SCHED;
;             PG8_LDA(At, 0, 1); PG8_STAGE(PG8_SB(0, 0), b2, voffB); PG8_STAGE(PG8_SB(0, 1), b2 + hstepB, voffB); PG8_STAGE(PG8_SA(0, 0), a2, voffA);
.LBB0_660:
	ds_read_b128 v[154:157], v150
	ds_read_b128 v[158:161], v150 offset:1024
	ds_read_b128 v[162:165], v150 offset:2048
	ds_read_b128 v[166:169], v150 offset:3072
	ds_read_b128 v[170:173], v151
	ds_read_b128 v[174:177], v151 offset:1024
	ds_read_b128 v[182:185], v151 offset:2048
	ds_read_b128 v[186:189], v151 offset:3072
	s_add_u32 s36, s0, 0xfff00080
	s_addc_u32 s37, s1, -1
	s_cmp_eq_u32 s35, 60
	s_cselect_b32 s67, s59, s37
	s_cselect_b32 s66, s58, s36
	s_cselect_b32 s65, s27, s33
	s_cselect_b32 s64, s28, s29
	v_lshl_add_u64 v[146:147], s[0:1], 0, v[138:139]
	s_add_i32 m0, s8, 0xc000
	ds_read_b128 v[190:193], v152
	ds_read_b128 v[194:197], v152 offset:1024
	ds_read_b128 v[198:201], v152 offset:2048
	ds_read_b128 v[202:205], v152 offset:3072
	ds_read_b128 v[206:209], v152 offset:4096
	ds_read_b128 v[212:215], v152 offset:5120
	ds_read_b128 v[216:219], v152 offset:6144
	ds_read_b128 v[220:223], v152 offset:7168
	global_load_lds_dwordx4 v[146:147], off
	v_lshl_add_u64 v[146:147], s[0:1], 0, v[140:141]
	s_add_i32 m0, s8, 0xe000
	s_nop 0
	global_load_lds_dwordx4 v[146:147], off
	s_waitcnt vmcnt(8)
	s_waitcnt lgkmcnt(0)
	s_barrier
	s_setprio 1
	s_waitcnt lgkmcnt(0)
	v_mfma_f32_16x16x32_bf16 v[126:129], v[154:157], v[190:193], v[126:129]
	v_mfma_f32_16x16x32_bf16 v[126:129], v[158:161], v[194:197], v[126:129]
	v_mfma_f32_16x16x32_bf16 v[118:121], v[158:161], v[202:205], v[118:121]
	v_mfma_f32_16x16x32_bf16 v[118:121], v[154:157], v[198:201], v[118:121]
	v_mfma_f32_16x16x32_bf16 v[102:105], v[154:157], v[206:209], v[102:105]
	v_mfma_f32_16x16x32_bf16 v[102:105], v[158:161], v[212:215], v[102:105]
	v_mfma_f32_16x16x32_bf16 v[86:89], v[158:161], v[220:223], v[86:89]
	v_mfma_f32_16x16x32_bf16 v[86:89], v[154:157], v[216:219], v[86:89]
	v_mfma_f32_16x16x32_bf16 v[78:81], v[162:165], v[216:219], v[78:81]
	v_mfma_f32_16x16x32_bf16 v[78:81], v[166:169], v[220:223], v[78:81]
	v_mfma_f32_16x16x32_bf16 v[94:97], v[166:169], v[212:215], v[94:97]
	v_mfma_f32_16x16x32_bf16 v[94:97], v[162:165], v[206:209], v[94:97]
	v_mfma_f32_16x16x32_bf16 v[110:113], v[162:165], v[198:201], v[110:113]
	v_mfma_f32_16x16x32_bf16 v[110:113], v[166:169], v[202:205], v[110:113]
	v_mfma_f32_16x16x32_bf16 v[122:125], v[166:169], v[194:197], v[122:125]
	v_mfma_f32_16x16x32_bf16 v[122:125], v[162:165], v[190:193], v[122:125]
	s_setprio 0
	s_setprio 1
	v_mfma_f32_16x16x32_bf16 v[106:109], v[182:185], v[190:193], v[106:109]
	v_mfma_f32_16x16x32_bf16 v[106:109], v[186:189], v[194:197], v[106:109]
	v_mfma_f32_16x16x32_bf16 v[90:93], v[186:189], v[202:205], v[90:93]
	v_mfma_f32_16x16x32_bf16 v[90:93], v[182:185], v[198:201], v[90:93]
	v_mfma_f32_16x16x32_bf16 v[74:77], v[182:185], v[206:209], v[74:77]
	v_mfma_f32_16x16x32_bf16 v[74:77], v[186:189], v[212:215], v[74:77]
	v_mfma_f32_16x16x32_bf16 v[66:69], v[186:189], v[220:223], v[66:69]
	v_mfma_f32_16x16x32_bf16 v[66:69], v[182:185], v[216:219], v[66:69]
	v_mfma_f32_16x16x32_bf16 v[70:73], v[170:173], v[216:219], v[70:73]
	v_mfma_f32_16x16x32_bf16 v[70:73], v[174:177], v[220:223], v[70:73]
	v_mfma_f32_16x16x32_bf16 v[82:85], v[174:177], v[212:215], v[82:85]
	v_mfma_f32_16x16x32_bf16 v[82:85], v[170:173], v[206:209], v[82:85]
	v_mfma_f32_16x16x32_bf16 v[98:101], v[170:173], v[198:201], v[98:101]
	v_mfma_f32_16x16x32_bf16 v[98:101], v[174:177], v[202:205], v[98:101]
	v_mfma_f32_16x16x32_bf16 v[114:117], v[174:177], v[194:197], v[114:117]
	v_mfma_f32_16x16x32_bf16 v[114:117], v[170:173], v[190:193], v[114:117]
	s_setprio 0
	s_barrier
	s_add_i32 s36, s20, s7
	v_lshl_add_u64 v[146:147], s[64:65], 0, v[132:133]
	s_mov_b32 m0, s36
	ds_read_b128 v[190:193], v152 offset:16384
	ds_read_b128 v[194:197], v152 offset:17408
	ds_read_b128 v[198:201], v152 offset:18432
	ds_read_b128 v[202:205], v152 offset:19456
	ds_read_b128 v[206:209], v152 offset:20480
	ds_read_b128 v[212:215], v152 offset:21504
	ds_read_b128 v[216:219], v152 offset:22528
	ds_read_b128 v[220:223], v152 offset:23552
	global_load_lds_dwordx4 v[146:147], off
	s_add_i32 m0, s36, 0x2000
	s_add_u32 s36, s64, 0x100000
	v_lshl_add_u64 v[224:225], s[64:65], 0, v[136:137]
	s_addc_u32 s37, s65, 0
	s_add_i32 s46, s21, s7
	global_load_lds_dwordx4 v[224:225], off
	v_lshl_add_u64 v[226:227], s[36:37], 0, v[132:133]
	s_mov_b32 m0, s46
	v_lshl_add_u64 v[228:229], s[66:67], 0, v[134:135]
	global_load_lds_dwordx4 v[226:227], off
	v_lshl_add_u64 v[226:227], s[36:37], 0, v[136:137]
	s_add_i32 m0, s46, 0x2000
	s_nop 0
	global_load_lds_dwordx4 v[226:227], off
	v_lshl_add_u64 v[226:227], s[66:67], 0, v[130:131]
	s_mov_b32 m0, s8
	s_nop 0
	global_load_lds_dwordx4 v[226:227], off
	s_mov_b32 m0, s11
	s_nop 0
	global_load_lds_dwordx4 v[228:229], off
	s_waitcnt vmcnt(8)
	s_waitcnt lgkmcnt(0)
	s_barrier
; #define PG8_STAGE(bufoff, gbase, voff) do { _Pragma("unroll") for (int _i = 0; _i < 2; ++_i) \
;         __builtin_amdgcn_global_load_lds((const unsigned*)((const char*)(gbase) + (voff)[_i]), (PG8_LAS unsigned*)(lds + (bufoff) + ldsw + _i * 8192), 16, 0, 0); } while (0)
; #define PG8_LDA(dst, b, h) do { _Pragma("unroll") for (int m = 0; m < 4; ++m) _Pragma("unroll") for (int k = 0; k < 2; ++k) dst[m][k] = *(const PG8_LAS bf16x8*)(lds + PG8_SA(b, h) + aoff + m * 2048 + k * 1024); } while (0)
; #define PG8_LDB(dst, b, h) do { _Pragma("unroll") for (int n = 0; n < 2; ++n) _Pragma("unroll") for (int k = 0; k < 2; ++k) dst[n][k] = *(const PG8_LAS bf16x8*)(lds + PG8_SB(b, h) + boff + n * 2048 + k * 1024); } while (0)
; #define PG8_MMA(ai, bj, At, Bt) do { __builtin_amdgcn_s_setprio(1); _Pragma("unroll") for (int m = 0; m < 4; ++m) _Pragma("unroll") for (int n = 0; n < 2; ++n) _Pragma("unroll") for (int k = 0; k < 2; ++k) \
;         acc[ai][bj][m][n] = mma16(Bt[n][k], At[m][k], acc[ai][bj][m][n]); __builtin_amdgcn_s_setprio(0); } while (0)
; #define PG8_WAIT_V(n) asm volatile("s_waitcnt vmcnt(" #n ")" ::: "memory")
; #define PG8_WAIT_L(n) asm volatile("s_waitcnt lgkmcnt(" #n ")" ::: "memory")
; #define PG8_BAR __builtin_amdgcn_s_barrier()
; #define PG8_SCHED __builtin_amdgcn_sched_barrier(0)
; template <class Epi, class Sched, bool ALIGN_EPI = false, bool SP2 = false>
; __device__ __forceinline__ void gemm_phase(PG8_LAS unsigned char* lds, const Gemm g, const Sched& S, const Epi& E) {
;     ...
;             PG8_WAIT_V(8); PG8_WAIT_L(0); PG8_BAR; PG8_MMA(1, 0, At, B0); PG8_MMA(1, 1, At, B1); PG8_BAR; PG8_SCHED;
;             PG8_LDB(B0, 1, 0); PG8_LDB(B1, 1, 1); PG8_SCHED; PG8_LDA(At, 1, 0); PG8_STAGE(PG8_SA(0, 1), a2 + hstepA, voffA);
;             PG8_WAIT_V(8); PG8_WAIT_L(0); PG8_BAR; PG8_MMA(0, 0, At, B0); PG8_MMA(0, 1, At, B1); PG8_BAR; PG8_SCHED;
	s_setprio 1
	s_waitcnt lgkmcnt(0)
	v_mfma_f32_16x16x32_bf16 v[62:65], v[154:157], v[190:193], v[62:65]
	v_mfma_f32_16x16x32_bf16 v[62:65], v[158:161], v[194:197], v[62:65]
	v_mfma_f32_16x16x32_bf16 v[54:57], v[158:161], v[202:205], v[54:57]
	v_mfma_f32_16x16x32_bf16 v[54:57], v[154:157], v[198:201], v[54:57]
	v_mfma_f32_16x16x32_bf16 v[38:41], v[154:157], v[206:209], v[38:41]
	v_mfma_f32_16x16x32_bf16 v[38:41], v[158:161], v[212:215], v[38:41]
	v_mfma_f32_16x16x32_bf16 v[22:25], v[158:161], v[220:223], v[22:25]
	v_mfma_f32_16x16x32_bf16 v[22:25], v[154:157], v[216:219], v[22:25]
	v_mfma_f32_16x16x32_bf16 v[14:17], v[162:165], v[216:219], v[14:17]
	v_mfma_f32_16x16x32_bf16 v[14:17], v[166:169], v[220:223], v[14:17]
	v_mfma_f32_16x16x32_bf16 v[30:33], v[166:169], v[212:215], v[30:33]
	v_mfma_f32_16x16x32_bf16 v[30:33], v[162:165], v[206:209], v[30:33]
	v_mfma_f32_16x16x32_bf16 v[46:49], v[162:165], v[198:201], v[46:49]
	v_mfma_f32_16x16x32_bf16 v[46:49], v[166:169], v[202:205], v[46:49]
	v_mfma_f32_16x16x32_bf16 v[58:61], v[166:169], v[194:197], v[58:61]
	v_mfma_f32_16x16x32_bf16 v[58:61], v[162:165], v[190:193], v[58:61]
	s_setprio 0
	s_setprio 1
	v_mfma_f32_16x16x32_bf16 v[42:45], v[182:185], v[190:193], v[42:45]
	v_mfma_f32_16x16x32_bf16 v[42:45], v[186:189], v[194:197], v[42:45]
	v_mfma_f32_16x16x32_bf16 v[26:29], v[186:189], v[202:205], v[26:29]
	v_mfma_f32_16x16x32_bf16 v[26:29], v[182:185], v[198:201], v[26:29]
	v_mfma_f32_16x16x32_bf16 v[10:13], v[182:185], v[206:209], v[10:13]
	v_mfma_f32_16x16x32_bf16 v[10:13], v[186:189], v[212:215], v[10:13]
	v_mfma_f32_16x16x32_bf16 v[2:5], v[186:189], v[220:223], v[2:5]
	v_mfma_f32_16x16x32_bf16 v[2:5], v[182:185], v[216:219], v[2:5]
	v_mfma_f32_16x16x32_bf16 v[6:9], v[170:173], v[216:219], v[6:9]
	v_mfma_f32_16x16x32_bf16 v[6:9], v[174:177], v[220:223], v[6:9]
	v_mfma_f32_16x16x32_bf16 v[18:21], v[174:177], v[212:215], v[18:21]
	v_mfma_f32_16x16x32_bf16 v[18:21], v[170:173], v[206:209], v[18:21]
	v_mfma_f32_16x16x32_bf16 v[34:37], v[170:173], v[198:201], v[34:37]
	v_mfma_f32_16x16x32_bf16 v[34:37], v[174:177], v[202:205], v[34:37]
	v_mfma_f32_16x16x32_bf16 v[50:53], v[174:177], v[194:197], v[50:53]
	v_mfma_f32_16x16x32_bf16 v[50:53], v[170:173], v[190:193], v[50:53]
	s_setprio 0
	s_barrier
	s_add_i32 s46, 0, 0x18000
	v_add_u32_e32 v153, s46, v148
	s_add_i32 s47, 0, 0x1c000
	ds_read_b128 v[154:157], v153
	ds_read_b128 v[158:161], v153 offset:1024
	ds_read_b128 v[162:165], v153 offset:2048
	ds_read_b128 v[166:169], v153 offset:3072
	v_add_u32_e32 v153, s47, v148
	ds_read_b128 v[170:173], v153
	ds_read_b128 v[174:177], v153 offset:1024
	ds_read_b128 v[182:185], v153 offset:2048
	ds_read_b128 v[186:189], v153 offset:3072
	s_add_u32 s36, s66, 0x100000
	s_addc_u32 s37, s67, 0
	s_mov_b32 m0, s12
	v_lshl_add_u64 v[230:231], s[36:37], 0, v[130:131]
	ds_read_b128 v[190:193], v152 offset:32768
	ds_read_b128 v[194:197], v152 offset:33792
	ds_read_b128 v[198:201], v152 offset:34816
	ds_read_b128 v[202:205], v152 offset:35840
	ds_read_b128 v[206:209], v152 offset:36864
	ds_read_b128 v[212:215], v152 offset:37888
	ds_read_b128 v[216:219], v152 offset:38912
	ds_read_b128 v[220:223], v152 offset:39936
	global_load_lds_dwordx4 v[230:231], off
	v_lshl_add_u64 v[230:231], s[36:37], 0, v[134:135]
	s_mov_b32 m0, s13
	s_nop 0
	global_load_lds_dwordx4 v[230:231], off
	s_waitcnt vmcnt(8)
	s_waitcnt lgkmcnt(0)
	s_barrier
	s_setprio 1
	s_waitcnt lgkmcnt(0)
	v_mfma_f32_16x16x32_bf16 v[126:129], v[154:157], v[190:193], v[126:129]
	v_mfma_f32_16x16x32_bf16 v[126:129], v[158:161], v[194:197], v[126:129]
	v_mfma_f32_16x16x32_bf16 v[118:121], v[158:161], v[202:205], v[118:121]
	v_mfma_f32_16x16x32_bf16 v[118:121], v[154:157], v[198:201], v[118:121]
	v_mfma_f32_16x16x32_bf16 v[102:105], v[154:157], v[206:209], v[102:105]
	v_mfma_f32_16x16x32_bf16 v[102:105], v[158:161], v[212:215], v[102:105]
	v_mfma_f32_16x16x32_bf16 v[86:89], v[158:161], v[220:223], v[86:89]
	v_mfma_f32_16x16x32_bf16 v[86:89], v[154:157], v[216:219], v[86:89]
	v_mfma_f32_16x16x32_bf16 v[78:81], v[162:165], v[216:219], v[78:81]
	v_mfma_f32_16x16x32_bf16 v[78:81], v[166:169], v[220:223], v[78:81]
	v_mfma_f32_16x16x32_bf16 v[94:97], v[166:169], v[212:215], v[94:97]
	v_mfma_f32_16x16x32_bf16 v[94:97], v[162:165], v[206:209], v[94:97]
	v_mfma_f32_16x16x32_bf16 v[110:113], v[162:165], v[198:201], v[110:113]
	v_mfma_f32_16x16x32_bf16 v[110:113], v[166:169], v[202:205], v[110:113]
	v_mfma_f32_16x16x32_bf16 v[122:125], v[166:169], v[194:197], v[122:125]
	v_mfma_f32_16x16x32_bf16 v[122:125], v[162:165], v[190:193], v[122:125]
	s_setprio 0
	s_setprio 1
	v_mfma_f32_16x16x32_bf16 v[106:109], v[182:185], v[190:193], v[106:109]
	v_mfma_f32_16x16x32_bf16 v[106:109], v[186:189], v[194:197], v[106:109]
	v_mfma_f32_16x16x32_bf16 v[90:93], v[186:189], v[202:205], v[90:93]
	v_mfma_f32_16x16x32_bf16 v[90:93], v[182:185], v[198:201], v[90:93]
	v_mfma_f32_16x16x32_bf16 v[74:77], v[182:185], v[206:209], v[74:77]
	v_mfma_f32_16x16x32_bf16 v[74:77], v[186:189], v[212:215], v[74:77]
	v_mfma_f32_16x16x32_bf16 v[66:69], v[186:189], v[220:223], v[66:69]
	v_mfma_f32_16x16x32_bf16 v[66:69], v[182:185], v[216:219], v[66:69]
	v_mfma_f32_16x16x32_bf16 v[70:73], v[170:173], v[216:219], v[70:73]
	v_mfma_f32_16x16x32_bf16 v[70:73], v[174:177], v[220:223], v[70:73]
	v_mfma_f32_16x16x32_bf16 v[82:85], v[174:177], v[212:215], v[82:85]
	v_mfma_f32_16x16x32_bf16 v[82:85], v[170:173], v[206:209], v[82:85]
	v_mfma_f32_16x16x32_bf16 v[98:101], v[170:173], v[198:201], v[98:101]
	v_mfma_f32_16x16x32_bf16 v[98:101], v[174:177], v[202:205], v[98:101]
	v_mfma_f32_16x16x32_bf16 v[114:117], v[174:177], v[194:197], v[114:117]
	v_mfma_f32_16x16x32_bf16 v[114:117], v[170:173], v[190:193], v[114:117]
	s_setprio 0
	s_barrier
; #define PG8_STAGE(bufoff, gbase, voff) do { _Pragma("unroll") for (int _i = 0; _i < 2; ++_i) \
;         __builtin_amdgcn_global_load_lds((const unsigned*)((const char*)(gbase) + (voff)[_i]), (PG8_LAS unsigned*)(lds + (bufoff) + ldsw + _i * 8192), 16, 0, 0); } while (0)
; #define PG8_LDA(dst, b, h) do { _Pragma("unroll") for (int m = 0; m < 4; ++m) _Pragma("unroll") for (int k = 0; k < 2; ++k) dst[m][k] = *(const PG8_LAS bf16x8*)(lds + PG8_SA(b, h) + aoff + m * 2048 + k * 1024); } while (0)
; #define PG8_MMA(ai, bj, At, Bt) do { __builtin_amdgcn_s_setprio(1); _Pragma("unroll") for (int m = 0; m < 4; ++m) _Pragma("unroll") for (int n = 0; n < 2; ++n) _Pragma("unroll") for (int k = 0; k < 2; ++k) \
;         acc[ai][bj][m][n] = mma16(Bt[n][k], At[m][k], acc[ai][bj][m][n]); __builtin_amdgcn_s_setprio(0); } while (0)
; #define PG8_WAIT_V(n) asm volatile("s_waitcnt vmcnt(" #n ")" ::: "memory")
; #define PG8_WAIT_L(n) asm volatile("s_waitcnt lgkmcnt(" #n ")" ::: "memory")
; #define PG8_BAR __builtin_amdgcn_s_barrier()
; #define PG8_SCHED __builtin_amdgcn_sched_barrier(0)
; template <class Epi, class Sched, bool ALIGN_EPI = false, bool SP2 = false>
; __device__ __forceinline__ void gemm_phase(PG8_LAS unsigned char* lds, const Gemm g, const Sched& S, const Epi& E) {
;     ...
;             PG8_LDA(At, 1, 1); PG8_STAGE(PG8_SB(1, 0), b3, voffB); PG8_STAGE(PG8_SB(1, 1), b3 + hstepB, voffB); PG8_STAGE(PG8_SA(1, 0), a3, voffA);
;             PG8_WAIT_V(8); PG8_WAIT_L(0); PG8_BAR; PG8_MMA(1, 0, At, B0); PG8_MMA(1, 1, At, B1); PG8_BAR; PG8_SCHED;
;     ...
;         if constexpr (ALIGN_EPI) { if (wr == 0) PG8_BAR; }
	s_add_i32 s36, s46, s7
	v_lshl_add_u64 v[146:147], v[146:147], 0, s[40:41]
	s_mov_b32 m0, s36
	ds_read_b128 v[190:193], v152 offset:49152
	ds_read_b128 v[194:197], v152 offset:50176
	ds_read_b128 v[198:201], v152 offset:51200
	ds_read_b128 v[202:205], v152 offset:52224
	ds_read_b128 v[206:209], v152 offset:53248
	ds_read_b128 v[212:215], v152 offset:54272
	ds_read_b128 v[216:219], v152 offset:55296
	ds_read_b128 v[220:223], v152 offset:56320
	global_load_lds_dwordx4 v[146:147], off
	s_add_i32 m0, s36, 0x2000
	s_add_u32 s36, s64, 0x100080
	v_lshl_add_u64 v[146:147], v[224:225], 0, s[40:41]
	s_addc_u32 s37, s65, 0
	s_add_i32 s46, s47, s7
	global_load_lds_dwordx4 v[146:147], off
	v_lshl_add_u64 v[146:147], s[36:37], 0, v[132:133]
	s_mov_b32 m0, s46
	s_nop 0
	global_load_lds_dwordx4 v[146:147], off
	v_lshl_add_u64 v[146:147], s[36:37], 0, v[136:137]
	s_add_i32 m0, s46, 0x2000
	s_nop 0
	global_load_lds_dwordx4 v[146:147], off
	v_lshl_add_u64 v[146:147], v[226:227], 0, s[40:41]
	s_mov_b32 m0, s17
	s_nop 0
	global_load_lds_dwordx4 v[146:147], off
	v_lshl_add_u64 v[146:147], v[228:229], 0, s[40:41]
	s_mov_b32 m0, s18
	s_nop 0
	global_load_lds_dwordx4 v[146:147], off
	s_waitcnt vmcnt(8)
	s_waitcnt lgkmcnt(0)
	s_barrier
	s_setprio 1
	s_waitcnt lgkmcnt(0)
	v_mfma_f32_16x16x32_bf16 v[62:65], v[154:157], v[190:193], v[62:65]
	v_mfma_f32_16x16x32_bf16 v[62:65], v[158:161], v[194:197], v[62:65]
	v_mfma_f32_16x16x32_bf16 v[54:57], v[158:161], v[202:205], v[54:57]
	v_mfma_f32_16x16x32_bf16 v[54:57], v[154:157], v[198:201], v[54:57]
	v_mfma_f32_16x16x32_bf16 v[38:41], v[154:157], v[206:209], v[38:41]
	v_mfma_f32_16x16x32_bf16 v[38:41], v[158:161], v[212:215], v[38:41]
	v_mfma_f32_16x16x32_bf16 v[22:25], v[158:161], v[220:223], v[22:25]
	v_mfma_f32_16x16x32_bf16 v[22:25], v[154:157], v[216:219], v[22:25]
	v_mfma_f32_16x16x32_bf16 v[14:17], v[162:165], v[216:219], v[14:17]
	v_mfma_f32_16x16x32_bf16 v[14:17], v[166:169], v[220:223], v[14:17]
	v_mfma_f32_16x16x32_bf16 v[30:33], v[166:169], v[212:215], v[30:33]
	v_mfma_f32_16x16x32_bf16 v[30:33], v[162:165], v[206:209], v[30:33]
	v_mfma_f32_16x16x32_bf16 v[46:49], v[162:165], v[198:201], v[46:49]
	v_mfma_f32_16x16x32_bf16 v[46:49], v[166:169], v[202:205], v[46:49]
	v_mfma_f32_16x16x32_bf16 v[58:61], v[166:169], v[194:197], v[58:61]
	v_mfma_f32_16x16x32_bf16 v[58:61], v[162:165], v[190:193], v[58:61]
	s_setprio 0
	s_setprio 1
	v_mfma_f32_16x16x32_bf16 v[42:45], v[182:185], v[190:193], v[42:45]
	v_mfma_f32_16x16x32_bf16 v[42:45], v[186:189], v[194:197], v[42:45]
	v_mfma_f32_16x16x32_bf16 v[26:29], v[186:189], v[202:205], v[26:29]
	v_mfma_f32_16x16x32_bf16 v[26:29], v[182:185], v[198:201], v[26:29]
	v_mfma_f32_16x16x32_bf16 v[10:13], v[182:185], v[206:209], v[10:13]
	v_mfma_f32_16x16x32_bf16 v[10:13], v[186:189], v[212:215], v[10:13]
	v_mfma_f32_16x16x32_bf16 v[2:5], v[186:189], v[220:223], v[2:5]
	v_mfma_f32_16x16x32_bf16 v[2:5], v[182:185], v[216:219], v[2:5]
	v_mfma_f32_16x16x32_bf16 v[6:9], v[170:173], v[216:219], v[6:9]
	v_mfma_f32_16x16x32_bf16 v[6:9], v[174:177], v[220:223], v[6:9]
	v_mfma_f32_16x16x32_bf16 v[18:21], v[174:177], v[212:215], v[18:21]
	v_mfma_f32_16x16x32_bf16 v[18:21], v[170:173], v[206:209], v[18:21]
	v_mfma_f32_16x16x32_bf16 v[34:37], v[170:173], v[198:201], v[34:37]
	v_mfma_f32_16x16x32_bf16 v[34:37], v[174:177], v[202:205], v[34:37]
	v_mfma_f32_16x16x32_bf16 v[50:53], v[174:177], v[194:197], v[50:53]
	v_mfma_f32_16x16x32_bf16 v[50:53], v[170:173], v[190:193], v[50:53]
	s_setprio 0
	s_barrier
	s_add_i32 s35, s35, 2
	s_add_u32 s0, s0, 0x100
	s_addc_u32 s1, s1, 0
	s_add_u32 s29, s29, 0x100
	s_addc_u32 s33, s33, 0
	s_cmp_gt_u32 s35, 61
	s_cbranch_scc0 .LBB0_660
	s_and_b64 vcc, exec, s[42:43]
	s_cbranch_vccz .LBB0_663
	s_barrier

; #define PG8_STAGE(bufoff, gbase, voff) do { _Pragma("unroll") for (int _i = 0; _i < 2; ++_i) \
;         __builtin_amdgcn_global_load_lds((const unsigned*)((const char*)(gbase) + (voff)[_i]), (PG8_LAS unsigned*)(lds + (bufoff) + ldsw + _i * 8192), 16, 0, 0); } while (0)
; #define PG8_LDA(dst, b, h) do { _Pragma("unroll") for (int m = 0; m < 4; ++m) _Pragma("unroll") for (int k = 0; k < 2; ++k) dst[m][k] = *(const PG8_LAS bf16x8*)(lds + PG8_SA(b, h) + aoff + m * 2048 + k * 1024); } while (0)
; #define PG8_LDB(dst, b, h) do { _Pragma("unroll") for (int n = 0; n < 2; ++n) _Pragma("unroll") for (int k = 0; k < 2; ++k) dst[n][k] = *(const PG8_LAS bf16x8*)(lds + PG8_SB(b, h) + boff + n * 2048 + k * 1024); } while (0)
; #define PG8_MMA(ai, bj, At, Bt) do { __builtin_amdgcn_s_setprio(1); _Pragma("unroll") for (int m = 0; m < 4; ++m) _Pragma("unroll") for (int n = 0; n < 2; ++n) _Pragma("unroll") for (int k = 0; k < 2; ++k) \
;         acc[ai][bj][m][n] = mma16(Bt[n][k], At[m][k], acc[ai][bj][m][n]); __builtin_amdgcn_s_setprio(0); } while (0)
; #define PG8_WAIT_V(n) asm volatile("s_waitcnt vmcnt(" #n ")" ::: "memory")
; #define PG8_WAIT_L(n) asm volatile("s_waitcnt lgkmcnt(" #n ")" ::: "memory")
; #define PG8_BAR __builtin_amdgcn_s_barrier()
; #define PG8_SCHED __builtin_amdgcn_sched_barrier(0)
; template <class Epi, class Sched, bool ALIGN_EPI = false, bool SP2 = false>
; __device__ __forceinline__ void gemm_phase(PG8_LAS unsigned char* lds, const Gemm g, const Sched& S, const Epi& E) {
;     ...
;             const bool last = (t == nt - 2);
;             const char* a1 = cA + (size_t)(t + 1) * kstep;
;             const char* a2 = last ? nA : cA + (size_t)(t + 2) * kstep; const char* b2 = last ? nB : cB + (size_t)(t + 2) * kstep;
;             const char* a3 = a2 + kstep; const char* b3 = b2 + kstep;
;             if (last && has_next) S.a_ready(nxt);
;             if constexpr (SP2) {
;             PG8_LDB(B0, 0, 0); PG8_LDB(B1, 0, 1); PG8_SCHED; PG8_LDA(At, 0, 0); PG8_STAGE(PG8_SA(1, 1), a1 + hstepA, voffA);
;             PG8_WAIT_V(8); PG8_WAIT_L(0); PG8_BAR; PG8_MMA(0, 0, At, B0); PG8_MMA(0, 1, At, B1); PG8_BAR; PG8_SCHED;
;             PG8_LDA(At, 0, 1); PG8_STAGE(PG8_SB(0, 0), b2, voffB); PG8_STAGE(PG8_SB(0, 1), b2 + hstepB, voffB); PG8_STAGE(PG8_SA(0, 0), a2, voffA);
.LBB0_841:
	ds_read_b128 v[90:93], v173
	ds_read_b128 v[94:97], v173 offset:1024
	ds_read_b128 v[98:101], v173 offset:2048
	ds_read_b128 v[106:109], v173 offset:3072
	ds_read_b128 v[182:185], v174
	ds_read_b128 v[186:189], v174 offset:1024
	ds_read_b128 v[190:193], v174 offset:2048
	ds_read_b128 v[194:197], v174 offset:3072
	s_add_u32 s58, s56, 0xfff80080
	s_addc_u32 s59, s57, -1
	s_cmp_eq_u32 s68, 28
	s_cselect_b32 s61, s62, s59
	s_cselect_b32 s60, s63, s58
	s_cselect_b32 s59, s64, s67
	s_cselect_b32 s58, s65, s66
	v_lshl_add_u64 v[166:167], s[56:57], 0, v[158:159]
	s_add_i32 m0, s12, 0xc000
	ds_read_b128 v[198:201], v175
	ds_read_b128 v[202:205], v175 offset:1024
	ds_read_b128 v[206:209], v175 offset:2048
	ds_read_b128 v[212:215], v175 offset:3072
	ds_read_b128 v[216:219], v175 offset:4096
	ds_read_b128 v[220:223], v175 offset:5120
	ds_read_b128 v[224:227], v175 offset:6144
	ds_read_b128 v[228:231], v175 offset:7168
	global_load_lds_dwordx4 v[166:167], off
	v_lshl_add_u64 v[166:167], s[56:57], 0, v[160:161]
	s_add_i32 m0, s12, 0xe000
	s_nop 0
	global_load_lds_dwordx4 v[166:167], off
	s_waitcnt vmcnt(8)
	s_waitcnt lgkmcnt(0)
	s_barrier
	s_setprio 1
	s_waitcnt lgkmcnt(0)
	v_mfma_i32_16x16x64_i8 v[142:145], v[90:93], v[198:201], v[142:145]
	v_mfma_i32_16x16x64_i8 v[142:145], v[94:97], v[202:205], v[142:145]
	v_mfma_i32_16x16x64_i8 v[126:129], v[94:97], v[212:215], v[126:129]
	v_mfma_i32_16x16x64_i8 v[126:129], v[90:93], v[206:209], v[126:129]
	v_mfma_i32_16x16x64_i8 v[110:113], v[90:93], v[216:219], v[110:113]
	v_mfma_i32_16x16x64_i8 v[110:113], v[94:97], v[220:223], v[110:113]
	v_mfma_i32_16x16x64_i8 v[78:81], v[94:97], v[228:231], v[78:81]
	v_mfma_i32_16x16x64_i8 v[78:81], v[90:93], v[224:227], v[78:81]
	v_mfma_i32_16x16x64_i8 v[74:77], v[98:101], v[224:227], v[74:77]
	v_mfma_i32_16x16x64_i8 v[74:77], v[106:109], v[228:231], v[74:77]
	v_mfma_i32_16x16x64_i8 v[102:105], v[106:109], v[220:223], v[102:105]
	v_mfma_i32_16x16x64_i8 v[102:105], v[98:101], v[216:219], v[102:105]
	v_mfma_i32_16x16x64_i8 v[122:125], v[98:101], v[206:209], v[122:125]
	v_mfma_i32_16x16x64_i8 v[122:125], v[106:109], v[212:215], v[122:125]
	v_mfma_i32_16x16x64_i8 v[138:141], v[106:109], v[202:205], v[138:141]
	v_mfma_i32_16x16x64_i8 v[138:141], v[98:101], v[198:201], v[138:141]
	s_setprio 0
	s_setprio 1
	v_mfma_i32_16x16x64_i8 v[130:133], v[190:193], v[198:201], v[130:133]
	v_mfma_i32_16x16x64_i8 v[130:133], v[194:197], v[202:205], v[130:133]
	v_mfma_i32_16x16x64_i8 v[114:117], v[194:197], v[212:215], v[114:117]
	v_mfma_i32_16x16x64_i8 v[114:117], v[190:193], v[206:209], v[114:117]
	v_mfma_i32_16x16x64_i8 v[82:85], v[190:193], v[216:219], v[82:85]
	v_mfma_i32_16x16x64_i8 v[82:85], v[194:197], v[220:223], v[82:85]
	v_mfma_i32_16x16x64_i8 v[66:69], v[194:197], v[228:231], v[66:69]
	v_mfma_i32_16x16x64_i8 v[66:69], v[190:193], v[224:227], v[66:69]
	v_mfma_i32_16x16x64_i8 v[70:73], v[182:185], v[224:227], v[70:73]
	v_mfma_i32_16x16x64_i8 v[70:73], v[186:189], v[228:231], v[70:73]
	v_mfma_i32_16x16x64_i8 v[86:89], v[186:189], v[220:223], v[86:89]
	v_mfma_i32_16x16x64_i8 v[86:89], v[182:185], v[216:219], v[86:89]
	v_mfma_i32_16x16x64_i8 v[118:121], v[182:185], v[206:209], v[118:121]
	v_mfma_i32_16x16x64_i8 v[118:121], v[186:189], v[212:215], v[118:121]
	v_mfma_i32_16x16x64_i8 v[134:137], v[186:189], v[202:205], v[134:137]
	v_mfma_i32_16x16x64_i8 v[134:137], v[182:185], v[198:201], v[134:137]
	s_setprio 0
	s_barrier
	s_add_i32 s69, s27, s6
	v_lshl_add_u64 v[166:167], s[58:59], 0, v[150:151]
	s_mov_b32 m0, s69
	ds_read_b128 v[198:201], v175 offset:16384
	ds_read_b128 v[202:205], v175 offset:17408
	ds_read_b128 v[206:209], v175 offset:18432
	ds_read_b128 v[212:215], v175 offset:19456
	ds_read_b128 v[216:219], v175 offset:20480
	ds_read_b128 v[220:223], v175 offset:21504
	ds_read_b128 v[224:227], v175 offset:22528
	ds_read_b128 v[228:231], v175 offset:23552
	global_load_lds_dwordx4 v[166:167], off
	s_add_i32 m0, s69, 0x2000
	s_add_u32 s70, s58, 0x80000
	v_lshl_add_u64 v[176:177], s[58:59], 0, v[146:147]
	s_addc_u32 s71, s59, 0
	s_add_i32 s69, s28, s6
	global_load_lds_dwordx4 v[176:177], off
	v_lshl_add_u64 v[232:233], s[70:71], 0, v[150:151]
	s_mov_b32 m0, s69
	v_lshl_add_u64 v[234:235], s[60:61], 0, v[148:149]
	global_load_lds_dwordx4 v[232:233], off
	v_lshl_add_u64 v[232:233], s[70:71], 0, v[146:147]
	s_add_i32 m0, s69, 0x2000
	s_nop 0
	global_load_lds_dwordx4 v[232:233], off
	v_lshl_add_u64 v[232:233], s[60:61], 0, v[152:153]
	s_mov_b32 m0, s12
	s_nop 0
	global_load_lds_dwordx4 v[232:233], off
	s_mov_b32 m0, s13
	s_nop 0
	global_load_lds_dwordx4 v[234:235], off
	s_waitcnt vmcnt(8)
	s_waitcnt lgkmcnt(0)
	s_barrier
; #define PG8_STAGE(bufoff, gbase, voff) do { _Pragma("unroll") for (int _i = 0; _i < 2; ++_i) \
;         __builtin_amdgcn_global_load_lds((const unsigned*)((const char*)(gbase) + (voff)[_i]), (PG8_LAS unsigned*)(lds + (bufoff) + ldsw + _i * 8192), 16, 0, 0); } while (0)
; #define PG8_LDA(dst, b, h) do { _Pragma("unroll") for (int m = 0; m < 4; ++m) _Pragma("unroll") for (int k = 0; k < 2; ++k) dst[m][k] = *(const PG8_LAS bf16x8*)(lds + PG8_SA(b, h) + aoff + m * 2048 + k * 1024); } while (0)
; #define PG8_LDB(dst, b, h) do { _Pragma("unroll") for (int n = 0; n < 2; ++n) _Pragma("unroll") for (int k = 0; k < 2; ++k) dst[n][k] = *(const PG8_LAS bf16x8*)(lds + PG8_SB(b, h) + boff + n * 2048 + k * 1024); } while (0)
; #define PG8_MMA(ai, bj, At, Bt) do { __builtin_amdgcn_s_setprio(1); _Pragma("unroll") for (int m = 0; m < 4; ++m) _Pragma("unroll") for (int n = 0; n < 2; ++n) _Pragma("unroll") for (int k = 0; k < 2; ++k) \
;         acc[ai][bj][m][n] = mma16(Bt[n][k], At[m][k], acc[ai][bj][m][n]); __builtin_amdgcn_s_setprio(0); } while (0)
; #define PG8_WAIT_V(n) asm volatile("s_waitcnt vmcnt(" #n ")" ::: "memory")
; #define PG8_WAIT_L(n) asm volatile("s_waitcnt lgkmcnt(" #n ")" ::: "memory")
; #define PG8_BAR __builtin_amdgcn_s_barrier()
; #define PG8_SCHED __builtin_amdgcn_sched_barrier(0)
; template <class Epi, class Sched, bool ALIGN_EPI = false, bool SP2 = false>
; __device__ __forceinline__ void gemm_phase(PG8_LAS unsigned char* lds, const Gemm g, const Sched& S, const Epi& E) {
;     ...
;             PG8_WAIT_V(8); PG8_WAIT_L(0); PG8_BAR; PG8_MMA(1, 0, At, B0); PG8_MMA(1, 1, At, B1); PG8_BAR; PG8_SCHED;
;             PG8_LDB(B0, 1, 0); PG8_LDB(B1, 1, 1); PG8_SCHED; PG8_LDA(At, 1, 0); PG8_STAGE(PG8_SA(0, 1), a2 + hstepA, voffA);
;             PG8_WAIT_V(8); PG8_WAIT_L(0); PG8_BAR; PG8_MMA(0, 0, At, B0); PG8_MMA(0, 1, At, B1); PG8_BAR; PG8_SCHED;
	s_setprio 1
	s_waitcnt lgkmcnt(0)
	v_mfma_i32_16x16x64_i8 v[62:65], v[90:93], v[198:201], v[62:65]
	v_mfma_i32_16x16x64_i8 v[62:65], v[94:97], v[202:205], v[62:65]
	v_mfma_i32_16x16x64_i8 v[46:49], v[94:97], v[212:215], v[46:49]
	v_mfma_i32_16x16x64_i8 v[46:49], v[90:93], v[206:209], v[46:49]
	v_mfma_i32_16x16x64_i8 v[30:33], v[90:93], v[216:219], v[30:33]
	v_mfma_i32_16x16x64_i8 v[30:33], v[94:97], v[220:223], v[30:33]
	v_mfma_i32_16x16x64_i8 v[14:17], v[94:97], v[228:231], v[14:17]
	v_mfma_i32_16x16x64_i8 v[14:17], v[90:93], v[224:227], v[14:17]
	v_mfma_i32_16x16x64_i8 v[10:13], v[98:101], v[224:227], v[10:13]
	v_mfma_i32_16x16x64_i8 v[10:13], v[106:109], v[228:231], v[10:13]
	v_mfma_i32_16x16x64_i8 v[26:29], v[106:109], v[220:223], v[26:29]
	v_mfma_i32_16x16x64_i8 v[26:29], v[98:101], v[216:219], v[26:29]
	v_mfma_i32_16x16x64_i8 v[42:45], v[98:101], v[206:209], v[42:45]
	v_mfma_i32_16x16x64_i8 v[42:45], v[106:109], v[212:215], v[42:45]
	v_mfma_i32_16x16x64_i8 v[58:61], v[106:109], v[202:205], v[58:61]
	v_mfma_i32_16x16x64_i8 v[58:61], v[98:101], v[198:201], v[58:61]
	s_setprio 0
	s_setprio 1
	v_mfma_i32_16x16x64_i8 v[50:53], v[190:193], v[198:201], v[50:53]
	v_mfma_i32_16x16x64_i8 v[50:53], v[194:197], v[202:205], v[50:53]
	v_mfma_i32_16x16x64_i8 v[34:37], v[194:197], v[212:215], v[34:37]
	v_mfma_i32_16x16x64_i8 v[34:37], v[190:193], v[206:209], v[34:37]
	v_mfma_i32_16x16x64_i8 v[18:21], v[190:193], v[216:219], v[18:21]
	v_mfma_i32_16x16x64_i8 v[18:21], v[194:197], v[220:223], v[18:21]
	v_mfma_i32_16x16x64_i8 v[2:5], v[194:197], v[228:231], v[2:5]
	v_mfma_i32_16x16x64_i8 v[2:5], v[190:193], v[224:227], v[2:5]
	v_mfma_i32_16x16x64_i8 v[6:9], v[182:185], v[224:227], v[6:9]
	v_mfma_i32_16x16x64_i8 v[6:9], v[186:189], v[228:231], v[6:9]
	v_mfma_i32_16x16x64_i8 v[22:25], v[186:189], v[220:223], v[22:25]
	v_mfma_i32_16x16x64_i8 v[22:25], v[182:185], v[216:219], v[22:25]
	v_mfma_i32_16x16x64_i8 v[38:41], v[182:185], v[206:209], v[38:41]
	v_mfma_i32_16x16x64_i8 v[38:41], v[186:189], v[212:215], v[38:41]
	v_mfma_i32_16x16x64_i8 v[54:57], v[186:189], v[202:205], v[54:57]
	v_mfma_i32_16x16x64_i8 v[54:57], v[182:185], v[198:201], v[54:57]
	s_setprio 0
	s_barrier
	s_add_i32 s69, 0, 0x18000
	s_add_i32 s70, 0, 0x1c000
	v_add_u32_e32 v106, s69, v171
	v_add_u32_e32 v181, s70, v171
	ds_read_b128 v[90:93], v106
	ds_read_b128 v[94:97], v106 offset:1024
	ds_read_b128 v[98:101], v106 offset:2048
	ds_read_b128 v[106:109], v106 offset:3072
	ds_read_b128 v[182:185], v181
	ds_read_b128 v[186:189], v181 offset:1024
	ds_read_b128 v[190:193], v181 offset:2048
	ds_read_b128 v[194:197], v181 offset:3072
	s_add_u32 s60, s60, 0x80000
	s_addc_u32 s61, s61, 0
	s_mov_b32 m0, s16
	v_lshl_add_u64 v[236:237], s[60:61], 0, v[152:153]
	ds_read_b128 v[198:201], v175 offset:32768
	ds_read_b128 v[202:205], v175 offset:33792
	ds_read_b128 v[206:209], v175 offset:34816
	ds_read_b128 v[212:215], v175 offset:35840
	ds_read_b128 v[216:219], v175 offset:36864
	ds_read_b128 v[220:223], v175 offset:37888
	ds_read_b128 v[224:227], v175 offset:38912
	ds_read_b128 v[228:231], v175 offset:39936
	global_load_lds_dwordx4 v[236:237], off
	v_lshl_add_u64 v[236:237], s[60:61], 0, v[148:149]
	s_mov_b32 m0, s17
	s_nop 0
	global_load_lds_dwordx4 v[236:237], off
	s_waitcnt vmcnt(8)
	s_waitcnt lgkmcnt(0)
	s_barrier
	s_setprio 1
	s_waitcnt lgkmcnt(0)
	v_mfma_i32_16x16x64_i8 v[142:145], v[90:93], v[198:201], v[142:145]
	v_mfma_i32_16x16x64_i8 v[142:145], v[94:97], v[202:205], v[142:145]
	v_mfma_i32_16x16x64_i8 v[126:129], v[94:97], v[212:215], v[126:129]
	v_mfma_i32_16x16x64_i8 v[126:129], v[90:93], v[206:209], v[126:129]
	v_mfma_i32_16x16x64_i8 v[110:113], v[90:93], v[216:219], v[110:113]
	v_mfma_i32_16x16x64_i8 v[110:113], v[94:97], v[220:223], v[110:113]
	v_mfma_i32_16x16x64_i8 v[78:81], v[94:97], v[228:231], v[78:81]
	v_mfma_i32_16x16x64_i8 v[78:81], v[90:93], v[224:227], v[78:81]
	v_mfma_i32_16x16x64_i8 v[74:77], v[98:101], v[224:227], v[74:77]
	v_mfma_i32_16x16x64_i8 v[74:77], v[106:109], v[228:231], v[74:77]
	v_mfma_i32_16x16x64_i8 v[102:105], v[106:109], v[220:223], v[102:105]
	v_mfma_i32_16x16x64_i8 v[102:105], v[98:101], v[216:219], v[102:105]
	v_mfma_i32_16x16x64_i8 v[122:125], v[98:101], v[206:209], v[122:125]
	v_mfma_i32_16x16x64_i8 v[122:125], v[106:109], v[212:215], v[122:125]
	v_mfma_i32_16x16x64_i8 v[138:141], v[106:109], v[202:205], v[138:141]
	v_mfma_i32_16x16x64_i8 v[138:141], v[98:101], v[198:201], v[138:141]
	s_setprio 0
	s_setprio 1
	v_mfma_i32_16x16x64_i8 v[130:133], v[190:193], v[198:201], v[130:133]
	v_mfma_i32_16x16x64_i8 v[130:133], v[194:197], v[202:205], v[130:133]
	v_mfma_i32_16x16x64_i8 v[114:117], v[194:197], v[212:215], v[114:117]
	v_mfma_i32_16x16x64_i8 v[114:117], v[190:193], v[206:209], v[114:117]
	v_mfma_i32_16x16x64_i8 v[82:85], v[190:193], v[216:219], v[82:85]
	v_mfma_i32_16x16x64_i8 v[82:85], v[194:197], v[220:223], v[82:85]
	v_mfma_i32_16x16x64_i8 v[66:69], v[194:197], v[228:231], v[66:69]
	v_mfma_i32_16x16x64_i8 v[66:69], v[190:193], v[224:227], v[66:69]
	v_mfma_i32_16x16x64_i8 v[70:73], v[182:185], v[224:227], v[70:73]
	v_mfma_i32_16x16x64_i8 v[70:73], v[186:189], v[228:231], v[70:73]
	v_mfma_i32_16x16x64_i8 v[86:89], v[186:189], v[220:223], v[86:89]
	v_mfma_i32_16x16x64_i8 v[86:89], v[182:185], v[216:219], v[86:89]
	v_mfma_i32_16x16x64_i8 v[118:121], v[182:185], v[206:209], v[118:121]
	v_mfma_i32_16x16x64_i8 v[118:121], v[186:189], v[212:215], v[118:121]
	v_mfma_i32_16x16x64_i8 v[134:137], v[186:189], v[202:205], v[134:137]
	v_mfma_i32_16x16x64_i8 v[134:137], v[182:185], v[198:201], v[134:137]
	s_setprio 0
	s_barrier
; #define PG8_STAGE(bufoff, gbase, voff) do { _Pragma("unroll") for (int _i = 0; _i < 2; ++_i) \
;         __builtin_amdgcn_global_load_lds((const unsigned*)((const char*)(gbase) + (voff)[_i]), (PG8_LAS unsigned*)(lds + (bufoff) + ldsw + _i * 8192), 16, 0, 0); } while (0)
; #define PG8_LDA(dst, b, h) do { _Pragma("unroll") for (int m = 0; m < 4; ++m) _Pragma("unroll") for (int k = 0; k < 2; ++k) dst[m][k] = *(const PG8_LAS bf16x8*)(lds + PG8_SA(b, h) + aoff + m * 2048 + k * 1024); } while (0)
; #define PG8_MMA(ai, bj, At, Bt) do { __builtin_amdgcn_s_setprio(1); _Pragma("unroll") for (int m = 0; m < 4; ++m) _Pragma("unroll") for (int n = 0; n < 2; ++n) _Pragma("unroll") for (int k = 0; k < 2; ++k) \
;         acc[ai][bj][m][n] = mma16(Bt[n][k], At[m][k], acc[ai][bj][m][n]); __builtin_amdgcn_s_setprio(0); } while (0)
; #define PG8_WAIT_V(n) asm volatile("s_waitcnt vmcnt(" #n ")" ::: "memory")
; #define PG8_WAIT_L(n) asm volatile("s_waitcnt lgkmcnt(" #n ")" ::: "memory")
; #define PG8_BAR __builtin_amdgcn_s_barrier()
; #define PG8_SCHED __builtin_amdgcn_sched_barrier(0)
; template <class Epi, class Sched, bool ALIGN_EPI = false, bool SP2 = false>
; __device__ __forceinline__ void gemm_phase(PG8_LAS unsigned char* lds, const Gemm g, const Sched& S, const Epi& E) {
;     ...
;             PG8_LDA(At, 1, 1); PG8_STAGE(PG8_SB(1, 0), b3, voffB); PG8_STAGE(PG8_SB(1, 1), b3 + hstepB, voffB); PG8_STAGE(PG8_SA(1, 0), a3, voffA);
;             PG8_WAIT_V(8); PG8_WAIT_L(0); PG8_BAR; PG8_MMA(1, 0, At, B0); PG8_MMA(1, 1, At, B1); PG8_BAR; PG8_SCHED;
;     ...
;         if constexpr (ALIGN_EPI) { if (wr == 0) PG8_BAR; }
	s_add_i32 s60, s69, s6
	v_lshl_add_u64 v[166:167], v[166:167], 0, s[36:37]
	s_mov_b32 m0, s60
	ds_read_b128 v[198:201], v175 offset:49152
	ds_read_b128 v[202:205], v175 offset:50176
	ds_read_b128 v[206:209], v175 offset:51200
	ds_read_b128 v[212:215], v175 offset:52224
	ds_read_b128 v[216:219], v175 offset:53248
	ds_read_b128 v[220:223], v175 offset:54272
	ds_read_b128 v[224:227], v175 offset:55296
	ds_read_b128 v[228:231], v175 offset:56320
	global_load_lds_dwordx4 v[166:167], off
	s_add_i32 m0, s60, 0x2000
	s_add_u32 s58, s58, 0x80080
	v_lshl_add_u64 v[166:167], v[176:177], 0, s[36:37]
	s_addc_u32 s59, s59, 0
	s_add_i32 s60, s70, s6
	global_load_lds_dwordx4 v[166:167], off
	v_lshl_add_u64 v[166:167], s[58:59], 0, v[150:151]
	s_mov_b32 m0, s60
	s_nop 0
	global_load_lds_dwordx4 v[166:167], off
	v_lshl_add_u64 v[166:167], s[58:59], 0, v[146:147]
	s_add_i32 m0, s60, 0x2000
	s_nop 0
	global_load_lds_dwordx4 v[166:167], off
	v_lshl_add_u64 v[166:167], v[232:233], 0, s[36:37]
	s_mov_b32 m0, s24
	s_nop 0
	global_load_lds_dwordx4 v[166:167], off
	v_lshl_add_u64 v[166:167], v[234:235], 0, s[36:37]
	s_mov_b32 m0, s25
	s_nop 0
	global_load_lds_dwordx4 v[166:167], off
	s_waitcnt vmcnt(8)
	s_waitcnt lgkmcnt(0)
	s_barrier
	s_setprio 1
	s_waitcnt lgkmcnt(0)
	v_mfma_i32_16x16x64_i8 v[62:65], v[90:93], v[198:201], v[62:65]
	v_mfma_i32_16x16x64_i8 v[62:65], v[94:97], v[202:205], v[62:65]
	v_mfma_i32_16x16x64_i8 v[46:49], v[94:97], v[212:215], v[46:49]
	v_mfma_i32_16x16x64_i8 v[46:49], v[90:93], v[206:209], v[46:49]
	v_mfma_i32_16x16x64_i8 v[30:33], v[90:93], v[216:219], v[30:33]
	v_mfma_i32_16x16x64_i8 v[30:33], v[94:97], v[220:223], v[30:33]
	v_mfma_i32_16x16x64_i8 v[14:17], v[94:97], v[228:231], v[14:17]
	v_mfma_i32_16x16x64_i8 v[14:17], v[90:93], v[224:227], v[14:17]
	v_mfma_i32_16x16x64_i8 v[10:13], v[98:101], v[224:227], v[10:13]
	v_mfma_i32_16x16x64_i8 v[10:13], v[106:109], v[228:231], v[10:13]
	v_mfma_i32_16x16x64_i8 v[26:29], v[106:109], v[220:223], v[26:29]
	v_mfma_i32_16x16x64_i8 v[26:29], v[98:101], v[216:219], v[26:29]
	v_mfma_i32_16x16x64_i8 v[42:45], v[98:101], v[206:209], v[42:45]
	v_mfma_i32_16x16x64_i8 v[42:45], v[106:109], v[212:215], v[42:45]
	v_mfma_i32_16x16x64_i8 v[58:61], v[106:109], v[202:205], v[58:61]
	v_mfma_i32_16x16x64_i8 v[58:61], v[98:101], v[198:201], v[58:61]
	s_setprio 0
	s_setprio 1
	v_mfma_i32_16x16x64_i8 v[50:53], v[190:193], v[198:201], v[50:53]
	v_mfma_i32_16x16x64_i8 v[50:53], v[194:197], v[202:205], v[50:53]
	v_mfma_i32_16x16x64_i8 v[34:37], v[194:197], v[212:215], v[34:37]
	v_mfma_i32_16x16x64_i8 v[34:37], v[190:193], v[206:209], v[34:37]
	v_mfma_i32_16x16x64_i8 v[18:21], v[190:193], v[216:219], v[18:21]
	v_mfma_i32_16x16x64_i8 v[18:21], v[194:197], v[220:223], v[18:21]
	v_mfma_i32_16x16x64_i8 v[2:5], v[194:197], v[228:231], v[2:5]
	v_mfma_i32_16x16x64_i8 v[2:5], v[190:193], v[224:227], v[2:5]
	v_mfma_i32_16x16x64_i8 v[6:9], v[182:185], v[224:227], v[6:9]
	v_mfma_i32_16x16x64_i8 v[6:9], v[186:189], v[228:231], v[6:9]
	v_mfma_i32_16x16x64_i8 v[22:25], v[186:189], v[220:223], v[22:25]
	v_mfma_i32_16x16x64_i8 v[22:25], v[182:185], v[216:219], v[22:25]
	v_mfma_i32_16x16x64_i8 v[38:41], v[182:185], v[206:209], v[38:41]
	v_mfma_i32_16x16x64_i8 v[38:41], v[186:189], v[212:215], v[38:41]
	v_mfma_i32_16x16x64_i8 v[54:57], v[186:189], v[202:205], v[54:57]
	v_mfma_i32_16x16x64_i8 v[54:57], v[182:185], v[198:201], v[54:57]
	s_setprio 0
	s_barrier
	s_add_i32 s68, s68, 2
	s_add_u32 s56, s56, 0x100
	s_addc_u32 s57, s57, 0
	s_add_u32 s66, s66, 0x100
	s_addc_u32 s67, s67, 0
	s_cmp_gt_u32 s68, 29
	s_cbranch_scc0 .LBB0_841
	s_and_b64 vcc, exec, s[44:45]
	s_cbranch_vccz .LBB0_844
	s_barrier

; #define PG8_STAGE(bufoff, gbase, voff) do { _Pragma("unroll") for (int _i = 0; _i < 2; ++_i) \
;         __builtin_amdgcn_global_load_lds((const unsigned*)((const char*)(gbase) + (voff)[_i]), (PG8_LAS unsigned*)(lds + (bufoff) + ldsw + _i * 8192), 16, 0, 0); } while (0)
; #define PG8_LDA(dst, b, h) do { _Pragma("unroll") for (int m = 0; m < 4; ++m) _Pragma("unroll") for (int k = 0; k < 2; ++k) dst[m][k] = *(const PG8_LAS bf16x8*)(lds + PG8_SA(b, h) + aoff + m * 2048 + k * 1024); } while (0)
; #define PG8_LDB(dst, b, h) do { _Pragma("unroll") for (int n = 0; n < 2; ++n) _Pragma("unroll") for (int k = 0; k < 2; ++k) dst[n][k] = *(const PG8_LAS bf16x8*)(lds + PG8_SB(b, h) + boff + n * 2048 + k * 1024); } while (0)
; #define PG8_MMA(ai, bj, At, Bt) do { __builtin_amdgcn_s_setprio(1); _Pragma("unroll") for (int m = 0; m < 4; ++m) _Pragma("unroll") for (int n = 0; n < 2; ++n) _Pragma("unroll") for (int k = 0; k < 2; ++k) \
;         acc[ai][bj][m][n] = mma16(Bt[n][k], At[m][k], acc[ai][bj][m][n]); __builtin_amdgcn_s_setprio(0); } while (0)
; #define PG8_WAIT_V(n) asm volatile("s_waitcnt vmcnt(" #n ")" ::: "memory")
; #define PG8_WAIT_L(n) asm volatile("s_waitcnt lgkmcnt(" #n ")" ::: "memory")
; #define PG8_BAR __builtin_amdgcn_s_barrier()
; #define PG8_SCHED __builtin_amdgcn_sched_barrier(0)
; template <class Epi, class Sched, bool ALIGN_EPI = false, bool SP2 = false>
; __device__ __forceinline__ void gemm_phase(PG8_LAS unsigned char* lds, const Gemm g, const Sched& S, const Epi& E) {
;     ...
;             const bool last = (t == nt - 2);
;             const char* a1 = cA + (size_t)(t + 1) * kstep;
;             const char* a2 = last ? nA : cA + (size_t)(t + 2) * kstep; const char* b2 = last ? nB : cB + (size_t)(t + 2) * kstep;
;             const char* a3 = a2 + kstep; const char* b3 = b2 + kstep;
;             if (last && has_next) S.a_ready(nxt);
;             if constexpr (SP2) {
;             PG8_LDB(B0, 0, 0); PG8_LDB(B1, 0, 1); PG8_SCHED; PG8_LDA(At, 0, 0); PG8_STAGE(PG8_SA(1, 1), a1 + hstepA, voffA);
;             PG8_WAIT_V(8); PG8_WAIT_L(0); PG8_BAR; PG8_MMA(0, 0, At, B0); PG8_MMA(0, 1, At, B1); PG8_BAR; PG8_SCHED;
;             PG8_LDA(At, 0, 1); PG8_STAGE(PG8_SB(0, 0), b2, voffB); PG8_STAGE(PG8_SB(0, 1), b2 + hstepB, voffB); PG8_STAGE(PG8_SA(0, 0), a2, voffA);
.LBB0_1020:
	ds_read_b128 v[122:125], v172
	ds_read_b128 v[126:129], v172 offset:1024
	ds_read_b128 v[130:133], v172 offset:2048
	ds_read_b128 v[138:141], v172 offset:3072
	ds_read_b128 v[182:185], v173
	ds_read_b128 v[186:189], v173 offset:1024
	ds_read_b128 v[190:193], v173 offset:2048
	ds_read_b128 v[194:197], v173 offset:3072
	s_add_u32 s58, s56, 0xffea8080
	s_addc_u32 s59, s57, -1
	s_cmpk_eq_i32 s67, 0x52
	s_cselect_b32 s61, s1, s59
	s_cselect_b32 s60, s0, s58
	s_cselect_b32 s59, s53, s66
	s_cselect_b32 s58, s52, s65
	v_lshl_add_u64 v[166:167], s[56:57], 0, v[158:159]
	s_add_i32 m0, s9, 0xc000
	ds_read_b128 v[198:201], v174
	ds_read_b128 v[202:205], v174 offset:1024
	ds_read_b128 v[206:209], v174 offset:2048
	ds_read_b128 v[212:215], v174 offset:3072
	ds_read_b128 v[216:219], v174 offset:4096
	ds_read_b128 v[220:223], v174 offset:5120
	ds_read_b128 v[224:227], v174 offset:6144
	ds_read_b128 v[228:231], v174 offset:7168
	global_load_lds_dwordx4 v[166:167], off
	v_lshl_add_u64 v[166:167], s[56:57], 0, v[160:161]
	s_add_i32 m0, s9, 0xe000
	s_nop 0
	global_load_lds_dwordx4 v[166:167], off
	s_waitcnt vmcnt(8)
	s_waitcnt lgkmcnt(0)
	s_barrier
	s_setprio 1
	s_waitcnt lgkmcnt(0)
	v_mfma_i32_16x16x64_i8 v[142:145], v[122:125], v[198:201], v[142:145]
	v_mfma_i32_16x16x64_i8 v[142:145], v[126:129], v[202:205], v[142:145]
	v_mfma_i32_16x16x64_i8 v[110:113], v[126:129], v[212:215], v[110:113]
	v_mfma_i32_16x16x64_i8 v[110:113], v[122:125], v[206:209], v[110:113]
	v_mfma_i32_16x16x64_i8 v[94:97], v[122:125], v[216:219], v[94:97]
	v_mfma_i32_16x16x64_i8 v[94:97], v[126:129], v[220:223], v[94:97]
	v_mfma_i32_16x16x64_i8 v[78:81], v[126:129], v[228:231], v[78:81]
	v_mfma_i32_16x16x64_i8 v[78:81], v[122:125], v[224:227], v[78:81]
	v_mfma_i32_16x16x64_i8 v[74:77], v[130:133], v[224:227], v[74:77]
	v_mfma_i32_16x16x64_i8 v[74:77], v[138:141], v[228:231], v[74:77]
	v_mfma_i32_16x16x64_i8 v[90:93], v[138:141], v[220:223], v[90:93]
	v_mfma_i32_16x16x64_i8 v[90:93], v[130:133], v[216:219], v[90:93]
	v_mfma_i32_16x16x64_i8 v[106:109], v[130:133], v[206:209], v[106:109]
	v_mfma_i32_16x16x64_i8 v[106:109], v[138:141], v[212:215], v[106:109]
	v_mfma_i32_16x16x64_i8 v[134:137], v[138:141], v[202:205], v[134:137]
	v_mfma_i32_16x16x64_i8 v[134:137], v[130:133], v[198:201], v[134:137]
	s_setprio 0
	s_setprio 1
	v_mfma_i32_16x16x64_i8 v[114:117], v[190:193], v[198:201], v[114:117]
	v_mfma_i32_16x16x64_i8 v[114:117], v[194:197], v[202:205], v[114:117]
	v_mfma_i32_16x16x64_i8 v[98:101], v[194:197], v[212:215], v[98:101]
	v_mfma_i32_16x16x64_i8 v[98:101], v[190:193], v[206:209], v[98:101]
	v_mfma_i32_16x16x64_i8 v[82:85], v[190:193], v[216:219], v[82:85]
	v_mfma_i32_16x16x64_i8 v[82:85], v[194:197], v[220:223], v[82:85]
	v_mfma_i32_16x16x64_i8 v[66:69], v[194:197], v[228:231], v[66:69]
	v_mfma_i32_16x16x64_i8 v[66:69], v[190:193], v[224:227], v[66:69]
	v_mfma_i32_16x16x64_i8 v[70:73], v[182:185], v[224:227], v[70:73]
	v_mfma_i32_16x16x64_i8 v[70:73], v[186:189], v[228:231], v[70:73]
	v_mfma_i32_16x16x64_i8 v[86:89], v[186:189], v[220:223], v[86:89]
	v_mfma_i32_16x16x64_i8 v[86:89], v[182:185], v[216:219], v[86:89]
	v_mfma_i32_16x16x64_i8 v[102:105], v[182:185], v[206:209], v[102:105]
	v_mfma_i32_16x16x64_i8 v[102:105], v[186:189], v[212:215], v[102:105]
	v_mfma_i32_16x16x64_i8 v[118:121], v[186:189], v[202:205], v[118:121]
	v_mfma_i32_16x16x64_i8 v[118:121], v[182:185], v[198:201], v[118:121]
	s_setprio 0
	s_barrier
	s_add_i32 s68, s29, s7
	v_lshl_add_u64 v[166:167], s[58:59], 0, v[148:149]
	s_mov_b32 m0, s68
	ds_read_b128 v[198:201], v174 offset:16384
	ds_read_b128 v[202:205], v174 offset:17408
	ds_read_b128 v[206:209], v174 offset:18432
	ds_read_b128 v[212:215], v174 offset:19456
	ds_read_b128 v[216:219], v174 offset:20480
	ds_read_b128 v[220:223], v174 offset:21504
	ds_read_b128 v[224:227], v174 offset:22528
	ds_read_b128 v[228:231], v174 offset:23552
	global_load_lds_dwordx4 v[166:167], off
	s_add_i32 m0, s68, 0x2000
	s_add_u32 s68, s58, 0x158000
	v_lshl_add_u64 v[176:177], s[58:59], 0, v[152:153]
	s_addc_u32 s69, s59, 0
	s_add_i32 s70, s33, s7
	global_load_lds_dwordx4 v[176:177], off
	v_lshl_add_u64 v[232:233], s[68:69], 0, v[148:149]
	s_mov_b32 m0, s70
	v_lshl_add_u64 v[234:235], s[60:61], 0, v[150:151]
	global_load_lds_dwordx4 v[232:233], off
	v_lshl_add_u64 v[232:233], s[68:69], 0, v[152:153]
	s_add_i32 m0, s70, 0x2000
	s_nop 0
	global_load_lds_dwordx4 v[232:233], off
	v_lshl_add_u64 v[232:233], s[60:61], 0, v[146:147]
	s_mov_b32 m0, s9
	s_nop 0
	global_load_lds_dwordx4 v[232:233], off
	s_mov_b32 m0, s11
	s_nop 0
	global_load_lds_dwordx4 v[234:235], off
	s_waitcnt vmcnt(8)
	s_waitcnt lgkmcnt(0)
	s_barrier
; #define PG8_STAGE(bufoff, gbase, voff) do { _Pragma("unroll") for (int _i = 0; _i < 2; ++_i) \
;         __builtin_amdgcn_global_load_lds((const unsigned*)((const char*)(gbase) + (voff)[_i]), (PG8_LAS unsigned*)(lds + (bufoff) + ldsw + _i * 8192), 16, 0, 0); } while (0)
; #define PG8_LDA(dst, b, h) do { _Pragma("unroll") for (int m = 0; m < 4; ++m) _Pragma("unroll") for (int k = 0; k < 2; ++k) dst[m][k] = *(const PG8_LAS bf16x8*)(lds + PG8_SA(b, h) + aoff + m * 2048 + k * 1024); } while (0)
; #define PG8_LDB(dst, b, h) do { _Pragma("unroll") for (int n = 0; n < 2; ++n) _Pragma("unroll") for (int k = 0; k < 2; ++k) dst[n][k] = *(const PG8_LAS bf16x8*)(lds + PG8_SB(b, h) + boff + n * 2048 + k * 1024); } while (0)
; #define PG8_MMA(ai, bj, At, Bt) do { __builtin_amdgcn_s_setprio(1); _Pragma("unroll") for (int m = 0; m < 4; ++m) _Pragma("unroll") for (int n = 0; n < 2; ++n) _Pragma("unroll") for (int k = 0; k < 2; ++k) \
;         acc[ai][bj][m][n] = mma16(Bt[n][k], At[m][k], acc[ai][bj][m][n]); __builtin_amdgcn_s_setprio(0); } while (0)
; #define PG8_WAIT_V(n) asm volatile("s_waitcnt vmcnt(" #n ")" ::: "memory")
; #define PG8_WAIT_L(n) asm volatile("s_waitcnt lgkmcnt(" #n ")" ::: "memory")
; #define PG8_BAR __builtin_amdgcn_s_barrier()
; #define PG8_SCHED __builtin_amdgcn_sched_barrier(0)
; template <class Epi, class Sched, bool ALIGN_EPI = false, bool SP2 = false>
; __device__ __forceinline__ void gemm_phase(PG8_LAS unsigned char* lds, const Gemm g, const Sched& S, const Epi& E) {
;     ...
;             PG8_WAIT_V(8); PG8_WAIT_L(0); PG8_BAR; PG8_MMA(1, 0, At, B0); PG8_MMA(1, 1, At, B1); PG8_BAR; PG8_SCHED;
;             PG8_LDB(B0, 1, 0); PG8_LDB(B1, 1, 1); PG8_SCHED; PG8_LDA(At, 1, 0); PG8_STAGE(PG8_SA(0, 1), a2 + hstepA, voffA);
;             PG8_WAIT_V(8); PG8_WAIT_L(0); PG8_BAR; PG8_MMA(0, 0, At, B0); PG8_MMA(0, 1, At, B1); PG8_BAR; PG8_SCHED;
	s_setprio 1
	s_waitcnt lgkmcnt(0)
	v_mfma_i32_16x16x64_i8 v[62:65], v[122:125], v[198:201], v[62:65]
	v_mfma_i32_16x16x64_i8 v[62:65], v[126:129], v[202:205], v[62:65]
	v_mfma_i32_16x16x64_i8 v[46:49], v[126:129], v[212:215], v[46:49]
	v_mfma_i32_16x16x64_i8 v[46:49], v[122:125], v[206:209], v[46:49]
	v_mfma_i32_16x16x64_i8 v[30:33], v[122:125], v[216:219], v[30:33]
	v_mfma_i32_16x16x64_i8 v[30:33], v[126:129], v[220:223], v[30:33]
	v_mfma_i32_16x16x64_i8 v[14:17], v[126:129], v[228:231], v[14:17]
	v_mfma_i32_16x16x64_i8 v[14:17], v[122:125], v[224:227], v[14:17]
	v_mfma_i32_16x16x64_i8 v[10:13], v[130:133], v[224:227], v[10:13]
	v_mfma_i32_16x16x64_i8 v[10:13], v[138:141], v[228:231], v[10:13]
	v_mfma_i32_16x16x64_i8 v[26:29], v[138:141], v[220:223], v[26:29]
	v_mfma_i32_16x16x64_i8 v[26:29], v[130:133], v[216:219], v[26:29]
	v_mfma_i32_16x16x64_i8 v[42:45], v[130:133], v[206:209], v[42:45]
	v_mfma_i32_16x16x64_i8 v[42:45], v[138:141], v[212:215], v[42:45]
	v_mfma_i32_16x16x64_i8 v[58:61], v[138:141], v[202:205], v[58:61]
	v_mfma_i32_16x16x64_i8 v[58:61], v[130:133], v[198:201], v[58:61]
	s_setprio 0
	s_setprio 1
	v_mfma_i32_16x16x64_i8 v[50:53], v[190:193], v[198:201], v[50:53]
	v_mfma_i32_16x16x64_i8 v[50:53], v[194:197], v[202:205], v[50:53]
	v_mfma_i32_16x16x64_i8 v[34:37], v[194:197], v[212:215], v[34:37]
	v_mfma_i32_16x16x64_i8 v[34:37], v[190:193], v[206:209], v[34:37]
	v_mfma_i32_16x16x64_i8 v[18:21], v[190:193], v[216:219], v[18:21]
	v_mfma_i32_16x16x64_i8 v[18:21], v[194:197], v[220:223], v[18:21]
	v_mfma_i32_16x16x64_i8 v[2:5], v[194:197], v[228:231], v[2:5]
	v_mfma_i32_16x16x64_i8 v[2:5], v[190:193], v[224:227], v[2:5]
	v_mfma_i32_16x16x64_i8 v[6:9], v[182:185], v[224:227], v[6:9]
	v_mfma_i32_16x16x64_i8 v[6:9], v[186:189], v[228:231], v[6:9]
	v_mfma_i32_16x16x64_i8 v[22:25], v[186:189], v[220:223], v[22:25]
	v_mfma_i32_16x16x64_i8 v[22:25], v[182:185], v[216:219], v[22:25]
	v_mfma_i32_16x16x64_i8 v[38:41], v[182:185], v[206:209], v[38:41]
	v_mfma_i32_16x16x64_i8 v[38:41], v[186:189], v[212:215], v[38:41]
	v_mfma_i32_16x16x64_i8 v[54:57], v[186:189], v[202:205], v[54:57]
	v_mfma_i32_16x16x64_i8 v[54:57], v[182:185], v[198:201], v[54:57]
	s_setprio 0
	s_barrier
	s_add_i32 s68, 0, 0x18000
	s_add_i32 s69, 0, 0x1c000
	v_add_u32_e32 v138, s68, v170
	v_add_u32_e32 v175, s69, v170
	ds_read_b128 v[122:125], v138
	ds_read_b128 v[126:129], v138 offset:1024
	ds_read_b128 v[130:133], v138 offset:2048
	ds_read_b128 v[138:141], v138 offset:3072
	ds_read_b128 v[182:185], v175
	ds_read_b128 v[186:189], v175 offset:1024
	ds_read_b128 v[190:193], v175 offset:2048
	ds_read_b128 v[194:197], v175 offset:3072
	s_add_u32 s60, s60, 0x158000
	s_addc_u32 s61, s61, 0
	s_mov_b32 m0, s12
	v_lshl_add_u64 v[236:237], s[60:61], 0, v[146:147]
	ds_read_b128 v[198:201], v174 offset:32768
	ds_read_b128 v[202:205], v174 offset:33792
	ds_read_b128 v[206:209], v174 offset:34816
	ds_read_b128 v[212:215], v174 offset:35840
	ds_read_b128 v[216:219], v174 offset:36864
	ds_read_b128 v[220:223], v174 offset:37888
	ds_read_b128 v[224:227], v174 offset:38912
	ds_read_b128 v[228:231], v174 offset:39936
	global_load_lds_dwordx4 v[236:237], off
	v_lshl_add_u64 v[236:237], s[60:61], 0, v[150:151]
	s_mov_b32 m0, s13
	s_nop 0
	global_load_lds_dwordx4 v[236:237], off
	s_waitcnt vmcnt(8)
	s_waitcnt lgkmcnt(0)
	s_barrier
	s_setprio 1
	s_waitcnt lgkmcnt(0)
	v_mfma_i32_16x16x64_i8 v[142:145], v[122:125], v[198:201], v[142:145]
	v_mfma_i32_16x16x64_i8 v[142:145], v[126:129], v[202:205], v[142:145]
	v_mfma_i32_16x16x64_i8 v[110:113], v[126:129], v[212:215], v[110:113]
	v_mfma_i32_16x16x64_i8 v[110:113], v[122:125], v[206:209], v[110:113]
	v_mfma_i32_16x16x64_i8 v[94:97], v[122:125], v[216:219], v[94:97]
	v_mfma_i32_16x16x64_i8 v[94:97], v[126:129], v[220:223], v[94:97]
	v_mfma_i32_16x16x64_i8 v[78:81], v[126:129], v[228:231], v[78:81]
	v_mfma_i32_16x16x64_i8 v[78:81], v[122:125], v[224:227], v[78:81]
	v_mfma_i32_16x16x64_i8 v[74:77], v[130:133], v[224:227], v[74:77]
	v_mfma_i32_16x16x64_i8 v[74:77], v[138:141], v[228:231], v[74:77]
	v_mfma_i32_16x16x64_i8 v[90:93], v[138:141], v[220:223], v[90:93]
	v_mfma_i32_16x16x64_i8 v[90:93], v[130:133], v[216:219], v[90:93]
	v_mfma_i32_16x16x64_i8 v[106:109], v[130:133], v[206:209], v[106:109]
	v_mfma_i32_16x16x64_i8 v[106:109], v[138:141], v[212:215], v[106:109]
	v_mfma_i32_16x16x64_i8 v[134:137], v[138:141], v[202:205], v[134:137]
	v_mfma_i32_16x16x64_i8 v[134:137], v[130:133], v[198:201], v[134:137]
	s_setprio 0
	s_setprio 1
	v_mfma_i32_16x16x64_i8 v[114:117], v[190:193], v[198:201], v[114:117]
	v_mfma_i32_16x16x64_i8 v[114:117], v[194:197], v[202:205], v[114:117]
	v_mfma_i32_16x16x64_i8 v[98:101], v[194:197], v[212:215], v[98:101]
	v_mfma_i32_16x16x64_i8 v[98:101], v[190:193], v[206:209], v[98:101]
	v_mfma_i32_16x16x64_i8 v[82:85], v[190:193], v[216:219], v[82:85]
	v_mfma_i32_16x16x64_i8 v[82:85], v[194:197], v[220:223], v[82:85]
	v_mfma_i32_16x16x64_i8 v[66:69], v[194:197], v[228:231], v[66:69]
	v_mfma_i32_16x16x64_i8 v[66:69], v[190:193], v[224:227], v[66:69]
	v_mfma_i32_16x16x64_i8 v[70:73], v[182:185], v[224:227], v[70:73]
	v_mfma_i32_16x16x64_i8 v[70:73], v[186:189], v[228:231], v[70:73]
	v_mfma_i32_16x16x64_i8 v[86:89], v[186:189], v[220:223], v[86:89]
	v_mfma_i32_16x16x64_i8 v[86:89], v[182:185], v[216:219], v[86:89]
	v_mfma_i32_16x16x64_i8 v[102:105], v[182:185], v[206:209], v[102:105]
	v_mfma_i32_16x16x64_i8 v[102:105], v[186:189], v[212:215], v[102:105]
	v_mfma_i32_16x16x64_i8 v[118:121], v[186:189], v[202:205], v[118:121]
	v_mfma_i32_16x16x64_i8 v[118:121], v[182:185], v[198:201], v[118:121]
	s_setprio 0
	s_barrier
; #define PG8_STAGE(bufoff, gbase, voff) do { _Pragma("unroll") for (int _i = 0; _i < 2; ++_i) \
;         __builtin_amdgcn_global_load_lds((const unsigned*)((const char*)(gbase) + (voff)[_i]), (PG8_LAS unsigned*)(lds + (bufoff) + ldsw + _i * 8192), 16, 0, 0); } while (0)
; #define PG8_LDA(dst, b, h) do { _Pragma("unroll") for (int m = 0; m < 4; ++m) _Pragma("unroll") for (int k = 0; k < 2; ++k) dst[m][k] = *(const PG8_LAS bf16x8*)(lds + PG8_SA(b, h) + aoff + m * 2048 + k * 1024); } while (0)
; #define PG8_MMA(ai, bj, At, Bt) do { __builtin_amdgcn_s_setprio(1); _Pragma("unroll") for (int m = 0; m < 4; ++m) _Pragma("unroll") for (int n = 0; n < 2; ++n) _Pragma("unroll") for (int k = 0; k < 2; ++k) \
;         acc[ai][bj][m][n] = mma16(Bt[n][k], At[m][k], acc[ai][bj][m][n]); __builtin_amdgcn_s_setprio(0); } while (0)
; #define PG8_WAIT_V(n) asm volatile("s_waitcnt vmcnt(" #n ")" ::: "memory")
; #define PG8_WAIT_L(n) asm volatile("s_waitcnt lgkmcnt(" #n ")" ::: "memory")
; #define PG8_BAR __builtin_amdgcn_s_barrier()
; #define PG8_SCHED __builtin_amdgcn_sched_barrier(0)
; template <class Epi, class Sched, bool ALIGN_EPI = false, bool SP2 = false>
; __device__ __forceinline__ void gemm_phase(PG8_LAS unsigned char* lds, const Gemm g, const Sched& S, const Epi& E) {
;     ...
;             PG8_LDA(At, 1, 1); PG8_STAGE(PG8_SB(1, 0), b3, voffB); PG8_STAGE(PG8_SB(1, 1), b3 + hstepB, voffB); PG8_STAGE(PG8_SA(1, 0), a3, voffA);
;             PG8_WAIT_V(8); PG8_WAIT_L(0); PG8_BAR; PG8_MMA(1, 0, At, B0); PG8_MMA(1, 1, At, B1); PG8_BAR; PG8_SCHED;
;     ...
;         if constexpr (ALIGN_EPI) { if (wr == 0) PG8_BAR; }
	s_add_i32 s60, s68, s7
	v_lshl_add_u64 v[166:167], v[166:167], 0, s[24:25]
	s_mov_b32 m0, s60
	ds_read_b128 v[198:201], v174 offset:49152
	ds_read_b128 v[202:205], v174 offset:50176
	ds_read_b128 v[206:209], v174 offset:51200
	ds_read_b128 v[212:215], v174 offset:52224
	ds_read_b128 v[216:219], v174 offset:53248
	ds_read_b128 v[220:223], v174 offset:54272
	ds_read_b128 v[224:227], v174 offset:55296
	ds_read_b128 v[228:231], v174 offset:56320
	global_load_lds_dwordx4 v[166:167], off
	s_add_i32 m0, s60, 0x2000
	s_add_u32 s58, s58, 0x158080
	v_lshl_add_u64 v[166:167], v[176:177], 0, s[24:25]
	s_addc_u32 s59, s59, 0
	s_add_i32 s60, s69, s7
	global_load_lds_dwordx4 v[166:167], off
	v_lshl_add_u64 v[166:167], s[58:59], 0, v[148:149]
	s_mov_b32 m0, s60
	s_nop 0
	global_load_lds_dwordx4 v[166:167], off
	v_lshl_add_u64 v[166:167], s[58:59], 0, v[152:153]
	s_add_i32 m0, s60, 0x2000
	s_nop 0
	global_load_lds_dwordx4 v[166:167], off
	v_lshl_add_u64 v[166:167], v[232:233], 0, s[24:25]
	s_mov_b32 m0, s26
	s_nop 0
	global_load_lds_dwordx4 v[166:167], off
	v_lshl_add_u64 v[166:167], v[234:235], 0, s[24:25]
	s_mov_b32 m0, s27
	s_nop 0
	global_load_lds_dwordx4 v[166:167], off
	s_waitcnt vmcnt(8)
	s_waitcnt lgkmcnt(0)
	s_barrier
	s_setprio 1
	s_waitcnt lgkmcnt(0)
	v_mfma_i32_16x16x64_i8 v[62:65], v[122:125], v[198:201], v[62:65]
	v_mfma_i32_16x16x64_i8 v[62:65], v[126:129], v[202:205], v[62:65]
	v_mfma_i32_16x16x64_i8 v[46:49], v[126:129], v[212:215], v[46:49]
	v_mfma_i32_16x16x64_i8 v[46:49], v[122:125], v[206:209], v[46:49]
	v_mfma_i32_16x16x64_i8 v[30:33], v[122:125], v[216:219], v[30:33]
	v_mfma_i32_16x16x64_i8 v[30:33], v[126:129], v[220:223], v[30:33]
	v_mfma_i32_16x16x64_i8 v[14:17], v[126:129], v[228:231], v[14:17]
	v_mfma_i32_16x16x64_i8 v[14:17], v[122:125], v[224:227], v[14:17]
	v_mfma_i32_16x16x64_i8 v[10:13], v[130:133], v[224:227], v[10:13]
	v_mfma_i32_16x16x64_i8 v[10:13], v[138:141], v[228:231], v[10:13]
	v_mfma_i32_16x16x64_i8 v[26:29], v[138:141], v[220:223], v[26:29]
	v_mfma_i32_16x16x64_i8 v[26:29], v[130:133], v[216:219], v[26:29]
	v_mfma_i32_16x16x64_i8 v[42:45], v[130:133], v[206:209], v[42:45]
	v_mfma_i32_16x16x64_i8 v[42:45], v[138:141], v[212:215], v[42:45]
	v_mfma_i32_16x16x64_i8 v[58:61], v[138:141], v[202:205], v[58:61]
	v_mfma_i32_16x16x64_i8 v[58:61], v[130:133], v[198:201], v[58:61]
	s_setprio 0
	s_setprio 1
	v_mfma_i32_16x16x64_i8 v[50:53], v[190:193], v[198:201], v[50:53]
	v_mfma_i32_16x16x64_i8 v[50:53], v[194:197], v[202:205], v[50:53]
	v_mfma_i32_16x16x64_i8 v[34:37], v[194:197], v[212:215], v[34:37]
	v_mfma_i32_16x16x64_i8 v[34:37], v[190:193], v[206:209], v[34:37]
	v_mfma_i32_16x16x64_i8 v[18:21], v[190:193], v[216:219], v[18:21]
	v_mfma_i32_16x16x64_i8 v[18:21], v[194:197], v[220:223], v[18:21]
	v_mfma_i32_16x16x64_i8 v[2:5], v[194:197], v[228:231], v[2:5]
	v_mfma_i32_16x16x64_i8 v[2:5], v[190:193], v[224:227], v[2:5]
	v_mfma_i32_16x16x64_i8 v[6:9], v[182:185], v[224:227], v[6:9]
	v_mfma_i32_16x16x64_i8 v[6:9], v[186:189], v[228:231], v[6:9]
	v_mfma_i32_16x16x64_i8 v[22:25], v[186:189], v[220:223], v[22:25]
	v_mfma_i32_16x16x64_i8 v[22:25], v[182:185], v[216:219], v[22:25]
	v_mfma_i32_16x16x64_i8 v[38:41], v[182:185], v[206:209], v[38:41]
	v_mfma_i32_16x16x64_i8 v[38:41], v[186:189], v[212:215], v[38:41]
	v_mfma_i32_16x16x64_i8 v[54:57], v[186:189], v[202:205], v[54:57]
	v_mfma_i32_16x16x64_i8 v[54:57], v[182:185], v[198:201], v[54:57]
	s_setprio 0
	s_barrier
	s_add_i32 s67, s67, 2
	s_add_u32 s56, s56, 0x100
	s_addc_u32 s57, s57, 0
	s_add_u32 s65, s65, 0x100
	s_addc_u32 s66, s66, 0
	s_cmpk_gt_u32 s67, 0x53
	s_cbranch_scc0 .LBB0_1020
	s_and_b64 vcc, exec, s[36:37]
	s_cbranch_vccz .LBB0_1023
	s_barrier

; #define PG8_STAGE(bufoff, gbase, voff) do { _Pragma("unroll") for (int _i = 0; _i < 2; ++_i) \
;         __builtin_amdgcn_global_load_lds((const unsigned*)((const char*)(gbase) + (voff)[_i]), (PG8_LAS unsigned*)(lds + (bufoff) + ldsw + _i * 8192), 16, 0, 0); } while (0)
; #define PG8_LDA(dst, b, h) do { _Pragma("unroll") for (int m = 0; m < 4; ++m) _Pragma("unroll") for (int k = 0; k < 2; ++k) dst[m][k] = *(const PG8_LAS bf16x8*)(lds + PG8_SA(b, h) + aoff + m * 2048 + k * 1024); } while (0)
; #define PG8_LDB(dst, b, h) do { _Pragma("unroll") for (int n = 0; n < 2; ++n) _Pragma("unroll") for (int k = 0; k < 2; ++k) dst[n][k] = *(const PG8_LAS bf16x8*)(lds + PG8_SB(b, h) + boff + n * 2048 + k * 1024); } while (0)
; #define PG8_MMA(ai, bj, At, Bt) do { __builtin_amdgcn_s_setprio(1); _Pragma("unroll") for (int m = 0; m < 4; ++m) _Pragma("unroll") for (int n = 0; n < 2; ++n) _Pragma("unroll") for (int k = 0; k < 2; ++k) \
;         acc[ai][bj][m][n] = mma16(Bt[n][k], At[m][k], acc[ai][bj][m][n]); __builtin_amdgcn_s_setprio(0); } while (0)
; #define PG8_WAIT_V(n) asm volatile("s_waitcnt vmcnt(" #n ")" ::: "memory")
; #define PG8_WAIT_L(n) asm volatile("s_waitcnt lgkmcnt(" #n ")" ::: "memory")
; #define PG8_BAR __builtin_amdgcn_s_barrier()
; #define PG8_SCHED __builtin_amdgcn_sched_barrier(0)
; template <class Epi, class Sched, bool ALIGN_EPI = false, bool SP2 = false>
; __device__ __forceinline__ void gemm_phase(PG8_LAS unsigned char* lds, const Gemm g, const Sched& S, const Epi& E) {
;     ...
;             const bool last = (t == nt - 2);
;             const char* a1 = cA + (size_t)(t + 1) * kstep;
;             const char* a2 = last ? nA : cA + (size_t)(t + 2) * kstep; const char* b2 = last ? nB : cB + (size_t)(t + 2) * kstep;
;             const char* a3 = a2 + kstep; const char* b3 = b2 + kstep;
;             if (last && has_next) S.a_ready(nxt);
;             if constexpr (SP2) {
;             PG8_LDB(B0, 0, 0); PG8_LDB(B1, 0, 1); PG8_SCHED; PG8_LDA(At, 0, 0); PG8_STAGE(PG8_SA(1, 1), a1 + hstepA, voffA);
;             PG8_WAIT_V(8); PG8_WAIT_L(0); PG8_BAR; PG8_MMA(0, 0, At, B0); PG8_MMA(0, 1, At, B1); PG8_BAR; PG8_SCHED;
;             PG8_LDA(At, 0, 1); PG8_STAGE(PG8_SB(0, 0), b2, voffB); PG8_STAGE(PG8_SB(0, 1), b2 + hstepB, voffB); PG8_STAGE(PG8_SA(0, 0), a2, voffA);
.LBB0_1037:
	ds_read_b128 v[118:121], v167
	ds_read_b128 v[126:129], v167 offset:1024
	ds_read_b128 v[130:133], v167 offset:2048
	ds_read_b128 v[134:137], v167 offset:3072
	ds_read_b128 v[172:175], v168
	ds_read_b128 v[182:185], v168 offset:1024
	ds_read_b128 v[186:189], v168 offset:2048
	ds_read_b128 v[190:193], v168 offset:3072
	s_add_u32 s52, s50, 0xffea8080
	s_addc_u32 s53, s51, -1
	s_cmpk_eq_i32 s71, 0x52
	s_cselect_b32 s55, s47, s53
	s_cselect_b32 s54, s46, s52
	s_cselect_b32 s53, s9, s70
	s_cselect_b32 s52, s8, s45
	s_mov_b32 m0, s35
	v_lshl_add_u64 v[162:163], s[50:51], 0, v[158:159]
	ds_read_b128 v[194:197], v169
	ds_read_b128 v[198:201], v169 offset:1024
	ds_read_b128 v[202:205], v169 offset:2048
	ds_read_b128 v[206:209], v169 offset:3072
	ds_read_b128 v[212:215], v169 offset:4096
	ds_read_b128 v[216:219], v169 offset:5120
	ds_read_b128 v[220:223], v169 offset:6144
	ds_read_b128 v[224:227], v169 offset:7168
	global_load_lds_dwordx4 v[162:163], off
	v_lshl_add_u64 v[162:163], s[50:51], 0, v[160:161]
	s_mov_b32 m0, s56
	s_nop 0
	global_load_lds_dwordx4 v[162:163], off
	s_waitcnt vmcnt(8)
	s_waitcnt lgkmcnt(0)
	s_barrier
	s_setprio 1
	s_waitcnt lgkmcnt(0)
	v_mfma_i32_16x16x64_i8 v[142:145], v[118:121], v[194:197], v[142:145]
	v_mfma_i32_16x16x64_i8 v[142:145], v[126:129], v[198:201], v[142:145]
	v_mfma_i32_16x16x64_i8 v[110:113], v[126:129], v[206:209], v[110:113]
	v_mfma_i32_16x16x64_i8 v[110:113], v[118:121], v[202:205], v[110:113]
	v_mfma_i32_16x16x64_i8 v[94:97], v[118:121], v[212:215], v[94:97]
	v_mfma_i32_16x16x64_i8 v[94:97], v[126:129], v[216:219], v[94:97]
	v_mfma_i32_16x16x64_i8 v[78:81], v[126:129], v[224:227], v[78:81]
	v_mfma_i32_16x16x64_i8 v[78:81], v[118:121], v[220:223], v[78:81]
	v_mfma_i32_16x16x64_i8 v[74:77], v[130:133], v[220:223], v[74:77]
	v_mfma_i32_16x16x64_i8 v[74:77], v[134:137], v[224:227], v[74:77]
	v_mfma_i32_16x16x64_i8 v[90:93], v[134:137], v[216:219], v[90:93]
	v_mfma_i32_16x16x64_i8 v[90:93], v[130:133], v[212:215], v[90:93]
	v_mfma_i32_16x16x64_i8 v[106:109], v[130:133], v[202:205], v[106:109]
	v_mfma_i32_16x16x64_i8 v[106:109], v[134:137], v[206:209], v[106:109]
	v_mfma_i32_16x16x64_i8 v[138:141], v[134:137], v[198:201], v[138:141]
	v_mfma_i32_16x16x64_i8 v[138:141], v[130:133], v[194:197], v[138:141]
	s_setprio 0
	s_setprio 1
	v_mfma_i32_16x16x64_i8 v[114:117], v[186:189], v[194:197], v[114:117]
	v_mfma_i32_16x16x64_i8 v[114:117], v[190:193], v[198:201], v[114:117]
	v_mfma_i32_16x16x64_i8 v[98:101], v[190:193], v[206:209], v[98:101]
	v_mfma_i32_16x16x64_i8 v[98:101], v[186:189], v[202:205], v[98:101]
	v_mfma_i32_16x16x64_i8 v[82:85], v[186:189], v[212:215], v[82:85]
	v_mfma_i32_16x16x64_i8 v[82:85], v[190:193], v[216:219], v[82:85]
	v_mfma_i32_16x16x64_i8 v[66:69], v[190:193], v[224:227], v[66:69]
	v_mfma_i32_16x16x64_i8 v[66:69], v[186:189], v[220:223], v[66:69]
	v_mfma_i32_16x16x64_i8 v[70:73], v[172:175], v[220:223], v[70:73]
	v_mfma_i32_16x16x64_i8 v[70:73], v[182:185], v[224:227], v[70:73]
	v_mfma_i32_16x16x64_i8 v[86:89], v[182:185], v[216:219], v[86:89]
	v_mfma_i32_16x16x64_i8 v[86:89], v[172:175], v[212:215], v[86:89]
	v_mfma_i32_16x16x64_i8 v[102:105], v[172:175], v[202:205], v[102:105]
	v_mfma_i32_16x16x64_i8 v[102:105], v[182:185], v[206:209], v[102:105]
	v_mfma_i32_16x16x64_i8 v[122:125], v[182:185], v[198:201], v[122:125]
	v_mfma_i32_16x16x64_i8 v[122:125], v[172:175], v[194:197], v[122:125]
	s_setprio 0
	s_barrier
	s_mov_b32 m0, s57
	v_lshl_add_u64 v[162:163], s[52:53], 0, v[150:151]
	s_add_u32 s74, s52, 0x158000
	ds_read_b128 v[194:197], v169 offset:16384
	ds_read_b128 v[198:201], v169 offset:17408
	ds_read_b128 v[202:205], v169 offset:18432
	ds_read_b128 v[206:209], v169 offset:19456
	ds_read_b128 v[212:215], v169 offset:20480
	ds_read_b128 v[216:219], v169 offset:21504
	ds_read_b128 v[220:223], v169 offset:22528
	ds_read_b128 v[224:227], v169 offset:23552
	global_load_lds_dwordx4 v[162:163], off
	v_lshl_add_u64 v[176:177], s[52:53], 0, v[146:147]
	s_mov_b32 m0, s58
	s_addc_u32 s75, s53, 0
	global_load_lds_dwordx4 v[176:177], off
	v_lshl_add_u64 v[228:229], s[74:75], 0, v[150:151]
	s_mov_b32 m0, s63
	v_lshl_add_u64 v[230:231], s[54:55], 0, v[148:149]
	global_load_lds_dwordx4 v[228:229], off
	v_lshl_add_u64 v[228:229], s[74:75], 0, v[146:147]
	s_mov_b32 m0, s64
	s_nop 0
	global_load_lds_dwordx4 v[228:229], off
	v_lshl_add_u64 v[228:229], s[54:55], 0, v[152:153]
	s_mov_b32 m0, s5
	s_nop 0
	global_load_lds_dwordx4 v[228:229], off
	s_mov_b32 m0, s6
	s_nop 0
	global_load_lds_dwordx4 v[230:231], off
	s_waitcnt vmcnt(8)
	s_waitcnt lgkmcnt(0)
	s_barrier
; #define PG8_STAGE(bufoff, gbase, voff) do { _Pragma("unroll") for (int _i = 0; _i < 2; ++_i) \
;         __builtin_amdgcn_global_load_lds((const unsigned*)((const char*)(gbase) + (voff)[_i]), (PG8_LAS unsigned*)(lds + (bufoff) + ldsw + _i * 8192), 16, 0, 0); } while (0)
; #define PG8_LDA(dst, b, h) do { _Pragma("unroll") for (int m = 0; m < 4; ++m) _Pragma("unroll") for (int k = 0; k < 2; ++k) dst[m][k] = *(const PG8_LAS bf16x8*)(lds + PG8_SA(b, h) + aoff + m * 2048 + k * 1024); } while (0)
; #define PG8_LDB(dst, b, h) do { _Pragma("unroll") for (int n = 0; n < 2; ++n) _Pragma("unroll") for (int k = 0; k < 2; ++k) dst[n][k] = *(const PG8_LAS bf16x8*)(lds + PG8_SB(b, h) + boff + n * 2048 + k * 1024); } while (0)
; #define PG8_MMA(ai, bj, At, Bt) do { __builtin_amdgcn_s_setprio(1); _Pragma("unroll") for (int m = 0; m < 4; ++m) _Pragma("unroll") for (int n = 0; n < 2; ++n) _Pragma("unroll") for (int k = 0; k < 2; ++k) \
;         acc[ai][bj][m][n] = mma16(Bt[n][k], At[m][k], acc[ai][bj][m][n]); __builtin_amdgcn_s_setprio(0); } while (0)
; #define PG8_WAIT_V(n) asm volatile("s_waitcnt vmcnt(" #n ")" ::: "memory")
; #define PG8_WAIT_L(n) asm volatile("s_waitcnt lgkmcnt(" #n ")" ::: "memory")
; #define PG8_BAR __builtin_amdgcn_s_barrier()
; #define PG8_SCHED __builtin_amdgcn_sched_barrier(0)
; template <class Epi, class Sched, bool ALIGN_EPI = false, bool SP2 = false>
; __device__ __forceinline__ void gemm_phase(PG8_LAS unsigned char* lds, const Gemm g, const Sched& S, const Epi& E) {
;     ...
;             PG8_WAIT_V(8); PG8_WAIT_L(0); PG8_BAR; PG8_MMA(1, 0, At, B0); PG8_MMA(1, 1, At, B1); PG8_BAR; PG8_SCHED;
;             PG8_LDB(B0, 1, 0); PG8_LDB(B1, 1, 1); PG8_SCHED; PG8_LDA(At, 1, 0); PG8_STAGE(PG8_SA(0, 1), a2 + hstepA, voffA);
;             PG8_WAIT_V(8); PG8_WAIT_L(0); PG8_BAR; PG8_MMA(0, 0, At, B0); PG8_MMA(0, 1, At, B1); PG8_BAR; PG8_SCHED;
	s_setprio 1
	s_waitcnt lgkmcnt(0)
	v_mfma_i32_16x16x64_i8 v[62:65], v[118:121], v[194:197], v[62:65]
	v_mfma_i32_16x16x64_i8 v[62:65], v[126:129], v[198:201], v[62:65]
	v_mfma_i32_16x16x64_i8 v[46:49], v[126:129], v[206:209], v[46:49]
	v_mfma_i32_16x16x64_i8 v[46:49], v[118:121], v[202:205], v[46:49]
	v_mfma_i32_16x16x64_i8 v[30:33], v[118:121], v[212:215], v[30:33]
	v_mfma_i32_16x16x64_i8 v[30:33], v[126:129], v[216:219], v[30:33]
	v_mfma_i32_16x16x64_i8 v[14:17], v[126:129], v[224:227], v[14:17]
	v_mfma_i32_16x16x64_i8 v[14:17], v[118:121], v[220:223], v[14:17]
	v_mfma_i32_16x16x64_i8 v[10:13], v[130:133], v[220:223], v[10:13]
	v_mfma_i32_16x16x64_i8 v[10:13], v[134:137], v[224:227], v[10:13]
	v_mfma_i32_16x16x64_i8 v[26:29], v[134:137], v[216:219], v[26:29]
	v_mfma_i32_16x16x64_i8 v[26:29], v[130:133], v[212:215], v[26:29]
	v_mfma_i32_16x16x64_i8 v[42:45], v[130:133], v[202:205], v[42:45]
	v_mfma_i32_16x16x64_i8 v[42:45], v[134:137], v[206:209], v[42:45]
	v_mfma_i32_16x16x64_i8 v[58:61], v[134:137], v[198:201], v[58:61]
	v_mfma_i32_16x16x64_i8 v[58:61], v[130:133], v[194:197], v[58:61]
	s_setprio 0
	s_setprio 1
	v_mfma_i32_16x16x64_i8 v[50:53], v[186:189], v[194:197], v[50:53]
	v_mfma_i32_16x16x64_i8 v[50:53], v[190:193], v[198:201], v[50:53]
	v_mfma_i32_16x16x64_i8 v[34:37], v[190:193], v[206:209], v[34:37]
	v_mfma_i32_16x16x64_i8 v[34:37], v[186:189], v[202:205], v[34:37]
	v_mfma_i32_16x16x64_i8 v[18:21], v[186:189], v[212:215], v[18:21]
	v_mfma_i32_16x16x64_i8 v[18:21], v[190:193], v[216:219], v[18:21]
	v_mfma_i32_16x16x64_i8 v[2:5], v[190:193], v[224:227], v[2:5]
	v_mfma_i32_16x16x64_i8 v[2:5], v[186:189], v[220:223], v[2:5]
	v_mfma_i32_16x16x64_i8 v[6:9], v[172:175], v[220:223], v[6:9]
	v_mfma_i32_16x16x64_i8 v[6:9], v[182:185], v[224:227], v[6:9]
	v_mfma_i32_16x16x64_i8 v[22:25], v[182:185], v[216:219], v[22:25]
	v_mfma_i32_16x16x64_i8 v[22:25], v[172:175], v[212:215], v[22:25]
	v_mfma_i32_16x16x64_i8 v[38:41], v[172:175], v[202:205], v[38:41]
	v_mfma_i32_16x16x64_i8 v[38:41], v[182:185], v[206:209], v[38:41]
	v_mfma_i32_16x16x64_i8 v[54:57], v[182:185], v[198:201], v[54:57]
	v_mfma_i32_16x16x64_i8 v[54:57], v[172:175], v[194:197], v[54:57]
	s_setprio 0
	s_barrier
	ds_read_b128 v[118:121], v170
	ds_read_b128 v[126:129], v170 offset:1024
	ds_read_b128 v[130:133], v170 offset:2048
	ds_read_b128 v[134:137], v170 offset:3072
	ds_read_b128 v[172:175], v171
	ds_read_b128 v[182:185], v171 offset:1024
	ds_read_b128 v[186:189], v171 offset:2048
	ds_read_b128 v[190:193], v171 offset:3072
	s_add_u32 s54, s54, 0x158000
	s_addc_u32 s55, s55, 0
	s_mov_b32 m0, s7
	v_lshl_add_u64 v[232:233], s[54:55], 0, v[152:153]
	ds_read_b128 v[194:197], v169 offset:32768
	ds_read_b128 v[198:201], v169 offset:33792
	ds_read_b128 v[202:205], v169 offset:34816
	ds_read_b128 v[206:209], v169 offset:35840
	ds_read_b128 v[212:215], v169 offset:36864
	ds_read_b128 v[216:219], v169 offset:37888
	ds_read_b128 v[220:223], v169 offset:38912
	ds_read_b128 v[224:227], v169 offset:39936
	global_load_lds_dwordx4 v[232:233], off
	v_lshl_add_u64 v[232:233], s[54:55], 0, v[148:149]
	s_mov_b32 m0, s11
	s_nop 0
	global_load_lds_dwordx4 v[232:233], off
	s_waitcnt vmcnt(8)
	s_waitcnt lgkmcnt(0)
	s_barrier
	s_setprio 1
	s_waitcnt lgkmcnt(0)
	v_mfma_i32_16x16x64_i8 v[142:145], v[118:121], v[194:197], v[142:145]
	v_mfma_i32_16x16x64_i8 v[142:145], v[126:129], v[198:201], v[142:145]
	v_mfma_i32_16x16x64_i8 v[110:113], v[126:129], v[206:209], v[110:113]
	v_mfma_i32_16x16x64_i8 v[110:113], v[118:121], v[202:205], v[110:113]
	v_mfma_i32_16x16x64_i8 v[94:97], v[118:121], v[212:215], v[94:97]
	v_mfma_i32_16x16x64_i8 v[94:97], v[126:129], v[216:219], v[94:97]
	v_mfma_i32_16x16x64_i8 v[78:81], v[126:129], v[224:227], v[78:81]
	v_mfma_i32_16x16x64_i8 v[78:81], v[118:121], v[220:223], v[78:81]
	v_mfma_i32_16x16x64_i8 v[74:77], v[130:133], v[220:223], v[74:77]
	v_mfma_i32_16x16x64_i8 v[74:77], v[134:137], v[224:227], v[74:77]
	v_mfma_i32_16x16x64_i8 v[90:93], v[134:137], v[216:219], v[90:93]
	v_mfma_i32_16x16x64_i8 v[90:93], v[130:133], v[212:215], v[90:93]
	v_mfma_i32_16x16x64_i8 v[106:109], v[130:133], v[202:205], v[106:109]
	v_mfma_i32_16x16x64_i8 v[106:109], v[134:137], v[206:209], v[106:109]
	v_mfma_i32_16x16x64_i8 v[138:141], v[134:137], v[198:201], v[138:141]
	v_mfma_i32_16x16x64_i8 v[138:141], v[130:133], v[194:197], v[138:141]
	s_setprio 0
	s_setprio 1
	v_mfma_i32_16x16x64_i8 v[114:117], v[186:189], v[194:197], v[114:117]
	v_mfma_i32_16x16x64_i8 v[114:117], v[190:193], v[198:201], v[114:117]
	v_mfma_i32_16x16x64_i8 v[98:101], v[190:193], v[206:209], v[98:101]
	v_mfma_i32_16x16x64_i8 v[98:101], v[186:189], v[202:205], v[98:101]
	v_mfma_i32_16x16x64_i8 v[82:85], v[186:189], v[212:215], v[82:85]
	v_mfma_i32_16x16x64_i8 v[82:85], v[190:193], v[216:219], v[82:85]
	v_mfma_i32_16x16x64_i8 v[66:69], v[190:193], v[224:227], v[66:69]
	v_mfma_i32_16x16x64_i8 v[66:69], v[186:189], v[220:223], v[66:69]
	v_mfma_i32_16x16x64_i8 v[70:73], v[172:175], v[220:223], v[70:73]
	v_mfma_i32_16x16x64_i8 v[70:73], v[182:185], v[224:227], v[70:73]
	v_mfma_i32_16x16x64_i8 v[86:89], v[182:185], v[216:219], v[86:89]
	v_mfma_i32_16x16x64_i8 v[86:89], v[172:175], v[212:215], v[86:89]
	v_mfma_i32_16x16x64_i8 v[102:105], v[172:175], v[202:205], v[102:105]
	v_mfma_i32_16x16x64_i8 v[102:105], v[182:185], v[206:209], v[102:105]
	v_mfma_i32_16x16x64_i8 v[122:125], v[182:185], v[198:201], v[122:125]
	v_mfma_i32_16x16x64_i8 v[122:125], v[172:175], v[194:197], v[122:125]
	s_setprio 0
	s_barrier
; #define PG8_STAGE(bufoff, gbase, voff) do { _Pragma("unroll") for (int _i = 0; _i < 2; ++_i) \
;         __builtin_amdgcn_global_load_lds((const unsigned*)((const char*)(gbase) + (voff)[_i]), (PG8_LAS unsigned*)(lds + (bufoff) + ldsw + _i * 8192), 16, 0, 0); } while (0)
; #define PG8_LDA(dst, b, h) do { _Pragma("unroll") for (int m = 0; m < 4; ++m) _Pragma("unroll") for (int k = 0; k < 2; ++k) dst[m][k] = *(const PG8_LAS bf16x8*)(lds + PG8_SA(b, h) + aoff + m * 2048 + k * 1024); } while (0)
; #define PG8_MMA(ai, bj, At, Bt) do { __builtin_amdgcn_s_setprio(1); _Pragma("unroll") for (int m = 0; m < 4; ++m) _Pragma("unroll") for (int n = 0; n < 2; ++n) _Pragma("unroll") for (int k = 0; k < 2; ++k) \
;         acc[ai][bj][m][n] = mma16(Bt[n][k], At[m][k], acc[ai][bj][m][n]); __builtin_amdgcn_s_setprio(0); } while (0)
; #define PG8_WAIT_V(n) asm volatile("s_waitcnt vmcnt(" #n ")" ::: "memory")
; #define PG8_WAIT_L(n) asm volatile("s_waitcnt lgkmcnt(" #n ")" ::: "memory")
; #define PG8_BAR __builtin_amdgcn_s_barrier()
; #define PG8_SCHED __builtin_amdgcn_sched_barrier(0)
; template <class Epi, class Sched, bool ALIGN_EPI = false, bool SP2 = false>
; __device__ __forceinline__ void gemm_phase(PG8_LAS unsigned char* lds, const Gemm g, const Sched& S, const Epi& E) {
;     ...
;         for (int t = 0; t < nt; t += 2) {
;             const bool last = (t == nt - 2);
;             const char* a1 = cA + (size_t)(t + 1) * kstep;
;             const char* a2 = last ? nA : cA + (size_t)(t + 2) * kstep; const char* b2 = last ? nB : cB + (size_t)(t + 2) * kstep;
;             const char* a3 = a2 + kstep; const char* b3 = b2 + kstep;
;     ...
;             PG8_LDA(At, 1, 1); PG8_STAGE(PG8_SB(1, 0), b3, voffB); PG8_STAGE(PG8_SB(1, 1), b3 + hstepB, voffB); PG8_STAGE(PG8_SA(1, 0), a3, voffA);
;             PG8_WAIT_V(8); PG8_WAIT_L(0); PG8_BAR; PG8_MMA(1, 0, At, B0); PG8_MMA(1, 1, At, B1); PG8_BAR; PG8_SCHED;
	s_mov_b32 m0, s65
	v_lshl_add_u64 v[162:163], v[162:163], 0, s[22:23]
	s_add_u32 s52, s52, 0x158080
	ds_read_b128 v[194:197], v169 offset:49152
	ds_read_b128 v[198:201], v169 offset:50176
	ds_read_b128 v[202:205], v169 offset:51200
	ds_read_b128 v[206:209], v169 offset:52224
	ds_read_b128 v[212:215], v169 offset:53248
	ds_read_b128 v[216:219], v169 offset:54272
	ds_read_b128 v[220:223], v169 offset:55296
	ds_read_b128 v[224:227], v169 offset:56320
	global_load_lds_dwordx4 v[162:163], off
	v_lshl_add_u64 v[162:163], v[176:177], 0, s[22:23]
	s_mov_b32 m0, s66
	s_addc_u32 s53, s53, 0
	global_load_lds_dwordx4 v[162:163], off
	v_lshl_add_u64 v[162:163], s[52:53], 0, v[150:151]
	s_mov_b32 m0, s67
	s_nop 0
	global_load_lds_dwordx4 v[162:163], off
	v_lshl_add_u64 v[162:163], s[52:53], 0, v[146:147]
	s_mov_b32 m0, s68
	s_nop 0
	global_load_lds_dwordx4 v[162:163], off
	v_lshl_add_u64 v[162:163], v[228:229], 0, s[22:23]
	s_mov_b32 m0, s26
	s_nop 0
	global_load_lds_dwordx4 v[162:163], off
	v_lshl_add_u64 v[162:163], v[230:231], 0, s[22:23]
	s_mov_b32 m0, s27
	s_nop 0
	global_load_lds_dwordx4 v[162:163], off
	s_waitcnt vmcnt(8)
	s_waitcnt lgkmcnt(0)
	s_barrier
	s_setprio 1
	s_waitcnt lgkmcnt(0)
	v_mfma_i32_16x16x64_i8 v[62:65], v[118:121], v[194:197], v[62:65]
	v_mfma_i32_16x16x64_i8 v[62:65], v[126:129], v[198:201], v[62:65]
	v_mfma_i32_16x16x64_i8 v[46:49], v[126:129], v[206:209], v[46:49]
	v_mfma_i32_16x16x64_i8 v[46:49], v[118:121], v[202:205], v[46:49]
	v_mfma_i32_16x16x64_i8 v[30:33], v[118:121], v[212:215], v[30:33]
	v_mfma_i32_16x16x64_i8 v[30:33], v[126:129], v[216:219], v[30:33]
	v_mfma_i32_16x16x64_i8 v[14:17], v[126:129], v[224:227], v[14:17]
	v_mfma_i32_16x16x64_i8 v[14:17], v[118:121], v[220:223], v[14:17]
	v_mfma_i32_16x16x64_i8 v[10:13], v[130:133], v[220:223], v[10:13]
	v_mfma_i32_16x16x64_i8 v[10:13], v[134:137], v[224:227], v[10:13]
	v_mfma_i32_16x16x64_i8 v[26:29], v[134:137], v[216:219], v[26:29]
	v_mfma_i32_16x16x64_i8 v[26:29], v[130:133], v[212:215], v[26:29]
	v_mfma_i32_16x16x64_i8 v[42:45], v[130:133], v[202:205], v[42:45]
	v_mfma_i32_16x16x64_i8 v[42:45], v[134:137], v[206:209], v[42:45]
	v_mfma_i32_16x16x64_i8 v[58:61], v[134:137], v[198:201], v[58:61]
	v_mfma_i32_16x16x64_i8 v[58:61], v[130:133], v[194:197], v[58:61]
	s_setprio 0
	s_setprio 1
	v_mfma_i32_16x16x64_i8 v[50:53], v[186:189], v[194:197], v[50:53]
	v_mfma_i32_16x16x64_i8 v[50:53], v[190:193], v[198:201], v[50:53]
	v_mfma_i32_16x16x64_i8 v[34:37], v[190:193], v[206:209], v[34:37]
	v_mfma_i32_16x16x64_i8 v[34:37], v[186:189], v[202:205], v[34:37]
	v_mfma_i32_16x16x64_i8 v[18:21], v[186:189], v[212:215], v[18:21]
	v_mfma_i32_16x16x64_i8 v[18:21], v[190:193], v[216:219], v[18:21]
	v_mfma_i32_16x16x64_i8 v[2:5], v[190:193], v[224:227], v[2:5]
	v_mfma_i32_16x16x64_i8 v[2:5], v[186:189], v[220:223], v[2:5]
	v_mfma_i32_16x16x64_i8 v[6:9], v[172:175], v[220:223], v[6:9]
	v_mfma_i32_16x16x64_i8 v[6:9], v[182:185], v[224:227], v[6:9]
	v_mfma_i32_16x16x64_i8 v[22:25], v[182:185], v[216:219], v[22:25]
	v_mfma_i32_16x16x64_i8 v[22:25], v[172:175], v[212:215], v[22:25]
	v_mfma_i32_16x16x64_i8 v[38:41], v[172:175], v[202:205], v[38:41]
	v_mfma_i32_16x16x64_i8 v[38:41], v[182:185], v[206:209], v[38:41]
	v_mfma_i32_16x16x64_i8 v[54:57], v[182:185], v[198:201], v[54:57]
	v_mfma_i32_16x16x64_i8 v[54:57], v[172:175], v[194:197], v[54:57]
	s_setprio 0
	s_barrier
	s_add_i32 s71, s71, 2
	s_add_u32 s50, s50, 0x100
	s_addc_u32 s51, s51, 0
	s_add_u32 s45, s45, 0x100
	s_addc_u32 s70, s70, 0
	s_cmpk_gt_u32 s71, 0x53
	s_cbranch_scc0 .LBB0_1037
	s_and_b64 vcc, exec, s[24:25]
	s_cbranch_vccz .LBB0_1040
	s_barrier
